# speedup vs baseline: 1.1532x; 1.0234x over previous
.Lpv_loop:
	v_mad_u64_u32 v[248:249], vcc, v227, s0, v[86:87]
	global_load_dwordx4 v[10:13], v[248:249], off
	global_load_dwordx4 v[2:5], v[248:249], off offset:256
	ds_read_b32 v250, v131 offset:16
	ds_read_b32 v130, v132 offset:16
	s_waitcnt vmcnt(15)
	v_cvt_scalef32_pk_f32_fp4 v[134:135], v14, 1.0
	v_cvt_scalef32_pk_f32_fp4 v[136:137], v14, 1.0 op_sel:[1,0,0]
	v_cvt_scalef32_pk_f32_fp4 v[138:139], v14, 1.0 op_sel:[0,1,0]
	v_cvt_scalef32_pk_f32_fp4 v[140:141], v14, 1.0 op_sel:[1,1,0]
	s_waitcnt lgkmcnt(0)
	v_pk_fma_f32 v[128:129], v[130:131], v[134:135], v[128:129] op_sel_hi:[0,1,1]
	v_pk_fma_f32 v[126:127], v[130:131], v[136:137], v[126:127] op_sel_hi:[0,1,1]
	v_pk_fma_f32 v[122:123], v[130:131], v[138:139], v[122:123] op_sel_hi:[0,1,1]
	v_pk_fma_f32 v[120:121], v[130:131], v[140:141], v[120:121] op_sel_hi:[0,1,1]
	v_cvt_scalef32_pk_f32_fp4 v[134:135], v15, 1.0
	v_cvt_scalef32_pk_f32_fp4 v[136:137], v15, 1.0 op_sel:[1,0,0]
	v_cvt_scalef32_pk_f32_fp4 v[138:139], v15, 1.0 op_sel:[0,1,0]
	v_cvt_scalef32_pk_f32_fp4 v[140:141], v15, 1.0 op_sel:[1,1,0]
	v_pk_fma_f32 v[118:119], v[130:131], v[134:135], v[118:119] op_sel_hi:[0,1,1]
	v_pk_fma_f32 v[116:117], v[130:131], v[136:137], v[116:117] op_sel_hi:[0,1,1]
	v_pk_fma_f32 v[114:115], v[130:131], v[138:139], v[114:115] op_sel_hi:[0,1,1]
	v_pk_fma_f32 v[112:113], v[130:131], v[140:141], v[112:113] op_sel_hi:[0,1,1]
	v_cvt_scalef32_pk_f32_fp4 v[134:135], v16, 1.0
	v_cvt_scalef32_pk_f32_fp4 v[136:137], v16, 1.0 op_sel:[1,0,0]
	v_cvt_scalef32_pk_f32_fp4 v[138:139], v16, 1.0 op_sel:[0,1,0]
	v_cvt_scalef32_pk_f32_fp4 v[140:141], v16, 1.0 op_sel:[1,1,0]
	v_pk_fma_f32 v[80:81], v[130:131], v[134:135], v[80:81] op_sel_hi:[0,1,1]
	v_pk_fma_f32 v[78:79], v[130:131], v[136:137], v[78:79] op_sel_hi:[0,1,1]
	v_pk_fma_f32 v[76:77], v[130:131], v[138:139], v[76:77] op_sel_hi:[0,1,1]
	v_pk_fma_f32 v[74:75], v[130:131], v[140:141], v[74:75] op_sel_hi:[0,1,1]
	v_cvt_scalef32_pk_f32_fp4 v[134:135], v17, 1.0
	v_cvt_scalef32_pk_f32_fp4 v[136:137], v17, 1.0 op_sel:[1,0,0]
	v_cvt_scalef32_pk_f32_fp4 v[138:139], v17, 1.0 op_sel:[0,1,0]
	v_cvt_scalef32_pk_f32_fp4 v[140:141], v17, 1.0 op_sel:[1,1,0]
	v_pk_fma_f32 v[72:73], v[130:131], v[134:135], v[72:73] op_sel_hi:[0,1,1]
	v_pk_fma_f32 v[70:71], v[130:131], v[136:137], v[70:71] op_sel_hi:[0,1,1]
	v_pk_fma_f32 v[68:69], v[130:131], v[138:139], v[68:69] op_sel_hi:[0,1,1]
	v_pk_fma_f32 v[66:67], v[130:131], v[140:141], v[66:67] op_sel_hi:[0,1,1]
	s_waitcnt vmcnt(14)
	v_cvt_scalef32_pk_f32_fp4 v[134:135], v6, 1.0
	v_cvt_scalef32_pk_f32_fp4 v[136:137], v6, 1.0 op_sel:[1,0,0]
	v_cvt_scalef32_pk_f32_fp4 v[138:139], v6, 1.0 op_sel:[0,1,0]
	v_cvt_scalef32_pk_f32_fp4 v[140:141], v6, 1.0 op_sel:[1,1,0]
	v_pk_fma_f32 v[34:35], v[130:131], v[134:135], v[34:35] op_sel_hi:[0,1,1]
	v_pk_fma_f32 v[36:37], v[130:131], v[136:137], v[36:37] op_sel_hi:[0,1,1]
	v_pk_fma_f32 v[38:39], v[130:131], v[138:139], v[38:39] op_sel_hi:[0,1,1]
	v_pk_fma_f32 v[40:41], v[130:131], v[140:141], v[40:41] op_sel_hi:[0,1,1]
	v_cvt_scalef32_pk_f32_fp4 v[134:135], v7, 1.0
	v_cvt_scalef32_pk_f32_fp4 v[136:137], v7, 1.0 op_sel:[1,0,0]
	v_cvt_scalef32_pk_f32_fp4 v[138:139], v7, 1.0 op_sel:[0,1,0]
	v_cvt_scalef32_pk_f32_fp4 v[140:141], v7, 1.0 op_sel:[1,1,0]
	v_pk_fma_f32 v[42:43], v[130:131], v[134:135], v[42:43] op_sel_hi:[0,1,1]
	v_pk_fma_f32 v[44:45], v[130:131], v[136:137], v[44:45] op_sel_hi:[0,1,1]
	v_pk_fma_f32 v[46:47], v[130:131], v[138:139], v[46:47] op_sel_hi:[0,1,1]
	v_pk_fma_f32 v[48:49], v[130:131], v[140:141], v[48:49] op_sel_hi:[0,1,1]
	v_cvt_scalef32_pk_f32_fp4 v[134:135], v8, 1.0
	v_cvt_scalef32_pk_f32_fp4 v[136:137], v8, 1.0 op_sel:[1,0,0]
	v_cvt_scalef32_pk_f32_fp4 v[138:139], v8, 1.0 op_sel:[0,1,0]
	v_cvt_scalef32_pk_f32_fp4 v[140:141], v8, 1.0 op_sel:[1,1,0]
	v_pk_fma_f32 v[50:51], v[130:131], v[134:135], v[50:51] op_sel_hi:[0,1,1]
	v_pk_fma_f32 v[52:53], v[130:131], v[136:137], v[52:53] op_sel_hi:[0,1,1]
	v_pk_fma_f32 v[54:55], v[130:131], v[138:139], v[54:55] op_sel_hi:[0,1,1]
	v_pk_fma_f32 v[56:57], v[130:131], v[140:141], v[56:57] op_sel_hi:[0,1,1]
	v_cvt_scalef32_pk_f32_fp4 v[134:135], v9, 1.0
	v_cvt_scalef32_pk_f32_fp4 v[136:137], v9, 1.0 op_sel:[1,0,0]
	v_cvt_scalef32_pk_f32_fp4 v[138:139], v9, 1.0 op_sel:[0,1,0]
	v_cvt_scalef32_pk_f32_fp4 v[140:141], v9, 1.0 op_sel:[1,1,0]
	v_pk_fma_f32 v[58:59], v[130:131], v[134:135], v[58:59] op_sel_hi:[0,1,1]
	v_pk_fma_f32 v[60:61], v[130:131], v[136:137], v[60:61] op_sel_hi:[0,1,1]
	v_pk_fma_f32 v[62:63], v[130:131], v[138:139], v[62:63] op_sel_hi:[0,1,1]
	v_pk_fma_f32 v[64:65], v[130:131], v[140:141], v[64:65] op_sel_hi:[0,1,1]
	v_mad_u64_u32 v[248:249], vcc, v250, s0, v[86:87]
	global_load_dwordx4 v[14:17], v[248:249], off
	global_load_dwordx4 v[6:9], v[248:249], off offset:256
	ds_read_b32 v227, v131 offset:32
	ds_read_b32 v130, v132 offset:32
	s_waitcnt vmcnt(15)
	v_cvt_scalef32_pk_f32_fp4 v[134:135], v22, 1.0
	v_cvt_scalef32_pk_f32_fp4 v[136:137], v22, 1.0 op_sel:[1,0,0]
	v_cvt_scalef32_pk_f32_fp4 v[138:139], v22, 1.0 op_sel:[0,1,0]
	v_cvt_scalef32_pk_f32_fp4 v[140:141], v22, 1.0 op_sel:[1,1,0]
	s_waitcnt lgkmcnt(0)
	v_pk_fma_f32 v[128:129], v[130:131], v[134:135], v[128:129] op_sel_hi:[0,1,1]
	v_pk_fma_f32 v[126:127], v[130:131], v[136:137], v[126:127] op_sel_hi:[0,1,1]
	v_pk_fma_f32 v[122:123], v[130:131], v[138:139], v[122:123] op_sel_hi:[0,1,1]
	v_pk_fma_f32 v[120:121], v[130:131], v[140:141], v[120:121] op_sel_hi:[0,1,1]
	v_cvt_scalef32_pk_f32_fp4 v[134:135], v23, 1.0
	v_cvt_scalef32_pk_f32_fp4 v[136:137], v23, 1.0 op_sel:[1,0,0]
	v_cvt_scalef32_pk_f32_fp4 v[138:139], v23, 1.0 op_sel:[0,1,0]
	v_cvt_scalef32_pk_f32_fp4 v[140:141], v23, 1.0 op_sel:[1,1,0]
	v_pk_fma_f32 v[118:119], v[130:131], v[134:135], v[118:119] op_sel_hi:[0,1,1]
	v_pk_fma_f32 v[116:117], v[130:131], v[136:137], v[116:117] op_sel_hi:[0,1,1]
	v_pk_fma_f32 v[114:115], v[130:131], v[138:139], v[114:115] op_sel_hi:[0,1,1]
	v_pk_fma_f32 v[112:113], v[130:131], v[140:141], v[112:113] op_sel_hi:[0,1,1]
	v_cvt_scalef32_pk_f32_fp4 v[134:135], v24, 1.0
	v_cvt_scalef32_pk_f32_fp4 v[136:137], v24, 1.0 op_sel:[1,0,0]
	v_cvt_scalef32_pk_f32_fp4 v[138:139], v24, 1.0 op_sel:[0,1,0]
	v_cvt_scalef32_pk_f32_fp4 v[140:141], v24, 1.0 op_sel:[1,1,0]
	v_pk_fma_f32 v[80:81], v[130:131], v[134:135], v[80:81] op_sel_hi:[0,1,1]
	v_pk_fma_f32 v[78:79], v[130:131], v[136:137], v[78:79] op_sel_hi:[0,1,1]
	v_pk_fma_f32 v[76:77], v[130:131], v[138:139], v[76:77] op_sel_hi:[0,1,1]
	v_pk_fma_f32 v[74:75], v[130:131], v[140:141], v[74:75] op_sel_hi:[0,1,1]
	v_cvt_scalef32_pk_f32_fp4 v[134:135], v25, 1.0
	v_cvt_scalef32_pk_f32_fp4 v[136:137], v25, 1.0 op_sel:[1,0,0]
	v_cvt_scalef32_pk_f32_fp4 v[138:139], v25, 1.0 op_sel:[0,1,0]
	v_cvt_scalef32_pk_f32_fp4 v[140:141], v25, 1.0 op_sel:[1,1,0]
	v_pk_fma_f32 v[72:73], v[130:131], v[134:135], v[72:73] op_sel_hi:[0,1,1]
	v_pk_fma_f32 v[70:71], v[130:131], v[136:137], v[70:71] op_sel_hi:[0,1,1]
	v_pk_fma_f32 v[68:69], v[130:131], v[138:139], v[68:69] op_sel_hi:[0,1,1]
	v_pk_fma_f32 v[66:67], v[130:131], v[140:141], v[66:67] op_sel_hi:[0,1,1]
	s_waitcnt vmcnt(14)
	v_cvt_scalef32_pk_f32_fp4 v[134:135], v18, 1.0
	v_cvt_scalef32_pk_f32_fp4 v[136:137], v18, 1.0 op_sel:[1,0,0]
	v_cvt_scalef32_pk_f32_fp4 v[138:139], v18, 1.0 op_sel:[0,1,0]
	v_cvt_scalef32_pk_f32_fp4 v[140:141], v18, 1.0 op_sel:[1,1,0]
	v_pk_fma_f32 v[34:35], v[130:131], v[134:135], v[34:35] op_sel_hi:[0,1,1]
	v_pk_fma_f32 v[36:37], v[130:131], v[136:137], v[36:37] op_sel_hi:[0,1,1]
	v_pk_fma_f32 v[38:39], v[130:131], v[138:139], v[38:39] op_sel_hi:[0,1,1]
	v_pk_fma_f32 v[40:41], v[130:131], v[140:141], v[40:41] op_sel_hi:[0,1,1]
	v_cvt_scalef32_pk_f32_fp4 v[134:135], v19, 1.0
	v_cvt_scalef32_pk_f32_fp4 v[136:137], v19, 1.0 op_sel:[1,0,0]
	v_cvt_scalef32_pk_f32_fp4 v[138:139], v19, 1.0 op_sel:[0,1,0]
	v_cvt_scalef32_pk_f32_fp4 v[140:141], v19, 1.0 op_sel:[1,1,0]
	v_pk_fma_f32 v[42:43], v[130:131], v[134:135], v[42:43] op_sel_hi:[0,1,1]
	v_pk_fma_f32 v[44:45], v[130:131], v[136:137], v[44:45] op_sel_hi:[0,1,1]
	v_pk_fma_f32 v[46:47], v[130:131], v[138:139], v[46:47] op_sel_hi:[0,1,1]
	v_pk_fma_f32 v[48:49], v[130:131], v[140:141], v[48:49] op_sel_hi:[0,1,1]
	v_cvt_scalef32_pk_f32_fp4 v[134:135], v20, 1.0
	v_cvt_scalef32_pk_f32_fp4 v[136:137], v20, 1.0 op_sel:[1,0,0]
	v_cvt_scalef32_pk_f32_fp4 v[138:139], v20, 1.0 op_sel:[0,1,0]
	v_cvt_scalef32_pk_f32_fp4 v[140:141], v20, 1.0 op_sel:[1,1,0]
	v_pk_fma_f32 v[50:51], v[130:131], v[134:135], v[50:51] op_sel_hi:[0,1,1]
	v_pk_fma_f32 v[52:53], v[130:131], v[136:137], v[52:53] op_sel_hi:[0,1,1]
	v_pk_fma_f32 v[54:55], v[130:131], v[138:139], v[54:55] op_sel_hi:[0,1,1]
	v_pk_fma_f32 v[56:57], v[130:131], v[140:141], v[56:57] op_sel_hi:[0,1,1]
	v_cvt_scalef32_pk_f32_fp4 v[134:135], v21, 1.0
	v_cvt_scalef32_pk_f32_fp4 v[136:137], v21, 1.0 op_sel:[1,0,0]
	v_cvt_scalef32_pk_f32_fp4 v[138:139], v21, 1.0 op_sel:[0,1,0]
	v_cvt_scalef32_pk_f32_fp4 v[140:141], v21, 1.0 op_sel:[1,1,0]
	v_pk_fma_f32 v[58:59], v[130:131], v[134:135], v[58:59] op_sel_hi:[0,1,1]
	v_pk_fma_f32 v[60:61], v[130:131], v[136:137], v[60:61] op_sel_hi:[0,1,1]
	v_pk_fma_f32 v[62:63], v[130:131], v[138:139], v[62:63] op_sel_hi:[0,1,1]
	v_pk_fma_f32 v[64:65], v[130:131], v[140:141], v[64:65] op_sel_hi:[0,1,1]
	v_mad_u64_u32 v[248:249], vcc, v227, s0, v[86:87]
	global_load_dwordx4 v[22:25], v[248:249], off
	global_load_dwordx4 v[18:21], v[248:249], off offset:256
	ds_read_b32 v250, v131 offset:48
	ds_read_b32 v130, v132 offset:48
	s_waitcnt vmcnt(15)
	v_cvt_scalef32_pk_f32_fp4 v[134:135], v30, 1.0
	v_cvt_scalef32_pk_f32_fp4 v[136:137], v30, 1.0 op_sel:[1,0,0]
	v_cvt_scalef32_pk_f32_fp4 v[138:139], v30, 1.0 op_sel:[0,1,0]
	v_cvt_scalef32_pk_f32_fp4 v[140:141], v30, 1.0 op_sel:[1,1,0]
	s_waitcnt lgkmcnt(0)
	v_pk_fma_f32 v[128:129], v[130:131], v[134:135], v[128:129] op_sel_hi:[0,1,1]
	v_pk_fma_f32 v[126:127], v[130:131], v[136:137], v[126:127] op_sel_hi:[0,1,1]
	v_pk_fma_f32 v[122:123], v[130:131], v[138:139], v[122:123] op_sel_hi:[0,1,1]
	v_pk_fma_f32 v[120:121], v[130:131], v[140:141], v[120:121] op_sel_hi:[0,1,1]
	v_cvt_scalef32_pk_f32_fp4 v[134:135], v31, 1.0
	v_cvt_scalef32_pk_f32_fp4 v[136:137], v31, 1.0 op_sel:[1,0,0]
	v_cvt_scalef32_pk_f32_fp4 v[138:139], v31, 1.0 op_sel:[0,1,0]
	v_cvt_scalef32_pk_f32_fp4 v[140:141], v31, 1.0 op_sel:[1,1,0]
	v_pk_fma_f32 v[118:119], v[130:131], v[134:135], v[118:119] op_sel_hi:[0,1,1]
	v_pk_fma_f32 v[116:117], v[130:131], v[136:137], v[116:117] op_sel_hi:[0,1,1]
	v_pk_fma_f32 v[114:115], v[130:131], v[138:139], v[114:115] op_sel_hi:[0,1,1]
	v_pk_fma_f32 v[112:113], v[130:131], v[140:141], v[112:113] op_sel_hi:[0,1,1]
	v_cvt_scalef32_pk_f32_fp4 v[134:135], v32, 1.0
	v_cvt_scalef32_pk_f32_fp4 v[136:137], v32, 1.0 op_sel:[1,0,0]
	v_cvt_scalef32_pk_f32_fp4 v[138:139], v32, 1.0 op_sel:[0,1,0]
	v_cvt_scalef32_pk_f32_fp4 v[140:141], v32, 1.0 op_sel:[1,1,0]
	v_pk_fma_f32 v[80:81], v[130:131], v[134:135], v[80:81] op_sel_hi:[0,1,1]
	v_pk_fma_f32 v[78:79], v[130:131], v[136:137], v[78:79] op_sel_hi:[0,1,1]
	v_pk_fma_f32 v[76:77], v[130:131], v[138:139], v[76:77] op_sel_hi:[0,1,1]
	v_pk_fma_f32 v[74:75], v[130:131], v[140:141], v[74:75] op_sel_hi:[0,1,1]
	v_cvt_scalef32_pk_f32_fp4 v[134:135], v33, 1.0
	v_cvt_scalef32_pk_f32_fp4 v[136:137], v33, 1.0 op_sel:[1,0,0]
	v_cvt_scalef32_pk_f32_fp4 v[138:139], v33, 1.0 op_sel:[0,1,0]
	v_cvt_scalef32_pk_f32_fp4 v[140:141], v33, 1.0 op_sel:[1,1,0]
	v_pk_fma_f32 v[72:73], v[130:131], v[134:135], v[72:73] op_sel_hi:[0,1,1]
	v_pk_fma_f32 v[70:71], v[130:131], v[136:137], v[70:71] op_sel_hi:[0,1,1]
	v_pk_fma_f32 v[68:69], v[130:131], v[138:139], v[68:69] op_sel_hi:[0,1,1]
	v_pk_fma_f32 v[66:67], v[130:131], v[140:141], v[66:67] op_sel_hi:[0,1,1]
	s_waitcnt vmcnt(14)
	v_cvt_scalef32_pk_f32_fp4 v[134:135], v26, 1.0
	v_cvt_scalef32_pk_f32_fp4 v[136:137], v26, 1.0 op_sel:[1,0,0]
	v_cvt_scalef32_pk_f32_fp4 v[138:139], v26, 1.0 op_sel:[0,1,0]
	v_cvt_scalef32_pk_f32_fp4 v[140:141], v26, 1.0 op_sel:[1,1,0]
	v_pk_fma_f32 v[34:35], v[130:131], v[134:135], v[34:35] op_sel_hi:[0,1,1]
	v_pk_fma_f32 v[36:37], v[130:131], v[136:137], v[36:37] op_sel_hi:[0,1,1]
	v_pk_fma_f32 v[38:39], v[130:131], v[138:139], v[38:39] op_sel_hi:[0,1,1]
	v_pk_fma_f32 v[40:41], v[130:131], v[140:141], v[40:41] op_sel_hi:[0,1,1]
	v_cvt_scalef32_pk_f32_fp4 v[134:135], v27, 1.0
	v_cvt_scalef32_pk_f32_fp4 v[136:137], v27, 1.0 op_sel:[1,0,0]
	v_cvt_scalef32_pk_f32_fp4 v[138:139], v27, 1.0 op_sel:[0,1,0]
	v_cvt_scalef32_pk_f32_fp4 v[140:141], v27, 1.0 op_sel:[1,1,0]
	v_pk_fma_f32 v[42:43], v[130:131], v[134:135], v[42:43] op_sel_hi:[0,1,1]
	v_pk_fma_f32 v[44:45], v[130:131], v[136:137], v[44:45] op_sel_hi:[0,1,1]
	v_pk_fma_f32 v[46:47], v[130:131], v[138:139], v[46:47] op_sel_hi:[0,1,1]
	v_pk_fma_f32 v[48:49], v[130:131], v[140:141], v[48:49] op_sel_hi:[0,1,1]
	v_cvt_scalef32_pk_f32_fp4 v[134:135], v28, 1.0
	v_cvt_scalef32_pk_f32_fp4 v[136:137], v28, 1.0 op_sel:[1,0,0]
	v_cvt_scalef32_pk_f32_fp4 v[138:139], v28, 1.0 op_sel:[0,1,0]
	v_cvt_scalef32_pk_f32_fp4 v[140:141], v28, 1.0 op_sel:[1,1,0]
	v_pk_fma_f32 v[50:51], v[130:131], v[134:135], v[50:51] op_sel_hi:[0,1,1]
	v_pk_fma_f32 v[52:53], v[130:131], v[136:137], v[52:53] op_sel_hi:[0,1,1]
	v_pk_fma_f32 v[54:55], v[130:131], v[138:139], v[54:55] op_sel_hi:[0,1,1]
	v_pk_fma_f32 v[56:57], v[130:131], v[140:141], v[56:57] op_sel_hi:[0,1,1]
	v_cvt_scalef32_pk_f32_fp4 v[134:135], v29, 1.0
	v_cvt_scalef32_pk_f32_fp4 v[136:137], v29, 1.0 op_sel:[1,0,0]
	v_cvt_scalef32_pk_f32_fp4 v[138:139], v29, 1.0 op_sel:[0,1,0]
	v_cvt_scalef32_pk_f32_fp4 v[140:141], v29, 1.0 op_sel:[1,1,0]
	v_pk_fma_f32 v[58:59], v[130:131], v[134:135], v[58:59] op_sel_hi:[0,1,1]
	v_pk_fma_f32 v[60:61], v[130:131], v[136:137], v[60:61] op_sel_hi:[0,1,1]
	v_pk_fma_f32 v[62:63], v[130:131], v[138:139], v[62:63] op_sel_hi:[0,1,1]
	v_pk_fma_f32 v[64:65], v[130:131], v[140:141], v[64:65] op_sel_hi:[0,1,1]
	v_mad_u64_u32 v[248:249], vcc, v250, s0, v[86:87]
	global_load_dwordx4 v[30:33], v[248:249], off
	global_load_dwordx4 v[26:29], v[248:249], off offset:256
	ds_read_b32 v227, v131 offset:64
	ds_read_b32 v130, v132 offset:64
	s_waitcnt vmcnt(15)
	v_cvt_scalef32_pk_f32_fp4 v[134:135], v142, 1.0
	v_cvt_scalef32_pk_f32_fp4 v[136:137], v142, 1.0 op_sel:[1,0,0]
	v_cvt_scalef32_pk_f32_fp4 v[138:139], v142, 1.0 op_sel:[0,1,0]
	v_cvt_scalef32_pk_f32_fp4 v[140:141], v142, 1.0 op_sel:[1,1,0]
	s_waitcnt lgkmcnt(0)
	v_pk_fma_f32 v[128:129], v[130:131], v[134:135], v[128:129] op_sel_hi:[0,1,1]
	v_pk_fma_f32 v[126:127], v[130:131], v[136:137], v[126:127] op_sel_hi:[0,1,1]
	v_pk_fma_f32 v[122:123], v[130:131], v[138:139], v[122:123] op_sel_hi:[0,1,1]
	v_pk_fma_f32 v[120:121], v[130:131], v[140:141], v[120:121] op_sel_hi:[0,1,1]
	v_cvt_scalef32_pk_f32_fp4 v[134:135], v143, 1.0
	v_cvt_scalef32_pk_f32_fp4 v[136:137], v143, 1.0 op_sel:[1,0,0]
	v_cvt_scalef32_pk_f32_fp4 v[138:139], v143, 1.0 op_sel:[0,1,0]
	v_cvt_scalef32_pk_f32_fp4 v[140:141], v143, 1.0 op_sel:[1,1,0]
	v_pk_fma_f32 v[118:119], v[130:131], v[134:135], v[118:119] op_sel_hi:[0,1,1]
	v_pk_fma_f32 v[116:117], v[130:131], v[136:137], v[116:117] op_sel_hi:[0,1,1]
	v_pk_fma_f32 v[114:115], v[130:131], v[138:139], v[114:115] op_sel_hi:[0,1,1]
	v_pk_fma_f32 v[112:113], v[130:131], v[140:141], v[112:113] op_sel_hi:[0,1,1]
	v_cvt_scalef32_pk_f32_fp4 v[134:135], v144, 1.0
	v_cvt_scalef32_pk_f32_fp4 v[136:137], v144, 1.0 op_sel:[1,0,0]
	v_cvt_scalef32_pk_f32_fp4 v[138:139], v144, 1.0 op_sel:[0,1,0]
	v_cvt_scalef32_pk_f32_fp4 v[140:141], v144, 1.0 op_sel:[1,1,0]
	v_pk_fma_f32 v[80:81], v[130:131], v[134:135], v[80:81] op_sel_hi:[0,1,1]
	v_pk_fma_f32 v[78:79], v[130:131], v[136:137], v[78:79] op_sel_hi:[0,1,1]
	v_pk_fma_f32 v[76:77], v[130:131], v[138:139], v[76:77] op_sel_hi:[0,1,1]
	v_pk_fma_f32 v[74:75], v[130:131], v[140:141], v[74:75] op_sel_hi:[0,1,1]
	v_cvt_scalef32_pk_f32_fp4 v[134:135], v145, 1.0
	v_cvt_scalef32_pk_f32_fp4 v[136:137], v145, 1.0 op_sel:[1,0,0]
	v_cvt_scalef32_pk_f32_fp4 v[138:139], v145, 1.0 op_sel:[0,1,0]
	v_cvt_scalef32_pk_f32_fp4 v[140:141], v145, 1.0 op_sel:[1,1,0]
	v_pk_fma_f32 v[72:73], v[130:131], v[134:135], v[72:73] op_sel_hi:[0,1,1]
	v_pk_fma_f32 v[70:71], v[130:131], v[136:137], v[70:71] op_sel_hi:[0,1,1]
	v_pk_fma_f32 v[68:69], v[130:131], v[138:139], v[68:69] op_sel_hi:[0,1,1]
	v_pk_fma_f32 v[66:67], v[130:131], v[140:141], v[66:67] op_sel_hi:[0,1,1]
	s_waitcnt vmcnt(14)
	v_cvt_scalef32_pk_f32_fp4 v[134:135], v146, 1.0
	v_cvt_scalef32_pk_f32_fp4 v[136:137], v146, 1.0 op_sel:[1,0,0]
	v_cvt_scalef32_pk_f32_fp4 v[138:139], v146, 1.0 op_sel:[0,1,0]
	v_cvt_scalef32_pk_f32_fp4 v[140:141], v146, 1.0 op_sel:[1,1,0]
	v_pk_fma_f32 v[34:35], v[130:131], v[134:135], v[34:35] op_sel_hi:[0,1,1]
	v_pk_fma_f32 v[36:37], v[130:131], v[136:137], v[36:37] op_sel_hi:[0,1,1]
	v_pk_fma_f32 v[38:39], v[130:131], v[138:139], v[38:39] op_sel_hi:[0,1,1]
	v_pk_fma_f32 v[40:41], v[130:131], v[140:141], v[40:41] op_sel_hi:[0,1,1]
	v_cvt_scalef32_pk_f32_fp4 v[134:135], v147, 1.0
	v_cvt_scalef32_pk_f32_fp4 v[136:137], v147, 1.0 op_sel:[1,0,0]
	v_cvt_scalef32_pk_f32_fp4 v[138:139], v147, 1.0 op_sel:[0,1,0]
	v_cvt_scalef32_pk_f32_fp4 v[140:141], v147, 1.0 op_sel:[1,1,0]
	v_pk_fma_f32 v[42:43], v[130:131], v[134:135], v[42:43] op_sel_hi:[0,1,1]
	v_pk_fma_f32 v[44:45], v[130:131], v[136:137], v[44:45] op_sel_hi:[0,1,1]
	v_pk_fma_f32 v[46:47], v[130:131], v[138:139], v[46:47] op_sel_hi:[0,1,1]
	v_pk_fma_f32 v[48:49], v[130:131], v[140:141], v[48:49] op_sel_hi:[0,1,1]
	v_cvt_scalef32_pk_f32_fp4 v[134:135], v148, 1.0
	v_cvt_scalef32_pk_f32_fp4 v[136:137], v148, 1.0 op_sel:[1,0,0]
	v_cvt_scalef32_pk_f32_fp4 v[138:139], v148, 1.0 op_sel:[0,1,0]
	v_cvt_scalef32_pk_f32_fp4 v[140:141], v148, 1.0 op_sel:[1,1,0]
	v_pk_fma_f32 v[50:51], v[130:131], v[134:135], v[50:51] op_sel_hi:[0,1,1]
	v_pk_fma_f32 v[52:53], v[130:131], v[136:137], v[52:53] op_sel_hi:[0,1,1]
	v_pk_fma_f32 v[54:55], v[130:131], v[138:139], v[54:55] op_sel_hi:[0,1,1]
	v_pk_fma_f32 v[56:57], v[130:131], v[140:141], v[56:57] op_sel_hi:[0,1,1]
	v_cvt_scalef32_pk_f32_fp4 v[134:135], v149, 1.0
	v_cvt_scalef32_pk_f32_fp4 v[136:137], v149, 1.0 op_sel:[1,0,0]
	v_cvt_scalef32_pk_f32_fp4 v[138:139], v149, 1.0 op_sel:[0,1,0]
	v_cvt_scalef32_pk_f32_fp4 v[140:141], v149, 1.0 op_sel:[1,1,0]
	v_pk_fma_f32 v[58:59], v[130:131], v[134:135], v[58:59] op_sel_hi:[0,1,1]
	v_pk_fma_f32 v[60:61], v[130:131], v[136:137], v[60:61] op_sel_hi:[0,1,1]
	v_pk_fma_f32 v[62:63], v[130:131], v[138:139], v[62:63] op_sel_hi:[0,1,1]
	v_pk_fma_f32 v[64:65], v[130:131], v[140:141], v[64:65] op_sel_hi:[0,1,1]
	v_mad_u64_u32 v[248:249], vcc, v227, s0, v[86:87]
	global_load_dwordx4 v[142:145], v[248:249], off
	global_load_dwordx4 v[146:149], v[248:249], off offset:256
	ds_read_b32 v250, v131 offset:80
	ds_read_b32 v130, v132 offset:80
	s_waitcnt vmcnt(15)
	v_cvt_scalef32_pk_f32_fp4 v[134:135], v150, 1.0
	v_cvt_scalef32_pk_f32_fp4 v[136:137], v150, 1.0 op_sel:[1,0,0]
	v_cvt_scalef32_pk_f32_fp4 v[138:139], v150, 1.0 op_sel:[0,1,0]
	v_cvt_scalef32_pk_f32_fp4 v[140:141], v150, 1.0 op_sel:[1,1,0]
	s_waitcnt lgkmcnt(0)
	v_pk_fma_f32 v[128:129], v[130:131], v[134:135], v[128:129] op_sel_hi:[0,1,1]
	v_pk_fma_f32 v[126:127], v[130:131], v[136:137], v[126:127] op_sel_hi:[0,1,1]
	v_pk_fma_f32 v[122:123], v[130:131], v[138:139], v[122:123] op_sel_hi:[0,1,1]
	v_pk_fma_f32 v[120:121], v[130:131], v[140:141], v[120:121] op_sel_hi:[0,1,1]
	v_cvt_scalef32_pk_f32_fp4 v[134:135], v151, 1.0
	v_cvt_scalef32_pk_f32_fp4 v[136:137], v151, 1.0 op_sel:[1,0,0]
	v_cvt_scalef32_pk_f32_fp4 v[138:139], v151, 1.0 op_sel:[0,1,0]
	v_cvt_scalef32_pk_f32_fp4 v[140:141], v151, 1.0 op_sel:[1,1,0]
	v_pk_fma_f32 v[118:119], v[130:131], v[134:135], v[118:119] op_sel_hi:[0,1,1]
	v_pk_fma_f32 v[116:117], v[130:131], v[136:137], v[116:117] op_sel_hi:[0,1,1]
	v_pk_fma_f32 v[114:115], v[130:131], v[138:139], v[114:115] op_sel_hi:[0,1,1]
	v_pk_fma_f32 v[112:113], v[130:131], v[140:141], v[112:113] op_sel_hi:[0,1,1]
	v_cvt_scalef32_pk_f32_fp4 v[134:135], v152, 1.0
	v_cvt_scalef32_pk_f32_fp4 v[136:137], v152, 1.0 op_sel:[1,0,0]
	v_cvt_scalef32_pk_f32_fp4 v[138:139], v152, 1.0 op_sel:[0,1,0]
	v_cvt_scalef32_pk_f32_fp4 v[140:141], v152, 1.0 op_sel:[1,1,0]
	v_pk_fma_f32 v[80:81], v[130:131], v[134:135], v[80:81] op_sel_hi:[0,1,1]
	v_pk_fma_f32 v[78:79], v[130:131], v[136:137], v[78:79] op_sel_hi:[0,1,1]
	v_pk_fma_f32 v[76:77], v[130:131], v[138:139], v[76:77] op_sel_hi:[0,1,1]
	v_pk_fma_f32 v[74:75], v[130:131], v[140:141], v[74:75] op_sel_hi:[0,1,1]
	v_cvt_scalef32_pk_f32_fp4 v[134:135], v153, 1.0
	v_cvt_scalef32_pk_f32_fp4 v[136:137], v153, 1.0 op_sel:[1,0,0]
	v_cvt_scalef32_pk_f32_fp4 v[138:139], v153, 1.0 op_sel:[0,1,0]
	v_cvt_scalef32_pk_f32_fp4 v[140:141], v153, 1.0 op_sel:[1,1,0]
	v_pk_fma_f32 v[72:73], v[130:131], v[134:135], v[72:73] op_sel_hi:[0,1,1]
	v_pk_fma_f32 v[70:71], v[130:131], v[136:137], v[70:71] op_sel_hi:[0,1,1]
	v_pk_fma_f32 v[68:69], v[130:131], v[138:139], v[68:69] op_sel_hi:[0,1,1]
	v_pk_fma_f32 v[66:67], v[130:131], v[140:141], v[66:67] op_sel_hi:[0,1,1]
	s_waitcnt vmcnt(14)
	v_cvt_scalef32_pk_f32_fp4 v[134:135], v232, 1.0
	v_cvt_scalef32_pk_f32_fp4 v[136:137], v232, 1.0 op_sel:[1,0,0]
	v_cvt_scalef32_pk_f32_fp4 v[138:139], v232, 1.0 op_sel:[0,1,0]
	v_cvt_scalef32_pk_f32_fp4 v[140:141], v232, 1.0 op_sel:[1,1,0]
	v_pk_fma_f32 v[34:35], v[130:131], v[134:135], v[34:35] op_sel_hi:[0,1,1]
	v_pk_fma_f32 v[36:37], v[130:131], v[136:137], v[36:37] op_sel_hi:[0,1,1]
	v_pk_fma_f32 v[38:39], v[130:131], v[138:139], v[38:39] op_sel_hi:[0,1,1]
	v_pk_fma_f32 v[40:41], v[130:131], v[140:141], v[40:41] op_sel_hi:[0,1,1]
	v_cvt_scalef32_pk_f32_fp4 v[134:135], v233, 1.0
	v_cvt_scalef32_pk_f32_fp4 v[136:137], v233, 1.0 op_sel:[1,0,0]
	v_cvt_scalef32_pk_f32_fp4 v[138:139], v233, 1.0 op_sel:[0,1,0]
	v_cvt_scalef32_pk_f32_fp4 v[140:141], v233, 1.0 op_sel:[1,1,0]
	v_pk_fma_f32 v[42:43], v[130:131], v[134:135], v[42:43] op_sel_hi:[0,1,1]
	v_pk_fma_f32 v[44:45], v[130:131], v[136:137], v[44:45] op_sel_hi:[0,1,1]
	v_pk_fma_f32 v[46:47], v[130:131], v[138:139], v[46:47] op_sel_hi:[0,1,1]
	v_pk_fma_f32 v[48:49], v[130:131], v[140:141], v[48:49] op_sel_hi:[0,1,1]
	v_cvt_scalef32_pk_f32_fp4 v[134:135], v234, 1.0
	v_cvt_scalef32_pk_f32_fp4 v[136:137], v234, 1.0 op_sel:[1,0,0]
	v_cvt_scalef32_pk_f32_fp4 v[138:139], v234, 1.0 op_sel:[0,1,0]
	v_cvt_scalef32_pk_f32_fp4 v[140:141], v234, 1.0 op_sel:[1,1,0]
	v_pk_fma_f32 v[50:51], v[130:131], v[134:135], v[50:51] op_sel_hi:[0,1,1]
	v_pk_fma_f32 v[52:53], v[130:131], v[136:137], v[52:53] op_sel_hi:[0,1,1]
	v_pk_fma_f32 v[54:55], v[130:131], v[138:139], v[54:55] op_sel_hi:[0,1,1]
	v_pk_fma_f32 v[56:57], v[130:131], v[140:141], v[56:57] op_sel_hi:[0,1,1]
	v_cvt_scalef32_pk_f32_fp4 v[134:135], v235, 1.0
	v_cvt_scalef32_pk_f32_fp4 v[136:137], v235, 1.0 op_sel:[1,0,0]
	v_cvt_scalef32_pk_f32_fp4 v[138:139], v235, 1.0 op_sel:[0,1,0]
	v_cvt_scalef32_pk_f32_fp4 v[140:141], v235, 1.0 op_sel:[1,1,0]
	v_pk_fma_f32 v[58:59], v[130:131], v[134:135], v[58:59] op_sel_hi:[0,1,1]
	v_pk_fma_f32 v[60:61], v[130:131], v[136:137], v[60:61] op_sel_hi:[0,1,1]
	v_pk_fma_f32 v[62:63], v[130:131], v[138:139], v[62:63] op_sel_hi:[0,1,1]
	v_pk_fma_f32 v[64:65], v[130:131], v[140:141], v[64:65] op_sel_hi:[0,1,1]
	v_mad_u64_u32 v[248:249], vcc, v250, s0, v[86:87]
	global_load_dwordx4 v[150:153], v[248:249], off
	global_load_dwordx4 v[232:235], v[248:249], off offset:256
	ds_read_b32 v227, v131 offset:96
	ds_read_b32 v130, v132 offset:96
	s_waitcnt vmcnt(15)
	v_cvt_scalef32_pk_f32_fp4 v[134:135], v236, 1.0
	v_cvt_scalef32_pk_f32_fp4 v[136:137], v236, 1.0 op_sel:[1,0,0]
	v_cvt_scalef32_pk_f32_fp4 v[138:139], v236, 1.0 op_sel:[0,1,0]
	v_cvt_scalef32_pk_f32_fp4 v[140:141], v236, 1.0 op_sel:[1,1,0]
	s_waitcnt lgkmcnt(0)
	v_pk_fma_f32 v[128:129], v[130:131], v[134:135], v[128:129] op_sel_hi:[0,1,1]
	v_pk_fma_f32 v[126:127], v[130:131], v[136:137], v[126:127] op_sel_hi:[0,1,1]
	v_pk_fma_f32 v[122:123], v[130:131], v[138:139], v[122:123] op_sel_hi:[0,1,1]
	v_pk_fma_f32 v[120:121], v[130:131], v[140:141], v[120:121] op_sel_hi:[0,1,1]
	v_cvt_scalef32_pk_f32_fp4 v[134:135], v237, 1.0
	v_cvt_scalef32_pk_f32_fp4 v[136:137], v237, 1.0 op_sel:[1,0,0]
	v_cvt_scalef32_pk_f32_fp4 v[138:139], v237, 1.0 op_sel:[0,1,0]
	v_cvt_scalef32_pk_f32_fp4 v[140:141], v237, 1.0 op_sel:[1,1,0]
	v_pk_fma_f32 v[118:119], v[130:131], v[134:135], v[118:119] op_sel_hi:[0,1,1]
	v_pk_fma_f32 v[116:117], v[130:131], v[136:137], v[116:117] op_sel_hi:[0,1,1]
	v_pk_fma_f32 v[114:115], v[130:131], v[138:139], v[114:115] op_sel_hi:[0,1,1]
	v_pk_fma_f32 v[112:113], v[130:131], v[140:141], v[112:113] op_sel_hi:[0,1,1]
	v_cvt_scalef32_pk_f32_fp4 v[134:135], v238, 1.0
	v_cvt_scalef32_pk_f32_fp4 v[136:137], v238, 1.0 op_sel:[1,0,0]
	v_cvt_scalef32_pk_f32_fp4 v[138:139], v238, 1.0 op_sel:[0,1,0]
	v_cvt_scalef32_pk_f32_fp4 v[140:141], v238, 1.0 op_sel:[1,1,0]
	v_pk_fma_f32 v[80:81], v[130:131], v[134:135], v[80:81] op_sel_hi:[0,1,1]
	v_pk_fma_f32 v[78:79], v[130:131], v[136:137], v[78:79] op_sel_hi:[0,1,1]
	v_pk_fma_f32 v[76:77], v[130:131], v[138:139], v[76:77] op_sel_hi:[0,1,1]
	v_pk_fma_f32 v[74:75], v[130:131], v[140:141], v[74:75] op_sel_hi:[0,1,1]
	v_cvt_scalef32_pk_f32_fp4 v[134:135], v239, 1.0
	v_cvt_scalef32_pk_f32_fp4 v[136:137], v239, 1.0 op_sel:[1,0,0]
	v_cvt_scalef32_pk_f32_fp4 v[138:139], v239, 1.0 op_sel:[0,1,0]
	v_cvt_scalef32_pk_f32_fp4 v[140:141], v239, 1.0 op_sel:[1,1,0]
	v_pk_fma_f32 v[72:73], v[130:131], v[134:135], v[72:73] op_sel_hi:[0,1,1]
	v_pk_fma_f32 v[70:71], v[130:131], v[136:137], v[70:71] op_sel_hi:[0,1,1]
	v_pk_fma_f32 v[68:69], v[130:131], v[138:139], v[68:69] op_sel_hi:[0,1,1]
	v_pk_fma_f32 v[66:67], v[130:131], v[140:141], v[66:67] op_sel_hi:[0,1,1]
	s_waitcnt vmcnt(14)
	v_cvt_scalef32_pk_f32_fp4 v[134:135], v240, 1.0
	v_cvt_scalef32_pk_f32_fp4 v[136:137], v240, 1.0 op_sel:[1,0,0]
	v_cvt_scalef32_pk_f32_fp4 v[138:139], v240, 1.0 op_sel:[0,1,0]
	v_cvt_scalef32_pk_f32_fp4 v[140:141], v240, 1.0 op_sel:[1,1,0]
	v_pk_fma_f32 v[34:35], v[130:131], v[134:135], v[34:35] op_sel_hi:[0,1,1]
	v_pk_fma_f32 v[36:37], v[130:131], v[136:137], v[36:37] op_sel_hi:[0,1,1]
	v_pk_fma_f32 v[38:39], v[130:131], v[138:139], v[38:39] op_sel_hi:[0,1,1]
	v_pk_fma_f32 v[40:41], v[130:131], v[140:141], v[40:41] op_sel_hi:[0,1,1]
	v_cvt_scalef32_pk_f32_fp4 v[134:135], v241, 1.0
	v_cvt_scalef32_pk_f32_fp4 v[136:137], v241, 1.0 op_sel:[1,0,0]
	v_cvt_scalef32_pk_f32_fp4 v[138:139], v241, 1.0 op_sel:[0,1,0]
	v_cvt_scalef32_pk_f32_fp4 v[140:141], v241, 1.0 op_sel:[1,1,0]
	v_pk_fma_f32 v[42:43], v[130:131], v[134:135], v[42:43] op_sel_hi:[0,1,1]
	v_pk_fma_f32 v[44:45], v[130:131], v[136:137], v[44:45] op_sel_hi:[0,1,1]
	v_pk_fma_f32 v[46:47], v[130:131], v[138:139], v[46:47] op_sel_hi:[0,1,1]
	v_pk_fma_f32 v[48:49], v[130:131], v[140:141], v[48:49] op_sel_hi:[0,1,1]
	v_cvt_scalef32_pk_f32_fp4 v[134:135], v242, 1.0
	v_cvt_scalef32_pk_f32_fp4 v[136:137], v242, 1.0 op_sel:[1,0,0]
	v_cvt_scalef32_pk_f32_fp4 v[138:139], v242, 1.0 op_sel:[0,1,0]
	v_cvt_scalef32_pk_f32_fp4 v[140:141], v242, 1.0 op_sel:[1,1,0]
	v_pk_fma_f32 v[50:51], v[130:131], v[134:135], v[50:51] op_sel_hi:[0,1,1]
	v_pk_fma_f32 v[52:53], v[130:131], v[136:137], v[52:53] op_sel_hi:[0,1,1]
	v_pk_fma_f32 v[54:55], v[130:131], v[138:139], v[54:55] op_sel_hi:[0,1,1]
	v_pk_fma_f32 v[56:57], v[130:131], v[140:141], v[56:57] op_sel_hi:[0,1,1]
	v_cvt_scalef32_pk_f32_fp4 v[134:135], v243, 1.0
	v_cvt_scalef32_pk_f32_fp4 v[136:137], v243, 1.0 op_sel:[1,0,0]
	v_cvt_scalef32_pk_f32_fp4 v[138:139], v243, 1.0 op_sel:[0,1,0]
	v_cvt_scalef32_pk_f32_fp4 v[140:141], v243, 1.0 op_sel:[1,1,0]
	v_pk_fma_f32 v[58:59], v[130:131], v[134:135], v[58:59] op_sel_hi:[0,1,1]
	v_pk_fma_f32 v[60:61], v[130:131], v[136:137], v[60:61] op_sel_hi:[0,1,1]
	v_pk_fma_f32 v[62:63], v[130:131], v[138:139], v[62:63] op_sel_hi:[0,1,1]
	v_pk_fma_f32 v[64:65], v[130:131], v[140:141], v[64:65] op_sel_hi:[0,1,1]
	v_mad_u64_u32 v[248:249], vcc, v227, s0, v[86:87]
	global_load_dwordx4 v[236:239], v[248:249], off
	global_load_dwordx4 v[240:243], v[248:249], off offset:256
	ds_read_b32 v250, v131 offset:112
	ds_read_b32 v130, v132 offset:112
	s_waitcnt vmcnt(15)
	v_cvt_scalef32_pk_f32_fp4 v[134:135], v244, 1.0
	v_cvt_scalef32_pk_f32_fp4 v[136:137], v244, 1.0 op_sel:[1,0,0]
	v_cvt_scalef32_pk_f32_fp4 v[138:139], v244, 1.0 op_sel:[0,1,0]
	v_cvt_scalef32_pk_f32_fp4 v[140:141], v244, 1.0 op_sel:[1,1,0]
	s_waitcnt lgkmcnt(0)
	v_pk_fma_f32 v[128:129], v[130:131], v[134:135], v[128:129] op_sel_hi:[0,1,1]
	v_pk_fma_f32 v[126:127], v[130:131], v[136:137], v[126:127] op_sel_hi:[0,1,1]
	v_pk_fma_f32 v[122:123], v[130:131], v[138:139], v[122:123] op_sel_hi:[0,1,1]
	v_pk_fma_f32 v[120:121], v[130:131], v[140:141], v[120:121] op_sel_hi:[0,1,1]
	v_cvt_scalef32_pk_f32_fp4 v[134:135], v245, 1.0
	v_cvt_scalef32_pk_f32_fp4 v[136:137], v245, 1.0 op_sel:[1,0,0]
	v_cvt_scalef32_pk_f32_fp4 v[138:139], v245, 1.0 op_sel:[0,1,0]
	v_cvt_scalef32_pk_f32_fp4 v[140:141], v245, 1.0 op_sel:[1,1,0]
	v_pk_fma_f32 v[118:119], v[130:131], v[134:135], v[118:119] op_sel_hi:[0,1,1]
	v_pk_fma_f32 v[116:117], v[130:131], v[136:137], v[116:117] op_sel_hi:[0,1,1]
	v_pk_fma_f32 v[114:115], v[130:131], v[138:139], v[114:115] op_sel_hi:[0,1,1]
	v_pk_fma_f32 v[112:113], v[130:131], v[140:141], v[112:113] op_sel_hi:[0,1,1]
	v_cvt_scalef32_pk_f32_fp4 v[134:135], v246, 1.0
	v_cvt_scalef32_pk_f32_fp4 v[136:137], v246, 1.0 op_sel:[1,0,0]
	v_cvt_scalef32_pk_f32_fp4 v[138:139], v246, 1.0 op_sel:[0,1,0]
	v_cvt_scalef32_pk_f32_fp4 v[140:141], v246, 1.0 op_sel:[1,1,0]
	v_pk_fma_f32 v[80:81], v[130:131], v[134:135], v[80:81] op_sel_hi:[0,1,1]
	v_pk_fma_f32 v[78:79], v[130:131], v[136:137], v[78:79] op_sel_hi:[0,1,1]
	v_pk_fma_f32 v[76:77], v[130:131], v[138:139], v[76:77] op_sel_hi:[0,1,1]
	v_pk_fma_f32 v[74:75], v[130:131], v[140:141], v[74:75] op_sel_hi:[0,1,1]
	v_cvt_scalef32_pk_f32_fp4 v[134:135], v247, 1.0
	v_cvt_scalef32_pk_f32_fp4 v[136:137], v247, 1.0 op_sel:[1,0,0]
	v_cvt_scalef32_pk_f32_fp4 v[138:139], v247, 1.0 op_sel:[0,1,0]
	v_cvt_scalef32_pk_f32_fp4 v[140:141], v247, 1.0 op_sel:[1,1,0]
	v_pk_fma_f32 v[72:73], v[130:131], v[134:135], v[72:73] op_sel_hi:[0,1,1]
	v_pk_fma_f32 v[70:71], v[130:131], v[136:137], v[70:71] op_sel_hi:[0,1,1]
	v_pk_fma_f32 v[68:69], v[130:131], v[138:139], v[68:69] op_sel_hi:[0,1,1]
	v_pk_fma_f32 v[66:67], v[130:131], v[140:141], v[66:67] op_sel_hi:[0,1,1]
	s_waitcnt vmcnt(14)
	v_cvt_scalef32_pk_f32_fp4 v[134:135], v228, 1.0
	v_cvt_scalef32_pk_f32_fp4 v[136:137], v228, 1.0 op_sel:[1,0,0]
	v_cvt_scalef32_pk_f32_fp4 v[138:139], v228, 1.0 op_sel:[0,1,0]
	v_cvt_scalef32_pk_f32_fp4 v[140:141], v228, 1.0 op_sel:[1,1,0]
	v_pk_fma_f32 v[34:35], v[130:131], v[134:135], v[34:35] op_sel_hi:[0,1,1]
	v_pk_fma_f32 v[36:37], v[130:131], v[136:137], v[36:37] op_sel_hi:[0,1,1]
	v_pk_fma_f32 v[38:39], v[130:131], v[138:139], v[38:39] op_sel_hi:[0,1,1]
	v_pk_fma_f32 v[40:41], v[130:131], v[140:141], v[40:41] op_sel_hi:[0,1,1]
	v_cvt_scalef32_pk_f32_fp4 v[134:135], v229, 1.0
	v_cvt_scalef32_pk_f32_fp4 v[136:137], v229, 1.0 op_sel:[1,0,0]
	v_cvt_scalef32_pk_f32_fp4 v[138:139], v229, 1.0 op_sel:[0,1,0]
	v_cvt_scalef32_pk_f32_fp4 v[140:141], v229, 1.0 op_sel:[1,1,0]
	v_pk_fma_f32 v[42:43], v[130:131], v[134:135], v[42:43] op_sel_hi:[0,1,1]
	v_pk_fma_f32 v[44:45], v[130:131], v[136:137], v[44:45] op_sel_hi:[0,1,1]
	v_pk_fma_f32 v[46:47], v[130:131], v[138:139], v[46:47] op_sel_hi:[0,1,1]
	v_pk_fma_f32 v[48:49], v[130:131], v[140:141], v[48:49] op_sel_hi:[0,1,1]
	v_cvt_scalef32_pk_f32_fp4 v[134:135], v230, 1.0
	v_cvt_scalef32_pk_f32_fp4 v[136:137], v230, 1.0 op_sel:[1,0,0]
	v_cvt_scalef32_pk_f32_fp4 v[138:139], v230, 1.0 op_sel:[0,1,0]
	v_cvt_scalef32_pk_f32_fp4 v[140:141], v230, 1.0 op_sel:[1,1,0]
	v_pk_fma_f32 v[50:51], v[130:131], v[134:135], v[50:51] op_sel_hi:[0,1,1]
	v_pk_fma_f32 v[52:53], v[130:131], v[136:137], v[52:53] op_sel_hi:[0,1,1]
	v_pk_fma_f32 v[54:55], v[130:131], v[138:139], v[54:55] op_sel_hi:[0,1,1]
	v_pk_fma_f32 v[56:57], v[130:131], v[140:141], v[56:57] op_sel_hi:[0,1,1]
	v_cvt_scalef32_pk_f32_fp4 v[134:135], v231, 1.0
	v_cvt_scalef32_pk_f32_fp4 v[136:137], v231, 1.0 op_sel:[1,0,0]
	v_cvt_scalef32_pk_f32_fp4 v[138:139], v231, 1.0 op_sel:[0,1,0]
	v_cvt_scalef32_pk_f32_fp4 v[140:141], v231, 1.0 op_sel:[1,1,0]
	v_pk_fma_f32 v[58:59], v[130:131], v[134:135], v[58:59] op_sel_hi:[0,1,1]
	v_pk_fma_f32 v[60:61], v[130:131], v[136:137], v[60:61] op_sel_hi:[0,1,1]
	v_pk_fma_f32 v[62:63], v[130:131], v[138:139], v[62:63] op_sel_hi:[0,1,1]
	v_pk_fma_f32 v[64:65], v[130:131], v[140:141], v[64:65] op_sel_hi:[0,1,1]
	v_mad_u64_u32 v[248:249], vcc, v250, s0, v[86:87]
	global_load_dwordx4 v[244:247], v[248:249], off
	global_load_dwordx4 v[228:231], v[248:249], off offset:256
	ds_read_b32 v227, v131 offset:128
	ds_read_b32 v130, v132 offset:128
	s_waitcnt vmcnt(15)
	v_cvt_scalef32_pk_f32_fp4 v[134:135], v10, 1.0
	v_cvt_scalef32_pk_f32_fp4 v[136:137], v10, 1.0 op_sel:[1,0,0]
	v_cvt_scalef32_pk_f32_fp4 v[138:139], v10, 1.0 op_sel:[0,1,0]
	v_cvt_scalef32_pk_f32_fp4 v[140:141], v10, 1.0 op_sel:[1,1,0]
	s_waitcnt lgkmcnt(0)
	v_pk_fma_f32 v[128:129], v[130:131], v[134:135], v[128:129] op_sel_hi:[0,1,1]
	v_pk_fma_f32 v[126:127], v[130:131], v[136:137], v[126:127] op_sel_hi:[0,1,1]
	v_pk_fma_f32 v[122:123], v[130:131], v[138:139], v[122:123] op_sel_hi:[0,1,1]
	v_pk_fma_f32 v[120:121], v[130:131], v[140:141], v[120:121] op_sel_hi:[0,1,1]
	v_cvt_scalef32_pk_f32_fp4 v[134:135], v11, 1.0
	v_cvt_scalef32_pk_f32_fp4 v[136:137], v11, 1.0 op_sel:[1,0,0]
	v_cvt_scalef32_pk_f32_fp4 v[138:139], v11, 1.0 op_sel:[0,1,0]
	v_cvt_scalef32_pk_f32_fp4 v[140:141], v11, 1.0 op_sel:[1,1,0]
	v_pk_fma_f32 v[118:119], v[130:131], v[134:135], v[118:119] op_sel_hi:[0,1,1]
	v_pk_fma_f32 v[116:117], v[130:131], v[136:137], v[116:117] op_sel_hi:[0,1,1]
	v_pk_fma_f32 v[114:115], v[130:131], v[138:139], v[114:115] op_sel_hi:[0,1,1]
	v_pk_fma_f32 v[112:113], v[130:131], v[140:141], v[112:113] op_sel_hi:[0,1,1]
	v_cvt_scalef32_pk_f32_fp4 v[134:135], v12, 1.0
	v_cvt_scalef32_pk_f32_fp4 v[136:137], v12, 1.0 op_sel:[1,0,0]
	v_cvt_scalef32_pk_f32_fp4 v[138:139], v12, 1.0 op_sel:[0,1,0]
	v_cvt_scalef32_pk_f32_fp4 v[140:141], v12, 1.0 op_sel:[1,1,0]
	v_pk_fma_f32 v[80:81], v[130:131], v[134:135], v[80:81] op_sel_hi:[0,1,1]
	v_pk_fma_f32 v[78:79], v[130:131], v[136:137], v[78:79] op_sel_hi:[0,1,1]
	v_pk_fma_f32 v[76:77], v[130:131], v[138:139], v[76:77] op_sel_hi:[0,1,1]
	v_pk_fma_f32 v[74:75], v[130:131], v[140:141], v[74:75] op_sel_hi:[0,1,1]
	v_cvt_scalef32_pk_f32_fp4 v[134:135], v13, 1.0
	v_cvt_scalef32_pk_f32_fp4 v[136:137], v13, 1.0 op_sel:[1,0,0]
	v_cvt_scalef32_pk_f32_fp4 v[138:139], v13, 1.0 op_sel:[0,1,0]
	v_cvt_scalef32_pk_f32_fp4 v[140:141], v13, 1.0 op_sel:[1,1,0]
	v_pk_fma_f32 v[72:73], v[130:131], v[134:135], v[72:73] op_sel_hi:[0,1,1]
	v_pk_fma_f32 v[70:71], v[130:131], v[136:137], v[70:71] op_sel_hi:[0,1,1]
	v_pk_fma_f32 v[68:69], v[130:131], v[138:139], v[68:69] op_sel_hi:[0,1,1]
	v_pk_fma_f32 v[66:67], v[130:131], v[140:141], v[66:67] op_sel_hi:[0,1,1]
	s_waitcnt vmcnt(14)
	v_cvt_scalef32_pk_f32_fp4 v[134:135], v2, 1.0
	v_cvt_scalef32_pk_f32_fp4 v[136:137], v2, 1.0 op_sel:[1,0,0]
	v_cvt_scalef32_pk_f32_fp4 v[138:139], v2, 1.0 op_sel:[0,1,0]
	v_cvt_scalef32_pk_f32_fp4 v[140:141], v2, 1.0 op_sel:[1,1,0]
	v_pk_fma_f32 v[34:35], v[130:131], v[134:135], v[34:35] op_sel_hi:[0,1,1]
	v_pk_fma_f32 v[36:37], v[130:131], v[136:137], v[36:37] op_sel_hi:[0,1,1]
	v_pk_fma_f32 v[38:39], v[130:131], v[138:139], v[38:39] op_sel_hi:[0,1,1]
	v_pk_fma_f32 v[40:41], v[130:131], v[140:141], v[40:41] op_sel_hi:[0,1,1]
	v_cvt_scalef32_pk_f32_fp4 v[134:135], v3, 1.0
	v_cvt_scalef32_pk_f32_fp4 v[136:137], v3, 1.0 op_sel:[1,0,0]
	v_cvt_scalef32_pk_f32_fp4 v[138:139], v3, 1.0 op_sel:[0,1,0]
	v_cvt_scalef32_pk_f32_fp4 v[140:141], v3, 1.0 op_sel:[1,1,0]
	v_pk_fma_f32 v[42:43], v[130:131], v[134:135], v[42:43] op_sel_hi:[0,1,1]
	v_pk_fma_f32 v[44:45], v[130:131], v[136:137], v[44:45] op_sel_hi:[0,1,1]
	v_pk_fma_f32 v[46:47], v[130:131], v[138:139], v[46:47] op_sel_hi:[0,1,1]
	v_pk_fma_f32 v[48:49], v[130:131], v[140:141], v[48:49] op_sel_hi:[0,1,1]
	v_cvt_scalef32_pk_f32_fp4 v[134:135], v4, 1.0
	v_cvt_scalef32_pk_f32_fp4 v[136:137], v4, 1.0 op_sel:[1,0,0]
	v_cvt_scalef32_pk_f32_fp4 v[138:139], v4, 1.0 op_sel:[0,1,0]
	v_cvt_scalef32_pk_f32_fp4 v[140:141], v4, 1.0 op_sel:[1,1,0]
	v_pk_fma_f32 v[50:51], v[130:131], v[134:135], v[50:51] op_sel_hi:[0,1,1]
	v_pk_fma_f32 v[52:53], v[130:131], v[136:137], v[52:53] op_sel_hi:[0,1,1]
	v_pk_fma_f32 v[54:55], v[130:131], v[138:139], v[54:55] op_sel_hi:[0,1,1]
	v_pk_fma_f32 v[56:57], v[130:131], v[140:141], v[56:57] op_sel_hi:[0,1,1]
	v_cvt_scalef32_pk_f32_fp4 v[134:135], v5, 1.0
	v_cvt_scalef32_pk_f32_fp4 v[136:137], v5, 1.0 op_sel:[1,0,0]
	v_cvt_scalef32_pk_f32_fp4 v[138:139], v5, 1.0 op_sel:[0,1,0]
	v_cvt_scalef32_pk_f32_fp4 v[140:141], v5, 1.0 op_sel:[1,1,0]
	v_pk_fma_f32 v[58:59], v[130:131], v[134:135], v[58:59] op_sel_hi:[0,1,1]
	v_pk_fma_f32 v[60:61], v[130:131], v[136:137], v[60:61] op_sel_hi:[0,1,1]
	v_pk_fma_f32 v[62:63], v[130:131], v[138:139], v[62:63] op_sel_hi:[0,1,1]
	v_pk_fma_f32 v[64:65], v[130:131], v[140:141], v[64:65] op_sel_hi:[0,1,1]
	s_add_i32 s2, s2, 8
	v_add_u32_e32 v131, 0x80, v131
	v_add_u32_e32 v132, 0x80, v132
	s_cmp_lt_u32 s2, 24
	s_cbranch_scc1 .Lpv_loop
	ds_read_b32 v130, v132 offset:16
	s_waitcnt vmcnt(13)
	v_cvt_scalef32_pk_f32_fp4 v[134:135], v14, 1.0
	v_cvt_scalef32_pk_f32_fp4 v[136:137], v14, 1.0 op_sel:[1,0,0]
	v_cvt_scalef32_pk_f32_fp4 v[138:139], v14, 1.0 op_sel:[0,1,0]
	v_cvt_scalef32_pk_f32_fp4 v[140:141], v14, 1.0 op_sel:[1,1,0]
	s_waitcnt lgkmcnt(0)
	v_pk_fma_f32 v[128:129], v[130:131], v[134:135], v[128:129] op_sel_hi:[0,1,1]
	v_pk_fma_f32 v[126:127], v[130:131], v[136:137], v[126:127] op_sel_hi:[0,1,1]
	v_pk_fma_f32 v[122:123], v[130:131], v[138:139], v[122:123] op_sel_hi:[0,1,1]
	v_pk_fma_f32 v[120:121], v[130:131], v[140:141], v[120:121] op_sel_hi:[0,1,1]
	v_cvt_scalef32_pk_f32_fp4 v[134:135], v15, 1.0
	v_cvt_scalef32_pk_f32_fp4 v[136:137], v15, 1.0 op_sel:[1,0,0]
	v_cvt_scalef32_pk_f32_fp4 v[138:139], v15, 1.0 op_sel:[0,1,0]
	v_cvt_scalef32_pk_f32_fp4 v[140:141], v15, 1.0 op_sel:[1,1,0]
	v_pk_fma_f32 v[118:119], v[130:131], v[134:135], v[118:119] op_sel_hi:[0,1,1]
	v_pk_fma_f32 v[116:117], v[130:131], v[136:137], v[116:117] op_sel_hi:[0,1,1]
	v_pk_fma_f32 v[114:115], v[130:131], v[138:139], v[114:115] op_sel_hi:[0,1,1]
	v_pk_fma_f32 v[112:113], v[130:131], v[140:141], v[112:113] op_sel_hi:[0,1,1]
	v_cvt_scalef32_pk_f32_fp4 v[134:135], v16, 1.0
	v_cvt_scalef32_pk_f32_fp4 v[136:137], v16, 1.0 op_sel:[1,0,0]
	v_cvt_scalef32_pk_f32_fp4 v[138:139], v16, 1.0 op_sel:[0,1,0]
	v_cvt_scalef32_pk_f32_fp4 v[140:141], v16, 1.0 op_sel:[1,1,0]
	v_pk_fma_f32 v[80:81], v[130:131], v[134:135], v[80:81] op_sel_hi:[0,1,1]
	v_pk_fma_f32 v[78:79], v[130:131], v[136:137], v[78:79] op_sel_hi:[0,1,1]
	v_pk_fma_f32 v[76:77], v[130:131], v[138:139], v[76:77] op_sel_hi:[0,1,1]
	v_pk_fma_f32 v[74:75], v[130:131], v[140:141], v[74:75] op_sel_hi:[0,1,1]
	v_cvt_scalef32_pk_f32_fp4 v[134:135], v17, 1.0
	v_cvt_scalef32_pk_f32_fp4 v[136:137], v17, 1.0 op_sel:[1,0,0]
	v_cvt_scalef32_pk_f32_fp4 v[138:139], v17, 1.0 op_sel:[0,1,0]
	v_cvt_scalef32_pk_f32_fp4 v[140:141], v17, 1.0 op_sel:[1,1,0]
	v_pk_fma_f32 v[72:73], v[130:131], v[134:135], v[72:73] op_sel_hi:[0,1,1]
	v_pk_fma_f32 v[70:71], v[130:131], v[136:137], v[70:71] op_sel_hi:[0,1,1]
	v_pk_fma_f32 v[68:69], v[130:131], v[138:139], v[68:69] op_sel_hi:[0,1,1]
	v_pk_fma_f32 v[66:67], v[130:131], v[140:141], v[66:67] op_sel_hi:[0,1,1]
	s_waitcnt vmcnt(12)
	v_cvt_scalef32_pk_f32_fp4 v[134:135], v6, 1.0
	v_cvt_scalef32_pk_f32_fp4 v[136:137], v6, 1.0 op_sel:[1,0,0]
	v_cvt_scalef32_pk_f32_fp4 v[138:139], v6, 1.0 op_sel:[0,1,0]
	v_cvt_scalef32_pk_f32_fp4 v[140:141], v6, 1.0 op_sel:[1,1,0]
	v_pk_fma_f32 v[34:35], v[130:131], v[134:135], v[34:35] op_sel_hi:[0,1,1]
	v_pk_fma_f32 v[36:37], v[130:131], v[136:137], v[36:37] op_sel_hi:[0,1,1]
	v_pk_fma_f32 v[38:39], v[130:131], v[138:139], v[38:39] op_sel_hi:[0,1,1]
	v_pk_fma_f32 v[40:41], v[130:131], v[140:141], v[40:41] op_sel_hi:[0,1,1]
	v_cvt_scalef32_pk_f32_fp4 v[134:135], v7, 1.0
	v_cvt_scalef32_pk_f32_fp4 v[136:137], v7, 1.0 op_sel:[1,0,0]
	v_cvt_scalef32_pk_f32_fp4 v[138:139], v7, 1.0 op_sel:[0,1,0]
	v_cvt_scalef32_pk_f32_fp4 v[140:141], v7, 1.0 op_sel:[1,1,0]
	v_pk_fma_f32 v[42:43], v[130:131], v[134:135], v[42:43] op_sel_hi:[0,1,1]
	v_pk_fma_f32 v[44:45], v[130:131], v[136:137], v[44:45] op_sel_hi:[0,1,1]
	v_pk_fma_f32 v[46:47], v[130:131], v[138:139], v[46:47] op_sel_hi:[0,1,1]
	v_pk_fma_f32 v[48:49], v[130:131], v[140:141], v[48:49] op_sel_hi:[0,1,1]
	v_cvt_scalef32_pk_f32_fp4 v[134:135], v8, 1.0
	v_cvt_scalef32_pk_f32_fp4 v[136:137], v8, 1.0 op_sel:[1,0,0]
	v_cvt_scalef32_pk_f32_fp4 v[138:139], v8, 1.0 op_sel:[0,1,0]
	v_cvt_scalef32_pk_f32_fp4 v[140:141], v8, 1.0 op_sel:[1,1,0]
	v_pk_fma_f32 v[50:51], v[130:131], v[134:135], v[50:51] op_sel_hi:[0,1,1]
	v_pk_fma_f32 v[52:53], v[130:131], v[136:137], v[52:53] op_sel_hi:[0,1,1]
	v_pk_fma_f32 v[54:55], v[130:131], v[138:139], v[54:55] op_sel_hi:[0,1,1]
	v_pk_fma_f32 v[56:57], v[130:131], v[140:141], v[56:57] op_sel_hi:[0,1,1]
	v_cvt_scalef32_pk_f32_fp4 v[134:135], v9, 1.0
	v_cvt_scalef32_pk_f32_fp4 v[136:137], v9, 1.0 op_sel:[1,0,0]
	v_cvt_scalef32_pk_f32_fp4 v[138:139], v9, 1.0 op_sel:[0,1,0]
	v_cvt_scalef32_pk_f32_fp4 v[140:141], v9, 1.0 op_sel:[1,1,0]
	v_pk_fma_f32 v[58:59], v[130:131], v[134:135], v[58:59] op_sel_hi:[0,1,1]
	v_pk_fma_f32 v[60:61], v[130:131], v[136:137], v[60:61] op_sel_hi:[0,1,1]
	v_pk_fma_f32 v[62:63], v[130:131], v[138:139], v[62:63] op_sel_hi:[0,1,1]
	v_pk_fma_f32 v[64:65], v[130:131], v[140:141], v[64:65] op_sel_hi:[0,1,1]
	ds_read_b32 v130, v132 offset:32
	s_waitcnt vmcnt(11)
	v_cvt_scalef32_pk_f32_fp4 v[134:135], v22, 1.0
	v_cvt_scalef32_pk_f32_fp4 v[136:137], v22, 1.0 op_sel:[1,0,0]
	v_cvt_scalef32_pk_f32_fp4 v[138:139], v22, 1.0 op_sel:[0,1,0]
	v_cvt_scalef32_pk_f32_fp4 v[140:141], v22, 1.0 op_sel:[1,1,0]
	s_waitcnt lgkmcnt(0)
	v_pk_fma_f32 v[128:129], v[130:131], v[134:135], v[128:129] op_sel_hi:[0,1,1]
	v_pk_fma_f32 v[126:127], v[130:131], v[136:137], v[126:127] op_sel_hi:[0,1,1]
	v_pk_fma_f32 v[122:123], v[130:131], v[138:139], v[122:123] op_sel_hi:[0,1,1]
	v_pk_fma_f32 v[120:121], v[130:131], v[140:141], v[120:121] op_sel_hi:[0,1,1]
	v_cvt_scalef32_pk_f32_fp4 v[134:135], v23, 1.0
	v_cvt_scalef32_pk_f32_fp4 v[136:137], v23, 1.0 op_sel:[1,0,0]
	v_cvt_scalef32_pk_f32_fp4 v[138:139], v23, 1.0 op_sel:[0,1,0]
	v_cvt_scalef32_pk_f32_fp4 v[140:141], v23, 1.0 op_sel:[1,1,0]
	v_pk_fma_f32 v[118:119], v[130:131], v[134:135], v[118:119] op_sel_hi:[0,1,1]
	v_pk_fma_f32 v[116:117], v[130:131], v[136:137], v[116:117] op_sel_hi:[0,1,1]
	v_pk_fma_f32 v[114:115], v[130:131], v[138:139], v[114:115] op_sel_hi:[0,1,1]
	v_pk_fma_f32 v[112:113], v[130:131], v[140:141], v[112:113] op_sel_hi:[0,1,1]
	v_cvt_scalef32_pk_f32_fp4 v[134:135], v24, 1.0
	v_cvt_scalef32_pk_f32_fp4 v[136:137], v24, 1.0 op_sel:[1,0,0]
	v_cvt_scalef32_pk_f32_fp4 v[138:139], v24, 1.0 op_sel:[0,1,0]
	v_cvt_scalef32_pk_f32_fp4 v[140:141], v24, 1.0 op_sel:[1,1,0]
	v_pk_fma_f32 v[80:81], v[130:131], v[134:135], v[80:81] op_sel_hi:[0,1,1]
	v_pk_fma_f32 v[78:79], v[130:131], v[136:137], v[78:79] op_sel_hi:[0,1,1]
	v_pk_fma_f32 v[76:77], v[130:131], v[138:139], v[76:77] op_sel_hi:[0,1,1]
	v_pk_fma_f32 v[74:75], v[130:131], v[140:141], v[74:75] op_sel_hi:[0,1,1]
	v_cvt_scalef32_pk_f32_fp4 v[134:135], v25, 1.0
	v_cvt_scalef32_pk_f32_fp4 v[136:137], v25, 1.0 op_sel:[1,0,0]
	v_cvt_scalef32_pk_f32_fp4 v[138:139], v25, 1.0 op_sel:[0,1,0]
	v_cvt_scalef32_pk_f32_fp4 v[140:141], v25, 1.0 op_sel:[1,1,0]
	v_pk_fma_f32 v[72:73], v[130:131], v[134:135], v[72:73] op_sel_hi:[0,1,1]
	v_pk_fma_f32 v[70:71], v[130:131], v[136:137], v[70:71] op_sel_hi:[0,1,1]
	v_pk_fma_f32 v[68:69], v[130:131], v[138:139], v[68:69] op_sel_hi:[0,1,1]
	v_pk_fma_f32 v[66:67], v[130:131], v[140:141], v[66:67] op_sel_hi:[0,1,1]
	s_waitcnt vmcnt(10)
	v_cvt_scalef32_pk_f32_fp4 v[134:135], v18, 1.0
	v_cvt_scalef32_pk_f32_fp4 v[136:137], v18, 1.0 op_sel:[1,0,0]
	v_cvt_scalef32_pk_f32_fp4 v[138:139], v18, 1.0 op_sel:[0,1,0]
	v_cvt_scalef32_pk_f32_fp4 v[140:141], v18, 1.0 op_sel:[1,1,0]
	v_pk_fma_f32 v[34:35], v[130:131], v[134:135], v[34:35] op_sel_hi:[0,1,1]
	v_pk_fma_f32 v[36:37], v[130:131], v[136:137], v[36:37] op_sel_hi:[0,1,1]
	v_pk_fma_f32 v[38:39], v[130:131], v[138:139], v[38:39] op_sel_hi:[0,1,1]
	v_pk_fma_f32 v[40:41], v[130:131], v[140:141], v[40:41] op_sel_hi:[0,1,1]
	v_cvt_scalef32_pk_f32_fp4 v[134:135], v19, 1.0
	v_cvt_scalef32_pk_f32_fp4 v[136:137], v19, 1.0 op_sel:[1,0,0]
	v_cvt_scalef32_pk_f32_fp4 v[138:139], v19, 1.0 op_sel:[0,1,0]
	v_cvt_scalef32_pk_f32_fp4 v[140:141], v19, 1.0 op_sel:[1,1,0]
	v_pk_fma_f32 v[42:43], v[130:131], v[134:135], v[42:43] op_sel_hi:[0,1,1]
	v_pk_fma_f32 v[44:45], v[130:131], v[136:137], v[44:45] op_sel_hi:[0,1,1]
	v_pk_fma_f32 v[46:47], v[130:131], v[138:139], v[46:47] op_sel_hi:[0,1,1]
	v_pk_fma_f32 v[48:49], v[130:131], v[140:141], v[48:49] op_sel_hi:[0,1,1]
	v_cvt_scalef32_pk_f32_fp4 v[134:135], v20, 1.0
	v_cvt_scalef32_pk_f32_fp4 v[136:137], v20, 1.0 op_sel:[1,0,0]
	v_cvt_scalef32_pk_f32_fp4 v[138:139], v20, 1.0 op_sel:[0,1,0]
	v_cvt_scalef32_pk_f32_fp4 v[140:141], v20, 1.0 op_sel:[1,1,0]
	v_pk_fma_f32 v[50:51], v[130:131], v[134:135], v[50:51] op_sel_hi:[0,1,1]
	v_pk_fma_f32 v[52:53], v[130:131], v[136:137], v[52:53] op_sel_hi:[0,1,1]
	v_pk_fma_f32 v[54:55], v[130:131], v[138:139], v[54:55] op_sel_hi:[0,1,1]
	v_pk_fma_f32 v[56:57], v[130:131], v[140:141], v[56:57] op_sel_hi:[0,1,1]
	v_cvt_scalef32_pk_f32_fp4 v[134:135], v21, 1.0
	v_cvt_scalef32_pk_f32_fp4 v[136:137], v21, 1.0 op_sel:[1,0,0]
	v_cvt_scalef32_pk_f32_fp4 v[138:139], v21, 1.0 op_sel:[0,1,0]
	v_cvt_scalef32_pk_f32_fp4 v[140:141], v21, 1.0 op_sel:[1,1,0]
	v_pk_fma_f32 v[58:59], v[130:131], v[134:135], v[58:59] op_sel_hi:[0,1,1]
	v_pk_fma_f32 v[60:61], v[130:131], v[136:137], v[60:61] op_sel_hi:[0,1,1]
	v_pk_fma_f32 v[62:63], v[130:131], v[138:139], v[62:63] op_sel_hi:[0,1,1]
	v_pk_fma_f32 v[64:65], v[130:131], v[140:141], v[64:65] op_sel_hi:[0,1,1]
	ds_read_b32 v130, v132 offset:48
	s_waitcnt vmcnt(9)
	v_cvt_scalef32_pk_f32_fp4 v[134:135], v30, 1.0
	v_cvt_scalef32_pk_f32_fp4 v[136:137], v30, 1.0 op_sel:[1,0,0]
	v_cvt_scalef32_pk_f32_fp4 v[138:139], v30, 1.0 op_sel:[0,1,0]
	v_cvt_scalef32_pk_f32_fp4 v[140:141], v30, 1.0 op_sel:[1,1,0]
	s_waitcnt lgkmcnt(0)
	v_pk_fma_f32 v[128:129], v[130:131], v[134:135], v[128:129] op_sel_hi:[0,1,1]
	v_pk_fma_f32 v[126:127], v[130:131], v[136:137], v[126:127] op_sel_hi:[0,1,1]
	v_pk_fma_f32 v[122:123], v[130:131], v[138:139], v[122:123] op_sel_hi:[0,1,1]
	v_pk_fma_f32 v[120:121], v[130:131], v[140:141], v[120:121] op_sel_hi:[0,1,1]
	v_cvt_scalef32_pk_f32_fp4 v[134:135], v31, 1.0
	v_cvt_scalef32_pk_f32_fp4 v[136:137], v31, 1.0 op_sel:[1,0,0]
	v_cvt_scalef32_pk_f32_fp4 v[138:139], v31, 1.0 op_sel:[0,1,0]
	v_cvt_scalef32_pk_f32_fp4 v[140:141], v31, 1.0 op_sel:[1,1,0]
	v_pk_fma_f32 v[118:119], v[130:131], v[134:135], v[118:119] op_sel_hi:[0,1,1]
	v_pk_fma_f32 v[116:117], v[130:131], v[136:137], v[116:117] op_sel_hi:[0,1,1]
	v_pk_fma_f32 v[114:115], v[130:131], v[138:139], v[114:115] op_sel_hi:[0,1,1]
	v_pk_fma_f32 v[112:113], v[130:131], v[140:141], v[112:113] op_sel_hi:[0,1,1]
	v_cvt_scalef32_pk_f32_fp4 v[134:135], v32, 1.0
	v_cvt_scalef32_pk_f32_fp4 v[136:137], v32, 1.0 op_sel:[1,0,0]
	v_cvt_scalef32_pk_f32_fp4 v[138:139], v32, 1.0 op_sel:[0,1,0]
	v_cvt_scalef32_pk_f32_fp4 v[140:141], v32, 1.0 op_sel:[1,1,0]
	v_pk_fma_f32 v[80:81], v[130:131], v[134:135], v[80:81] op_sel_hi:[0,1,1]
	v_pk_fma_f32 v[78:79], v[130:131], v[136:137], v[78:79] op_sel_hi:[0,1,1]
	v_pk_fma_f32 v[76:77], v[130:131], v[138:139], v[76:77] op_sel_hi:[0,1,1]
	v_pk_fma_f32 v[74:75], v[130:131], v[140:141], v[74:75] op_sel_hi:[0,1,1]
	v_cvt_scalef32_pk_f32_fp4 v[134:135], v33, 1.0
	v_cvt_scalef32_pk_f32_fp4 v[136:137], v33, 1.0 op_sel:[1,0,0]
	v_cvt_scalef32_pk_f32_fp4 v[138:139], v33, 1.0 op_sel:[0,1,0]
	v_cvt_scalef32_pk_f32_fp4 v[140:141], v33, 1.0 op_sel:[1,1,0]
	v_pk_fma_f32 v[72:73], v[130:131], v[134:135], v[72:73] op_sel_hi:[0,1,1]
	v_pk_fma_f32 v[70:71], v[130:131], v[136:137], v[70:71] op_sel_hi:[0,1,1]
	v_pk_fma_f32 v[68:69], v[130:131], v[138:139], v[68:69] op_sel_hi:[0,1,1]
	v_pk_fma_f32 v[66:67], v[130:131], v[140:141], v[66:67] op_sel_hi:[0,1,1]
	s_waitcnt vmcnt(8)
	v_cvt_scalef32_pk_f32_fp4 v[134:135], v26, 1.0
	v_cvt_scalef32_pk_f32_fp4 v[136:137], v26, 1.0 op_sel:[1,0,0]
	v_cvt_scalef32_pk_f32_fp4 v[138:139], v26, 1.0 op_sel:[0,1,0]
	v_cvt_scalef32_pk_f32_fp4 v[140:141], v26, 1.0 op_sel:[1,1,0]
	v_pk_fma_f32 v[34:35], v[130:131], v[134:135], v[34:35] op_sel_hi:[0,1,1]
	v_pk_fma_f32 v[36:37], v[130:131], v[136:137], v[36:37] op_sel_hi:[0,1,1]
	v_pk_fma_f32 v[38:39], v[130:131], v[138:139], v[38:39] op_sel_hi:[0,1,1]
	v_pk_fma_f32 v[40:41], v[130:131], v[140:141], v[40:41] op_sel_hi:[0,1,1]
	v_cvt_scalef32_pk_f32_fp4 v[134:135], v27, 1.0
	v_cvt_scalef32_pk_f32_fp4 v[136:137], v27, 1.0 op_sel:[1,0,0]
	v_cvt_scalef32_pk_f32_fp4 v[138:139], v27, 1.0 op_sel:[0,1,0]
	v_cvt_scalef32_pk_f32_fp4 v[140:141], v27, 1.0 op_sel:[1,1,0]
	v_pk_fma_f32 v[42:43], v[130:131], v[134:135], v[42:43] op_sel_hi:[0,1,1]
	v_pk_fma_f32 v[44:45], v[130:131], v[136:137], v[44:45] op_sel_hi:[0,1,1]
	v_pk_fma_f32 v[46:47], v[130:131], v[138:139], v[46:47] op_sel_hi:[0,1,1]
	v_pk_fma_f32 v[48:49], v[130:131], v[140:141], v[48:49] op_sel_hi:[0,1,1]
	v_cvt_scalef32_pk_f32_fp4 v[134:135], v28, 1.0
	v_cvt_scalef32_pk_f32_fp4 v[136:137], v28, 1.0 op_sel:[1,0,0]
	v_cvt_scalef32_pk_f32_fp4 v[138:139], v28, 1.0 op_sel:[0,1,0]
	v_cvt_scalef32_pk_f32_fp4 v[140:141], v28, 1.0 op_sel:[1,1,0]
	v_pk_fma_f32 v[50:51], v[130:131], v[134:135], v[50:51] op_sel_hi:[0,1,1]
	v_pk_fma_f32 v[52:53], v[130:131], v[136:137], v[52:53] op_sel_hi:[0,1,1]
	v_pk_fma_f32 v[54:55], v[130:131], v[138:139], v[54:55] op_sel_hi:[0,1,1]
	v_pk_fma_f32 v[56:57], v[130:131], v[140:141], v[56:57] op_sel_hi:[0,1,1]
	v_cvt_scalef32_pk_f32_fp4 v[134:135], v29, 1.0
	v_cvt_scalef32_pk_f32_fp4 v[136:137], v29, 1.0 op_sel:[1,0,0]
	v_cvt_scalef32_pk_f32_fp4 v[138:139], v29, 1.0 op_sel:[0,1,0]
	v_cvt_scalef32_pk_f32_fp4 v[140:141], v29, 1.0 op_sel:[1,1,0]
	v_pk_fma_f32 v[58:59], v[130:131], v[134:135], v[58:59] op_sel_hi:[0,1,1]
	v_pk_fma_f32 v[60:61], v[130:131], v[136:137], v[60:61] op_sel_hi:[0,1,1]
	v_pk_fma_f32 v[62:63], v[130:131], v[138:139], v[62:63] op_sel_hi:[0,1,1]
	v_pk_fma_f32 v[64:65], v[130:131], v[140:141], v[64:65] op_sel_hi:[0,1,1]
	ds_read_b32 v130, v132 offset:64
	s_waitcnt vmcnt(7)
	v_cvt_scalef32_pk_f32_fp4 v[134:135], v142, 1.0
	v_cvt_scalef32_pk_f32_fp4 v[136:137], v142, 1.0 op_sel:[1,0,0]
	v_cvt_scalef32_pk_f32_fp4 v[138:139], v142, 1.0 op_sel:[0,1,0]
	v_cvt_scalef32_pk_f32_fp4 v[140:141], v142, 1.0 op_sel:[1,1,0]
	s_waitcnt lgkmcnt(0)
	v_pk_fma_f32 v[128:129], v[130:131], v[134:135], v[128:129] op_sel_hi:[0,1,1]
	v_pk_fma_f32 v[126:127], v[130:131], v[136:137], v[126:127] op_sel_hi:[0,1,1]
	v_pk_fma_f32 v[122:123], v[130:131], v[138:139], v[122:123] op_sel_hi:[0,1,1]
	v_pk_fma_f32 v[120:121], v[130:131], v[140:141], v[120:121] op_sel_hi:[0,1,1]
	v_cvt_scalef32_pk_f32_fp4 v[134:135], v143, 1.0
	v_cvt_scalef32_pk_f32_fp4 v[136:137], v143, 1.0 op_sel:[1,0,0]
	v_cvt_scalef32_pk_f32_fp4 v[138:139], v143, 1.0 op_sel:[0,1,0]
	v_cvt_scalef32_pk_f32_fp4 v[140:141], v143, 1.0 op_sel:[1,1,0]
	v_pk_fma_f32 v[118:119], v[130:131], v[134:135], v[118:119] op_sel_hi:[0,1,1]
	v_pk_fma_f32 v[116:117], v[130:131], v[136:137], v[116:117] op_sel_hi:[0,1,1]
	v_pk_fma_f32 v[114:115], v[130:131], v[138:139], v[114:115] op_sel_hi:[0,1,1]
	v_pk_fma_f32 v[112:113], v[130:131], v[140:141], v[112:113] op_sel_hi:[0,1,1]
	v_cvt_scalef32_pk_f32_fp4 v[134:135], v144, 1.0
	v_cvt_scalef32_pk_f32_fp4 v[136:137], v144, 1.0 op_sel:[1,0,0]
	v_cvt_scalef32_pk_f32_fp4 v[138:139], v144, 1.0 op_sel:[0,1,0]
	v_cvt_scalef32_pk_f32_fp4 v[140:141], v144, 1.0 op_sel:[1,1,0]
	v_pk_fma_f32 v[80:81], v[130:131], v[134:135], v[80:81] op_sel_hi:[0,1,1]
	v_pk_fma_f32 v[78:79], v[130:131], v[136:137], v[78:79] op_sel_hi:[0,1,1]
	v_pk_fma_f32 v[76:77], v[130:131], v[138:139], v[76:77] op_sel_hi:[0,1,1]
	v_pk_fma_f32 v[74:75], v[130:131], v[140:141], v[74:75] op_sel_hi:[0,1,1]
	v_cvt_scalef32_pk_f32_fp4 v[134:135], v145, 1.0
	v_cvt_scalef32_pk_f32_fp4 v[136:137], v145, 1.0 op_sel:[1,0,0]
	v_cvt_scalef32_pk_f32_fp4 v[138:139], v145, 1.0 op_sel:[0,1,0]
	v_cvt_scalef32_pk_f32_fp4 v[140:141], v145, 1.0 op_sel:[1,1,0]
	v_pk_fma_f32 v[72:73], v[130:131], v[134:135], v[72:73] op_sel_hi:[0,1,1]
	v_pk_fma_f32 v[70:71], v[130:131], v[136:137], v[70:71] op_sel_hi:[0,1,1]
	v_pk_fma_f32 v[68:69], v[130:131], v[138:139], v[68:69] op_sel_hi:[0,1,1]
	v_pk_fma_f32 v[66:67], v[130:131], v[140:141], v[66:67] op_sel_hi:[0,1,1]
	s_waitcnt vmcnt(6)
	v_cvt_scalef32_pk_f32_fp4 v[134:135], v146, 1.0
	v_cvt_scalef32_pk_f32_fp4 v[136:137], v146, 1.0 op_sel:[1,0,0]
	v_cvt_scalef32_pk_f32_fp4 v[138:139], v146, 1.0 op_sel:[0,1,0]
	v_cvt_scalef32_pk_f32_fp4 v[140:141], v146, 1.0 op_sel:[1,1,0]
	v_pk_fma_f32 v[34:35], v[130:131], v[134:135], v[34:35] op_sel_hi:[0,1,1]
	v_pk_fma_f32 v[36:37], v[130:131], v[136:137], v[36:37] op_sel_hi:[0,1,1]
	v_pk_fma_f32 v[38:39], v[130:131], v[138:139], v[38:39] op_sel_hi:[0,1,1]
	v_pk_fma_f32 v[40:41], v[130:131], v[140:141], v[40:41] op_sel_hi:[0,1,1]
	v_cvt_scalef32_pk_f32_fp4 v[134:135], v147, 1.0
	v_cvt_scalef32_pk_f32_fp4 v[136:137], v147, 1.0 op_sel:[1,0,0]
	v_cvt_scalef32_pk_f32_fp4 v[138:139], v147, 1.0 op_sel:[0,1,0]
	v_cvt_scalef32_pk_f32_fp4 v[140:141], v147, 1.0 op_sel:[1,1,0]
	v_pk_fma_f32 v[42:43], v[130:131], v[134:135], v[42:43] op_sel_hi:[0,1,1]
	v_pk_fma_f32 v[44:45], v[130:131], v[136:137], v[44:45] op_sel_hi:[0,1,1]
	v_pk_fma_f32 v[46:47], v[130:131], v[138:139], v[46:47] op_sel_hi:[0,1,1]
	v_pk_fma_f32 v[48:49], v[130:131], v[140:141], v[48:49] op_sel_hi:[0,1,1]
	v_cvt_scalef32_pk_f32_fp4 v[134:135], v148, 1.0
	v_cvt_scalef32_pk_f32_fp4 v[136:137], v148, 1.0 op_sel:[1,0,0]
	v_cvt_scalef32_pk_f32_fp4 v[138:139], v148, 1.0 op_sel:[0,1,0]
	v_cvt_scalef32_pk_f32_fp4 v[140:141], v148, 1.0 op_sel:[1,1,0]
	v_pk_fma_f32 v[50:51], v[130:131], v[134:135], v[50:51] op_sel_hi:[0,1,1]
	v_pk_fma_f32 v[52:53], v[130:131], v[136:137], v[52:53] op_sel_hi:[0,1,1]
	v_pk_fma_f32 v[54:55], v[130:131], v[138:139], v[54:55] op_sel_hi:[0,1,1]
	v_pk_fma_f32 v[56:57], v[130:131], v[140:141], v[56:57] op_sel_hi:[0,1,1]
	v_cvt_scalef32_pk_f32_fp4 v[134:135], v149, 1.0
	v_cvt_scalef32_pk_f32_fp4 v[136:137], v149, 1.0 op_sel:[1,0,0]
	v_cvt_scalef32_pk_f32_fp4 v[138:139], v149, 1.0 op_sel:[0,1,0]
	v_cvt_scalef32_pk_f32_fp4 v[140:141], v149, 1.0 op_sel:[1,1,0]
	v_pk_fma_f32 v[58:59], v[130:131], v[134:135], v[58:59] op_sel_hi:[0,1,1]
	v_pk_fma_f32 v[60:61], v[130:131], v[136:137], v[60:61] op_sel_hi:[0,1,1]
	v_pk_fma_f32 v[62:63], v[130:131], v[138:139], v[62:63] op_sel_hi:[0,1,1]
	v_pk_fma_f32 v[64:65], v[130:131], v[140:141], v[64:65] op_sel_hi:[0,1,1]
	ds_read_b32 v130, v132 offset:80
	s_waitcnt vmcnt(5)
	v_cvt_scalef32_pk_f32_fp4 v[134:135], v150, 1.0
	v_cvt_scalef32_pk_f32_fp4 v[136:137], v150, 1.0 op_sel:[1,0,0]
	v_cvt_scalef32_pk_f32_fp4 v[138:139], v150, 1.0 op_sel:[0,1,0]
	v_cvt_scalef32_pk_f32_fp4 v[140:141], v150, 1.0 op_sel:[1,1,0]
	s_waitcnt lgkmcnt(0)
	v_pk_fma_f32 v[128:129], v[130:131], v[134:135], v[128:129] op_sel_hi:[0,1,1]
	v_pk_fma_f32 v[126:127], v[130:131], v[136:137], v[126:127] op_sel_hi:[0,1,1]
	v_pk_fma_f32 v[122:123], v[130:131], v[138:139], v[122:123] op_sel_hi:[0,1,1]
	v_pk_fma_f32 v[120:121], v[130:131], v[140:141], v[120:121] op_sel_hi:[0,1,1]
	v_cvt_scalef32_pk_f32_fp4 v[134:135], v151, 1.0
	v_cvt_scalef32_pk_f32_fp4 v[136:137], v151, 1.0 op_sel:[1,0,0]
	v_cvt_scalef32_pk_f32_fp4 v[138:139], v151, 1.0 op_sel:[0,1,0]
	v_cvt_scalef32_pk_f32_fp4 v[140:141], v151, 1.0 op_sel:[1,1,0]
	v_pk_fma_f32 v[118:119], v[130:131], v[134:135], v[118:119] op_sel_hi:[0,1,1]
	v_pk_fma_f32 v[116:117], v[130:131], v[136:137], v[116:117] op_sel_hi:[0,1,1]
	v_pk_fma_f32 v[114:115], v[130:131], v[138:139], v[114:115] op_sel_hi:[0,1,1]
	v_pk_fma_f32 v[112:113], v[130:131], v[140:141], v[112:113] op_sel_hi:[0,1,1]
	v_cvt_scalef32_pk_f32_fp4 v[134:135], v152, 1.0
	v_cvt_scalef32_pk_f32_fp4 v[136:137], v152, 1.0 op_sel:[1,0,0]
	v_cvt_scalef32_pk_f32_fp4 v[138:139], v152, 1.0 op_sel:[0,1,0]
	v_cvt_scalef32_pk_f32_fp4 v[140:141], v152, 1.0 op_sel:[1,1,0]
	v_pk_fma_f32 v[80:81], v[130:131], v[134:135], v[80:81] op_sel_hi:[0,1,1]
	v_pk_fma_f32 v[78:79], v[130:131], v[136:137], v[78:79] op_sel_hi:[0,1,1]
	v_pk_fma_f32 v[76:77], v[130:131], v[138:139], v[76:77] op_sel_hi:[0,1,1]
	v_pk_fma_f32 v[74:75], v[130:131], v[140:141], v[74:75] op_sel_hi:[0,1,1]
	v_cvt_scalef32_pk_f32_fp4 v[134:135], v153, 1.0
	v_cvt_scalef32_pk_f32_fp4 v[136:137], v153, 1.0 op_sel:[1,0,0]
	v_cvt_scalef32_pk_f32_fp4 v[138:139], v153, 1.0 op_sel:[0,1,0]
	v_cvt_scalef32_pk_f32_fp4 v[140:141], v153, 1.0 op_sel:[1,1,0]
	v_pk_fma_f32 v[72:73], v[130:131], v[134:135], v[72:73] op_sel_hi:[0,1,1]
	v_pk_fma_f32 v[70:71], v[130:131], v[136:137], v[70:71] op_sel_hi:[0,1,1]
	v_pk_fma_f32 v[68:69], v[130:131], v[138:139], v[68:69] op_sel_hi:[0,1,1]
	v_pk_fma_f32 v[66:67], v[130:131], v[140:141], v[66:67] op_sel_hi:[0,1,1]
	s_waitcnt vmcnt(4)
	v_cvt_scalef32_pk_f32_fp4 v[134:135], v232, 1.0
	v_cvt_scalef32_pk_f32_fp4 v[136:137], v232, 1.0 op_sel:[1,0,0]
	v_cvt_scalef32_pk_f32_fp4 v[138:139], v232, 1.0 op_sel:[0,1,0]
	v_cvt_scalef32_pk_f32_fp4 v[140:141], v232, 1.0 op_sel:[1,1,0]
	v_pk_fma_f32 v[34:35], v[130:131], v[134:135], v[34:35] op_sel_hi:[0,1,1]
	v_pk_fma_f32 v[36:37], v[130:131], v[136:137], v[36:37] op_sel_hi:[0,1,1]
	v_pk_fma_f32 v[38:39], v[130:131], v[138:139], v[38:39] op_sel_hi:[0,1,1]
	v_pk_fma_f32 v[40:41], v[130:131], v[140:141], v[40:41] op_sel_hi:[0,1,1]
	v_cvt_scalef32_pk_f32_fp4 v[134:135], v233, 1.0
	v_cvt_scalef32_pk_f32_fp4 v[136:137], v233, 1.0 op_sel:[1,0,0]
	v_cvt_scalef32_pk_f32_fp4 v[138:139], v233, 1.0 op_sel:[0,1,0]
	v_cvt_scalef32_pk_f32_fp4 v[140:141], v233, 1.0 op_sel:[1,1,0]
	v_pk_fma_f32 v[42:43], v[130:131], v[134:135], v[42:43] op_sel_hi:[0,1,1]
	v_pk_fma_f32 v[44:45], v[130:131], v[136:137], v[44:45] op_sel_hi:[0,1,1]
	v_pk_fma_f32 v[46:47], v[130:131], v[138:139], v[46:47] op_sel_hi:[0,1,1]
	v_pk_fma_f32 v[48:49], v[130:131], v[140:141], v[48:49] op_sel_hi:[0,1,1]
	v_cvt_scalef32_pk_f32_fp4 v[134:135], v234, 1.0
	v_cvt_scalef32_pk_f32_fp4 v[136:137], v234, 1.0 op_sel:[1,0,0]
	v_cvt_scalef32_pk_f32_fp4 v[138:139], v234, 1.0 op_sel:[0,1,0]
	v_cvt_scalef32_pk_f32_fp4 v[140:141], v234, 1.0 op_sel:[1,1,0]
	v_pk_fma_f32 v[50:51], v[130:131], v[134:135], v[50:51] op_sel_hi:[0,1,1]
	v_pk_fma_f32 v[52:53], v[130:131], v[136:137], v[52:53] op_sel_hi:[0,1,1]
	v_pk_fma_f32 v[54:55], v[130:131], v[138:139], v[54:55] op_sel_hi:[0,1,1]
	v_pk_fma_f32 v[56:57], v[130:131], v[140:141], v[56:57] op_sel_hi:[0,1,1]
	v_cvt_scalef32_pk_f32_fp4 v[134:135], v235, 1.0
	v_cvt_scalef32_pk_f32_fp4 v[136:137], v235, 1.0 op_sel:[1,0,0]
	v_cvt_scalef32_pk_f32_fp4 v[138:139], v235, 1.0 op_sel:[0,1,0]
	v_cvt_scalef32_pk_f32_fp4 v[140:141], v235, 1.0 op_sel:[1,1,0]
	v_pk_fma_f32 v[58:59], v[130:131], v[134:135], v[58:59] op_sel_hi:[0,1,1]
	v_pk_fma_f32 v[60:61], v[130:131], v[136:137], v[60:61] op_sel_hi:[0,1,1]
	v_pk_fma_f32 v[62:63], v[130:131], v[138:139], v[62:63] op_sel_hi:[0,1,1]
	v_pk_fma_f32 v[64:65], v[130:131], v[140:141], v[64:65] op_sel_hi:[0,1,1]
	ds_read_b32 v130, v132 offset:96
	s_waitcnt vmcnt(3)
	v_cvt_scalef32_pk_f32_fp4 v[134:135], v236, 1.0
	v_cvt_scalef32_pk_f32_fp4 v[136:137], v236, 1.0 op_sel:[1,0,0]
	v_cvt_scalef32_pk_f32_fp4 v[138:139], v236, 1.0 op_sel:[0,1,0]
	v_cvt_scalef32_pk_f32_fp4 v[140:141], v236, 1.0 op_sel:[1,1,0]
	s_waitcnt lgkmcnt(0)
	v_pk_fma_f32 v[128:129], v[130:131], v[134:135], v[128:129] op_sel_hi:[0,1,1]
	v_pk_fma_f32 v[126:127], v[130:131], v[136:137], v[126:127] op_sel_hi:[0,1,1]
	v_pk_fma_f32 v[122:123], v[130:131], v[138:139], v[122:123] op_sel_hi:[0,1,1]
	v_pk_fma_f32 v[120:121], v[130:131], v[140:141], v[120:121] op_sel_hi:[0,1,1]
	v_cvt_scalef32_pk_f32_fp4 v[134:135], v237, 1.0
	v_cvt_scalef32_pk_f32_fp4 v[136:137], v237, 1.0 op_sel:[1,0,0]
	v_cvt_scalef32_pk_f32_fp4 v[138:139], v237, 1.0 op_sel:[0,1,0]
	v_cvt_scalef32_pk_f32_fp4 v[140:141], v237, 1.0 op_sel:[1,1,0]
	v_pk_fma_f32 v[118:119], v[130:131], v[134:135], v[118:119] op_sel_hi:[0,1,1]
	v_pk_fma_f32 v[116:117], v[130:131], v[136:137], v[116:117] op_sel_hi:[0,1,1]
	v_pk_fma_f32 v[114:115], v[130:131], v[138:139], v[114:115] op_sel_hi:[0,1,1]
	v_pk_fma_f32 v[112:113], v[130:131], v[140:141], v[112:113] op_sel_hi:[0,1,1]
	v_cvt_scalef32_pk_f32_fp4 v[134:135], v238, 1.0
	v_cvt_scalef32_pk_f32_fp4 v[136:137], v238, 1.0 op_sel:[1,0,0]
	v_cvt_scalef32_pk_f32_fp4 v[138:139], v238, 1.0 op_sel:[0,1,0]
	v_cvt_scalef32_pk_f32_fp4 v[140:141], v238, 1.0 op_sel:[1,1,0]
	v_pk_fma_f32 v[80:81], v[130:131], v[134:135], v[80:81] op_sel_hi:[0,1,1]
	v_pk_fma_f32 v[78:79], v[130:131], v[136:137], v[78:79] op_sel_hi:[0,1,1]
	v_pk_fma_f32 v[76:77], v[130:131], v[138:139], v[76:77] op_sel_hi:[0,1,1]
	v_pk_fma_f32 v[74:75], v[130:131], v[140:141], v[74:75] op_sel_hi:[0,1,1]
	v_cvt_scalef32_pk_f32_fp4 v[134:135], v239, 1.0
	v_cvt_scalef32_pk_f32_fp4 v[136:137], v239, 1.0 op_sel:[1,0,0]
	v_cvt_scalef32_pk_f32_fp4 v[138:139], v239, 1.0 op_sel:[0,1,0]
	v_cvt_scalef32_pk_f32_fp4 v[140:141], v239, 1.0 op_sel:[1,1,0]
	v_pk_fma_f32 v[72:73], v[130:131], v[134:135], v[72:73] op_sel_hi:[0,1,1]
	v_pk_fma_f32 v[70:71], v[130:131], v[136:137], v[70:71] op_sel_hi:[0,1,1]
	v_pk_fma_f32 v[68:69], v[130:131], v[138:139], v[68:69] op_sel_hi:[0,1,1]
	v_pk_fma_f32 v[66:67], v[130:131], v[140:141], v[66:67] op_sel_hi:[0,1,1]
	s_waitcnt vmcnt(2)
	v_cvt_scalef32_pk_f32_fp4 v[134:135], v240, 1.0
	v_cvt_scalef32_pk_f32_fp4 v[136:137], v240, 1.0 op_sel:[1,0,0]
	v_cvt_scalef32_pk_f32_fp4 v[138:139], v240, 1.0 op_sel:[0,1,0]
	v_cvt_scalef32_pk_f32_fp4 v[140:141], v240, 1.0 op_sel:[1,1,0]
	v_pk_fma_f32 v[34:35], v[130:131], v[134:135], v[34:35] op_sel_hi:[0,1,1]
	v_pk_fma_f32 v[36:37], v[130:131], v[136:137], v[36:37] op_sel_hi:[0,1,1]
	v_pk_fma_f32 v[38:39], v[130:131], v[138:139], v[38:39] op_sel_hi:[0,1,1]
	v_pk_fma_f32 v[40:41], v[130:131], v[140:141], v[40:41] op_sel_hi:[0,1,1]
	v_cvt_scalef32_pk_f32_fp4 v[134:135], v241, 1.0
	v_cvt_scalef32_pk_f32_fp4 v[136:137], v241, 1.0 op_sel:[1,0,0]
	v_cvt_scalef32_pk_f32_fp4 v[138:139], v241, 1.0 op_sel:[0,1,0]
	v_cvt_scalef32_pk_f32_fp4 v[140:141], v241, 1.0 op_sel:[1,1,0]
	v_pk_fma_f32 v[42:43], v[130:131], v[134:135], v[42:43] op_sel_hi:[0,1,1]
	v_pk_fma_f32 v[44:45], v[130:131], v[136:137], v[44:45] op_sel_hi:[0,1,1]
	v_pk_fma_f32 v[46:47], v[130:131], v[138:139], v[46:47] op_sel_hi:[0,1,1]
	v_pk_fma_f32 v[48:49], v[130:131], v[140:141], v[48:49] op_sel_hi:[0,1,1]
	v_cvt_scalef32_pk_f32_fp4 v[134:135], v242, 1.0
	v_cvt_scalef32_pk_f32_fp4 v[136:137], v242, 1.0 op_sel:[1,0,0]
	v_cvt_scalef32_pk_f32_fp4 v[138:139], v242, 1.0 op_sel:[0,1,0]
	v_cvt_scalef32_pk_f32_fp4 v[140:141], v242, 1.0 op_sel:[1,1,0]
	v_pk_fma_f32 v[50:51], v[130:131], v[134:135], v[50:51] op_sel_hi:[0,1,1]
	v_pk_fma_f32 v[52:53], v[130:131], v[136:137], v[52:53] op_sel_hi:[0,1,1]
	v_pk_fma_f32 v[54:55], v[130:131], v[138:139], v[54:55] op_sel_hi:[0,1,1]
	v_pk_fma_f32 v[56:57], v[130:131], v[140:141], v[56:57] op_sel_hi:[0,1,1]
	v_cvt_scalef32_pk_f32_fp4 v[134:135], v243, 1.0
	v_cvt_scalef32_pk_f32_fp4 v[136:137], v243, 1.0 op_sel:[1,0,0]
	v_cvt_scalef32_pk_f32_fp4 v[138:139], v243, 1.0 op_sel:[0,1,0]
	v_cvt_scalef32_pk_f32_fp4 v[140:141], v243, 1.0 op_sel:[1,1,0]
	v_pk_fma_f32 v[58:59], v[130:131], v[134:135], v[58:59] op_sel_hi:[0,1,1]
	v_pk_fma_f32 v[60:61], v[130:131], v[136:137], v[60:61] op_sel_hi:[0,1,1]
	v_pk_fma_f32 v[62:63], v[130:131], v[138:139], v[62:63] op_sel_hi:[0,1,1]
	v_pk_fma_f32 v[64:65], v[130:131], v[140:141], v[64:65] op_sel_hi:[0,1,1]
	ds_read_b32 v130, v132 offset:112
	s_waitcnt vmcnt(1)
	v_cvt_scalef32_pk_f32_fp4 v[134:135], v244, 1.0
	v_cvt_scalef32_pk_f32_fp4 v[136:137], v244, 1.0 op_sel:[1,0,0]
	v_cvt_scalef32_pk_f32_fp4 v[138:139], v244, 1.0 op_sel:[0,1,0]
	v_cvt_scalef32_pk_f32_fp4 v[140:141], v244, 1.0 op_sel:[1,1,0]
	s_waitcnt lgkmcnt(0)
	v_pk_fma_f32 v[128:129], v[130:131], v[134:135], v[128:129] op_sel_hi:[0,1,1]
	v_pk_fma_f32 v[126:127], v[130:131], v[136:137], v[126:127] op_sel_hi:[0,1,1]
	v_pk_fma_f32 v[122:123], v[130:131], v[138:139], v[122:123] op_sel_hi:[0,1,1]
	v_pk_fma_f32 v[120:121], v[130:131], v[140:141], v[120:121] op_sel_hi:[0,1,1]
	v_cvt_scalef32_pk_f32_fp4 v[134:135], v245, 1.0
	v_cvt_scalef32_pk_f32_fp4 v[136:137], v245, 1.0 op_sel:[1,0,0]
	v_cvt_scalef32_pk_f32_fp4 v[138:139], v245, 1.0 op_sel:[0,1,0]
	v_cvt_scalef32_pk_f32_fp4 v[140:141], v245, 1.0 op_sel:[1,1,0]
	v_pk_fma_f32 v[118:119], v[130:131], v[134:135], v[118:119] op_sel_hi:[0,1,1]
	v_pk_fma_f32 v[116:117], v[130:131], v[136:137], v[116:117] op_sel_hi:[0,1,1]
	v_pk_fma_f32 v[114:115], v[130:131], v[138:139], v[114:115] op_sel_hi:[0,1,1]
	v_pk_fma_f32 v[112:113], v[130:131], v[140:141], v[112:113] op_sel_hi:[0,1,1]
	v_cvt_scalef32_pk_f32_fp4 v[134:135], v246, 1.0
	v_cvt_scalef32_pk_f32_fp4 v[136:137], v246, 1.0 op_sel:[1,0,0]
	v_cvt_scalef32_pk_f32_fp4 v[138:139], v246, 1.0 op_sel:[0,1,0]
	v_cvt_scalef32_pk_f32_fp4 v[140:141], v246, 1.0 op_sel:[1,1,0]
	v_pk_fma_f32 v[80:81], v[130:131], v[134:135], v[80:81] op_sel_hi:[0,1,1]
	v_pk_fma_f32 v[78:79], v[130:131], v[136:137], v[78:79] op_sel_hi:[0,1,1]
	v_pk_fma_f32 v[76:77], v[130:131], v[138:139], v[76:77] op_sel_hi:[0,1,1]
	v_pk_fma_f32 v[74:75], v[130:131], v[140:141], v[74:75] op_sel_hi:[0,1,1]
	v_cvt_scalef32_pk_f32_fp4 v[134:135], v247, 1.0
	v_cvt_scalef32_pk_f32_fp4 v[136:137], v247, 1.0 op_sel:[1,0,0]
	v_cvt_scalef32_pk_f32_fp4 v[138:139], v247, 1.0 op_sel:[0,1,0]
	v_cvt_scalef32_pk_f32_fp4 v[140:141], v247, 1.0 op_sel:[1,1,0]
	v_pk_fma_f32 v[72:73], v[130:131], v[134:135], v[72:73] op_sel_hi:[0,1,1]
	v_pk_fma_f32 v[70:71], v[130:131], v[136:137], v[70:71] op_sel_hi:[0,1,1]
	v_pk_fma_f32 v[68:69], v[130:131], v[138:139], v[68:69] op_sel_hi:[0,1,1]
	v_pk_fma_f32 v[66:67], v[130:131], v[140:141], v[66:67] op_sel_hi:[0,1,1]
	s_waitcnt vmcnt(0)
	v_cvt_scalef32_pk_f32_fp4 v[134:135], v228, 1.0
	v_cvt_scalef32_pk_f32_fp4 v[136:137], v228, 1.0 op_sel:[1,0,0]
	v_cvt_scalef32_pk_f32_fp4 v[138:139], v228, 1.0 op_sel:[0,1,0]
	v_cvt_scalef32_pk_f32_fp4 v[140:141], v228, 1.0 op_sel:[1,1,0]
	v_pk_fma_f32 v[34:35], v[130:131], v[134:135], v[34:35] op_sel_hi:[0,1,1]
	v_pk_fma_f32 v[36:37], v[130:131], v[136:137], v[36:37] op_sel_hi:[0,1,1]
	v_pk_fma_f32 v[38:39], v[130:131], v[138:139], v[38:39] op_sel_hi:[0,1,1]
	v_pk_fma_f32 v[40:41], v[130:131], v[140:141], v[40:41] op_sel_hi:[0,1,1]
	v_cvt_scalef32_pk_f32_fp4 v[134:135], v229, 1.0
	v_cvt_scalef32_pk_f32_fp4 v[136:137], v229, 1.0 op_sel:[1,0,0]
	v_cvt_scalef32_pk_f32_fp4 v[138:139], v229, 1.0 op_sel:[0,1,0]
	v_cvt_scalef32_pk_f32_fp4 v[140:141], v229, 1.0 op_sel:[1,1,0]
	v_pk_fma_f32 v[42:43], v[130:131], v[134:135], v[42:43] op_sel_hi:[0,1,1]
	v_pk_fma_f32 v[44:45], v[130:131], v[136:137], v[44:45] op_sel_hi:[0,1,1]
	v_pk_fma_f32 v[46:47], v[130:131], v[138:139], v[46:47] op_sel_hi:[0,1,1]
	v_pk_fma_f32 v[48:49], v[130:131], v[140:141], v[48:49] op_sel_hi:[0,1,1]
	v_cvt_scalef32_pk_f32_fp4 v[134:135], v230, 1.0
	v_cvt_scalef32_pk_f32_fp4 v[136:137], v230, 1.0 op_sel:[1,0,0]
	v_cvt_scalef32_pk_f32_fp4 v[138:139], v230, 1.0 op_sel:[0,1,0]
	v_cvt_scalef32_pk_f32_fp4 v[140:141], v230, 1.0 op_sel:[1,1,0]
	v_pk_fma_f32 v[50:51], v[130:131], v[134:135], v[50:51] op_sel_hi:[0,1,1]
	v_pk_fma_f32 v[52:53], v[130:131], v[136:137], v[52:53] op_sel_hi:[0,1,1]
	v_pk_fma_f32 v[54:55], v[130:131], v[138:139], v[54:55] op_sel_hi:[0,1,1]
	v_pk_fma_f32 v[56:57], v[130:131], v[140:141], v[56:57] op_sel_hi:[0,1,1]
	v_cvt_scalef32_pk_f32_fp4 v[134:135], v231, 1.0
	v_cvt_scalef32_pk_f32_fp4 v[136:137], v231, 1.0 op_sel:[1,0,0]
	v_cvt_scalef32_pk_f32_fp4 v[138:139], v231, 1.0 op_sel:[0,1,0]
	v_cvt_scalef32_pk_f32_fp4 v[140:141], v231, 1.0 op_sel:[1,1,0]
	v_pk_fma_f32 v[58:59], v[130:131], v[134:135], v[58:59] op_sel_hi:[0,1,1]
	v_pk_fma_f32 v[60:61], v[130:131], v[136:137], v[60:61] op_sel_hi:[0,1,1]
	v_pk_fma_f32 v[62:63], v[130:131], v[138:139], v[62:63] op_sel_hi:[0,1,1]
	v_pk_fma_f32 v[64:65], v[130:131], v[140:141], v[64:65] op_sel_hi:[0,1,1]
	s_setprio 2
	v_lshrrev_b32_e32 v2, 1, v125
	v_and_b32_e32 v3, 1, v125
	v_lshlrev_b32_e32 v2, 9, v2
	v_lshl_add_u32 v2, v3, 4, v2
	v_lshlrev_b64 v[94:95], 10, v[94:95]
	v_or_b32_e32 v94, v94, v82
	v_add_u32_e32 v94, v94, v2
	v_lshlrev_b64 v[130:131], 2, v[94:95]
	v_lshl_add_u64 v[132:133], s[18:19], 0, v[130:131]
	global_load_dwordx4 v[4:7], v[132:133], off
	global_load_dwordx4 v[8:11], v[132:133], off offset:16
	global_load_dwordx4 v[12:15], v[132:133], off offset:32
	global_load_dwordx4 v[16:19], v[132:133], off offset:48
	v_lshlrev_b32_e32 v2, 2, v2
	v_mov_b32_e32 v3, 0
	v_lshl_add_u64 v[20:21], v[88:89], 0, v[2:3]
	global_load_dwordx4 v[134:137], v[20:21], off
	global_load_dwordx4 v[138:141], v[20:21], off offset:16
	global_load_dwordx4 v[142:145], v[20:21], off offset:32
	global_load_dwordx4 v[146:149], v[20:21], off offset:48
	v_readlane_b32 s60, v254, 29
	v_readlane_b32 s61, v254, 30
	v_readlane_b32 s62, v254, 31
	v_readlane_b32 s63, v254, 32
	v_lshl_add_u64 v[22:23], s[20:21], 0, v[130:131]
	v_lshl_add_u64 v[26:27], v[94:95], 1, s[16:17]
	v_permlane16_swap_b32_e32 v128, v80
	v_permlane16_swap_b32_e32 v129, v81
	v_pk_add_f32 v[128:129], v[128:129], v[80:81]
	v_permlane16_swap_b32_e32 v126, v78
	v_permlane16_swap_b32_e32 v127, v79
	v_pk_add_f32 v[126:127], v[126:127], v[78:79]
	v_permlane16_swap_b32_e32 v122, v76
	v_permlane16_swap_b32_e32 v123, v77
	v_pk_add_f32 v[122:123], v[122:123], v[76:77]
	v_permlane16_swap_b32_e32 v120, v74
	v_permlane16_swap_b32_e32 v121, v75
	v_pk_add_f32 v[120:121], v[120:121], v[74:75]
	v_permlane16_swap_b32_e32 v118, v72
	v_permlane16_swap_b32_e32 v119, v73
	v_pk_add_f32 v[118:119], v[118:119], v[72:73]
	v_permlane16_swap_b32_e32 v116, v70
	v_permlane16_swap_b32_e32 v117, v71
	v_pk_add_f32 v[116:117], v[116:117], v[70:71]
	v_permlane16_swap_b32_e32 v114, v68
	v_permlane16_swap_b32_e32 v115, v69
	v_pk_add_f32 v[114:115], v[114:115], v[68:69]
	v_permlane16_swap_b32_e32 v112, v66
	v_permlane16_swap_b32_e32 v113, v67
	v_pk_add_f32 v[112:113], v[112:113], v[66:67]
	v_permlane16_swap_b32_e32 v34, v50
	v_permlane16_swap_b32_e32 v35, v51
	v_pk_add_f32 v[34:35], v[34:35], v[50:51]
	v_permlane16_swap_b32_e32 v36, v52
	v_permlane16_swap_b32_e32 v37, v53
	v_pk_add_f32 v[36:37], v[36:37], v[52:53]
	v_permlane16_swap_b32_e32 v38, v54
	v_permlane16_swap_b32_e32 v39, v55
	v_pk_add_f32 v[38:39], v[38:39], v[54:55]
	v_permlane16_swap_b32_e32 v40, v56
	v_permlane16_swap_b32_e32 v41, v57
	v_pk_add_f32 v[40:41], v[40:41], v[56:57]
	v_permlane16_swap_b32_e32 v42, v58
	v_permlane16_swap_b32_e32 v43, v59
	v_pk_add_f32 v[42:43], v[42:43], v[58:59]
	v_permlane16_swap_b32_e32 v44, v60
	v_permlane16_swap_b32_e32 v45, v61
	v_pk_add_f32 v[44:45], v[44:45], v[60:61]
	v_permlane16_swap_b32_e32 v46, v62
	v_permlane16_swap_b32_e32 v47, v63
	v_pk_add_f32 v[46:47], v[46:47], v[62:63]
	v_permlane16_swap_b32_e32 v48, v64
	v_permlane16_swap_b32_e32 v49, v65
	v_pk_add_f32 v[48:49], v[48:49], v[64:65]
	v_permlane32_swap_b32_e32 v128, v34
	v_permlane32_swap_b32_e32 v129, v35
	v_pk_add_f32 v[128:129], v[128:129], v[34:35]
	v_permlane32_swap_b32_e32 v126, v36
	v_permlane32_swap_b32_e32 v127, v37
	v_pk_add_f32 v[126:127], v[126:127], v[36:37]
	v_permlane32_swap_b32_e32 v122, v38
	v_permlane32_swap_b32_e32 v123, v39
	v_pk_add_f32 v[122:123], v[122:123], v[38:39]
	v_permlane32_swap_b32_e32 v120, v40
	v_permlane32_swap_b32_e32 v121, v41
	v_pk_add_f32 v[120:121], v[120:121], v[40:41]
	v_permlane32_swap_b32_e32 v118, v42
	v_permlane32_swap_b32_e32 v119, v43
	v_pk_add_f32 v[118:119], v[118:119], v[42:43]
	v_permlane32_swap_b32_e32 v116, v44
	v_permlane32_swap_b32_e32 v117, v45
	v_pk_add_f32 v[116:117], v[116:117], v[44:45]
	v_permlane32_swap_b32_e32 v114, v46
	v_permlane32_swap_b32_e32 v115, v47
	v_pk_add_f32 v[114:115], v[114:115], v[46:47]
	v_permlane32_swap_b32_e32 v112, v48
	v_permlane32_swap_b32_e32 v113, v49
	v_pk_add_f32 v[112:113], v[112:113], v[48:49]
	v_lshl_add_u64 v[24:25], s[60:61], 0, v[130:131]
	s_waitcnt vmcnt(4)
	v_pk_add_f32 v[228:229], v[4:5], v[128:129]
	v_pk_add_f32 v[230:231], v[6:7], v[126:127]
	v_pk_add_f32 v[232:233], v[8:9], v[122:123]
	v_pk_add_f32 v[234:235], v[10:11], v[120:121]
	v_pk_add_f32 v[236:237], v[12:13], v[118:119]
	v_pk_add_f32 v[238:239], v[14:15], v[116:117]
	v_pk_add_f32 v[240:241], v[16:17], v[114:115]
	v_pk_add_f32 v[242:243], v[18:19], v[112:113]
	v_pk_mul_f32 v[244:245], v[228:229], v[228:229]
	v_pk_fma_f32 v[244:245], v[230:231], v[230:231], v[244:245]
	v_pk_fma_f32 v[244:245], v[232:233], v[232:233], v[244:245]
	v_pk_fma_f32 v[244:245], v[234:235], v[234:235], v[244:245]
	v_pk_fma_f32 v[244:245], v[236:237], v[236:237], v[244:245]
	v_pk_fma_f32 v[244:245], v[238:239], v[238:239], v[244:245]
	v_pk_fma_f32 v[244:245], v[240:241], v[240:241], v[244:245]
	v_pk_fma_f32 v[244:245], v[242:243], v[242:243], v[244:245]
	v_add_f32_e32 v244, v244, v245
	ds_bpermute_b32 v245, v207, v244
	s_waitcnt lgkmcnt(0)
	v_add_f32_e32 v244, v244, v245
	ds_bpermute_b32 v245, v208, v244
	s_waitcnt lgkmcnt(0)
	v_add_f32_e32 v244, v244, v245
	ds_bpermute_b32 v245, v209, v244
	s_waitcnt lgkmcnt(0)
	v_add_f32_e32 v244, v244, v245
	ds_bpermute_b32 v245, v210, v244
	s_waitcnt lgkmcnt(0)
	v_add_f32_e32 v244, v244, v245
	ds_bpermute_b32 v245, v211, v244
	s_waitcnt lgkmcnt(0)
	v_add_f32_e32 v244, v244, v245
	ds_bpermute_b32 v245, v212, v244
	s_waitcnt lgkmcnt(0)
	v_add_f32_e32 v244, v244, v245
	v_fmamk_f32 v244, v244, 0x3a800000, v172
	v_mul_f32_e32 v245, 0x4b800000, v244
	v_cmp_gt_f32_e32 vcc, s96, v244
	s_nop 1
	v_cndmask_b32_e32 v244, v244, v245, vcc
	v_rsq_f32_e32 v244, v244
	s_nop 0
	v_mul_f32_e32 v245, 0x45800000, v244
	v_cndmask_b32_e32 v246, v244, v245, vcc
	s_waitcnt vmcnt(0)
	v_pk_mul_f32 v[134:135], v[246:247], v[134:135] op_sel_hi:[0,1]
	v_pk_mul_f32 v[136:137], v[246:247], v[136:137] op_sel_hi:[0,1]
	v_pk_mul_f32 v[138:139], v[246:247], v[138:139] op_sel_hi:[0,1]
	v_pk_mul_f32 v[140:141], v[246:247], v[140:141] op_sel_hi:[0,1]
	v_pk_mul_f32 v[142:143], v[246:247], v[142:143] op_sel_hi:[0,1]
	v_pk_mul_f32 v[144:145], v[246:247], v[144:145] op_sel_hi:[0,1]
	v_pk_mul_f32 v[146:147], v[246:247], v[146:147] op_sel_hi:[0,1]
	v_pk_mul_f32 v[148:149], v[246:247], v[148:149] op_sel_hi:[0,1]
	v_pk_mul_f32 v[134:135], v[228:229], v[134:135]
	v_pk_mul_f32 v[136:137], v[230:231], v[136:137]
	v_pk_mul_f32 v[138:139], v[232:233], v[138:139]
	v_pk_mul_f32 v[140:141], v[234:235], v[140:141]
	v_pk_mul_f32 v[142:143], v[236:237], v[142:143]
	v_pk_mul_f32 v[144:145], v[238:239], v[144:145]
	v_pk_mul_f32 v[146:147], v[240:241], v[146:147]
	v_pk_mul_f32 v[148:149], v[242:243], v[148:149]
	s_andn2_b64 vcc, exec, s[22:23]
	s_cbranch_vccnz .Lpe_mid
	global_store_dwordx4 v[24:25], v[134:137], off
	global_store_dwordx4 v[24:25], v[138:141], off offset:16
	global_store_dwordx4 v[24:25], v[142:145], off offset:32
	global_store_dwordx4 v[24:25], v[146:149], off offset:48
	s_branch .Lpe_done

.Lpe_done:
	s_setprio 0
	s_mov_b64 s[6:7], exec
	s_branch .LBB0_140

.LBB0_218:
	s_barrier
	s_waitcnt vmcnt(7)
	ds_write_b128 v102, v[66:69]
	s_waitcnt vmcnt(6)
	ds_write_b128 v102, v[70:73] offset:18432
	s_waitcnt vmcnt(5)
	ds_write_b128 v102, v[74:77] offset:4096
	s_waitcnt vmcnt(4)
	ds_write_b128 v102, v[78:81] offset:22528
	s_waitcnt vmcnt(3)
	ds_write_b128 v102, v[82:85] offset:8192
	s_waitcnt vmcnt(2)
	ds_write_b128 v102, v[86:89] offset:26624
	s_waitcnt vmcnt(1)
	ds_write_b128 v102, v[90:93] offset:12288
	s_waitcnt vmcnt(0)
	ds_write_b128 v102, v[94:97] offset:30720
	s_waitcnt lgkmcnt(0)
	s_barrier
	s_add_u32 s100, s6, 0x27c0000
	s_addc_u32 s101, s7, 0
	v_lshl_add_u64 v[212:213], v[110:111], 0, s[100:101]
	global_load_dwordx4 v[66:69], v[212:213], off offset:128
	s_add_u32 s100, s6, 0x200000
	s_addc_u32 s101, s7, 0
	v_lshl_add_u64 v[214:215], v[108:109], 0, s[100:101]
	global_load_dwordx4 v[70:73], v[214:215], off offset:128
	s_add_u32 s100, s6, 0x27d0000
	s_addc_u32 s101, s7, 0
	v_lshl_add_u64 v[216:217], v[110:111], 0, s[100:101]
	global_load_dwordx4 v[74:77], v[216:217], off offset:128
	s_add_u32 s100, s6, 0x210000
	s_addc_u32 s101, s7, 0
	v_lshl_add_u64 v[218:219], v[108:109], 0, s[100:101]
	global_load_dwordx4 v[78:81], v[218:219], off offset:128
	s_add_u32 s100, s6, 0x27e0000
	s_addc_u32 s101, s7, 0
	v_lshl_add_u64 v[212:213], v[110:111], 0, s[100:101]
	global_load_dwordx4 v[82:85], v[212:213], off offset:128
	s_add_u32 s100, s6, 0x220000
	s_addc_u32 s101, s7, 0
	v_lshl_add_u64 v[214:215], v[108:109], 0, s[100:101]
	global_load_dwordx4 v[86:89], v[214:215], off offset:128
	s_add_u32 s100, s6, 0x27f0000
	s_addc_u32 s101, s7, 0
	v_lshl_add_u64 v[216:217], v[110:111], 0, s[100:101]
	global_load_dwordx4 v[90:93], v[216:217], off offset:128
	s_add_u32 s100, s6, 0x230000
	s_addc_u32 s101, s7, 0
	v_lshl_add_u64 v[218:219], v[108:109], 0, s[100:101]
	global_load_dwordx4 v[94:97], v[218:219], off offset:128
	s_setprio 3
	ds_read_b128 v[146:149], v115 offset:18432
	ds_read_b128 v[150:153], v0
	ds_read_b128 v[154:157], v115 offset:20480
	ds_read_b128 v[158:161], v115 offset:22528
	ds_read_b128 v[162:165], v115 offset:24576
	s_waitcnt lgkmcnt(3)
	v_mfma_f32_16x16x32_bf16 v[10:13], v[146:149], v[150:153], v[10:13]
	s_waitcnt lgkmcnt(2)
	v_mfma_f32_16x16x32_bf16 v[2:5], v[154:157], v[150:153], v[2:5]
	s_waitcnt lgkmcnt(1)
	v_mfma_f32_16x16x32_bf16 v[6:9], v[158:161], v[150:153], v[6:9]
	s_waitcnt lgkmcnt(0)
	v_mfma_f32_16x16x32_bf16 v[22:25], v[162:165], v[150:153], v[22:25]
	ds_read_b128 v[150:153], v0 offset:2048
	s_waitcnt lgkmcnt(0)
	v_mfma_f32_16x16x32_bf16 v[14:17], v[146:149], v[150:153], v[14:17]
	v_mfma_f32_16x16x32_bf16 v[18:21], v[154:157], v[150:153], v[18:21]
	v_mfma_f32_16x16x32_bf16 v[26:29], v[158:161], v[150:153], v[26:29]
	v_mfma_f32_16x16x32_bf16 v[30:33], v[162:165], v[150:153], v[30:33]
	ds_read_b128 v[150:153], v0 offset:4096
	s_waitcnt lgkmcnt(0)
	v_mfma_f32_16x16x32_bf16 v[46:49], v[146:149], v[150:153], v[46:49]
	v_mfma_f32_16x16x32_bf16 v[54:57], v[154:157], v[150:153], v[54:57]
	v_mfma_f32_16x16x32_bf16 v[58:61], v[158:161], v[150:153], v[58:61]
	v_mfma_f32_16x16x32_bf16 v[62:65], v[162:165], v[150:153], v[62:65]
	ds_read_b128 v[150:153], v0 offset:6144
	s_waitcnt lgkmcnt(0)
	v_mfma_f32_16x16x32_bf16 v[50:53], v[146:149], v[150:153], v[50:53]
	v_mfma_f32_16x16x32_bf16 v[42:45], v[154:157], v[150:153], v[42:45]
	ds_read_b128 v[154:157], v249 offset:18432
	ds_read_b128 v[146:149], v248
	ds_read_b128 v[208:211], v249 offset:22528
	v_mfma_f32_16x16x32_bf16 v[34:37], v[162:165], v[150:153], v[34:37]
	ds_read_b128 v[162:165], v249 offset:20480
	v_mfma_f32_16x16x32_bf16 v[38:41], v[158:161], v[150:153], v[38:41]
	ds_read_b128 v[116:119], v249 offset:24576
	ds_read_b128 v[150:153], v248 offset:2048
	ds_read_b128 v[158:161], v248 offset:4096
	ds_read_b128 v[120:123], v248 offset:6144
	s_waitcnt lgkmcnt(6)
	v_mfma_f32_16x16x32_bf16 v[10:13], v[154:157], v[146:149], v[10:13]
	s_waitcnt lgkmcnt(4)
	v_mfma_f32_16x16x32_bf16 v[2:5], v[162:165], v[146:149], v[2:5]
	v_mfma_f32_16x16x32_bf16 v[6:9], v[208:211], v[146:149], v[6:9]
	s_waitcnt lgkmcnt(3)
	v_mfma_f32_16x16x32_bf16 v[22:25], v[116:119], v[146:149], v[22:25]
	s_waitcnt lgkmcnt(2)
	v_mfma_f32_16x16x32_bf16 v[14:17], v[154:157], v[150:153], v[14:17]
	v_mfma_f32_16x16x32_bf16 v[18:21], v[162:165], v[150:153], v[18:21]
	v_mfma_f32_16x16x32_bf16 v[26:29], v[208:211], v[150:153], v[26:29]
	v_mfma_f32_16x16x32_bf16 v[30:33], v[116:119], v[150:153], v[30:33]
	s_waitcnt lgkmcnt(1)
	v_mfma_f32_16x16x32_bf16 v[46:49], v[154:157], v[158:161], v[46:49]
	v_mfma_f32_16x16x32_bf16 v[54:57], v[162:165], v[158:161], v[54:57]
	v_mfma_f32_16x16x32_bf16 v[58:61], v[208:211], v[158:161], v[58:61]
	v_mfma_f32_16x16x32_bf16 v[62:65], v[116:119], v[158:161], v[62:65]
	s_waitcnt lgkmcnt(0)
	v_mfma_f32_16x16x32_bf16 v[50:53], v[154:157], v[120:123], v[50:53]
	v_mfma_f32_16x16x32_bf16 v[42:45], v[162:165], v[120:123], v[42:45]
	v_mfma_f32_16x16x32_bf16 v[38:41], v[208:211], v[120:123], v[38:41]
	v_mfma_f32_16x16x32_bf16 v[34:37], v[116:119], v[120:123], v[34:37]
	s_setprio 0
	s_add_u32 s6, s6, 0x80
	s_addc_u32 s7, s7, 0
	s_cmpk_eq_i32 s6, 0x780
	s_cbranch_scc0 .LBB0_218
	s_barrier
	s_waitcnt vmcnt(7)
	ds_write_b128 v102, v[66:69]
	s_waitcnt vmcnt(6)
	ds_write_b128 v102, v[70:73] offset:18432
	s_waitcnt vmcnt(5)
	ds_write_b128 v102, v[74:77] offset:4096
	s_waitcnt vmcnt(4)
	ds_write_b128 v102, v[78:81] offset:22528
	s_waitcnt vmcnt(3)
	ds_write_b128 v102, v[82:85] offset:8192
	s_waitcnt vmcnt(2)
	ds_write_b128 v102, v[86:89] offset:26624
	s_waitcnt vmcnt(1)
	ds_write_b128 v102, v[90:93] offset:12288
	s_waitcnt vmcnt(0)
	ds_write_b128 v102, v[94:97] offset:30720
	s_waitcnt lgkmcnt(0)
	s_barrier
	s_setprio 3
	ds_read_b128 v[66:69], v0
	ds_read_b128 v[70:73], v0 offset:2048
	ds_read_b128 v[74:77], v0 offset:4096
	ds_read_b128 v[78:81], v0 offset:6144
	ds_read_b128 v[82:85], v115 offset:18432
	ds_read_b128 v[86:89], v115 offset:20480
	ds_read_b128 v[90:93], v115 offset:22528
	ds_read_b128 v[94:97], v115 offset:24576
	s_waitcnt lgkmcnt(3)
	v_mfma_f32_16x16x32_bf16 v[10:13], v[82:85], v[66:69], v[10:13]
	s_add_i32 s0, s0, s66
	s_cmpk_gt_i32 s0, 0x3ff
	s_waitcnt lgkmcnt(2)
	v_mfma_f32_16x16x32_bf16 v[2:5], v[86:89], v[66:69], v[2:5]
	s_waitcnt lgkmcnt(1)
	v_mfma_f32_16x16x32_bf16 v[6:9], v[90:93], v[66:69], v[6:9]
	s_waitcnt lgkmcnt(0)
	v_mfma_f32_16x16x32_bf16 v[22:25], v[94:97], v[66:69], v[22:25]
	v_mfma_f32_16x16x32_bf16 v[14:17], v[82:85], v[70:73], v[14:17]
	v_mfma_f32_16x16x32_bf16 v[18:21], v[86:89], v[70:73], v[18:21]
	v_mfma_f32_16x16x32_bf16 v[26:29], v[90:93], v[70:73], v[26:29]
	v_mfma_f32_16x16x32_bf16 v[30:33], v[94:97], v[70:73], v[30:33]
	v_mfma_f32_16x16x32_bf16 v[46:49], v[82:85], v[74:77], v[46:49]
	v_mfma_f32_16x16x32_bf16 v[54:57], v[86:89], v[74:77], v[54:57]
	v_mfma_f32_16x16x32_bf16 v[58:61], v[90:93], v[74:77], v[58:61]
	v_mfma_f32_16x16x32_bf16 v[62:65], v[94:97], v[74:77], v[62:65]
	v_mfma_f32_16x16x32_bf16 v[50:53], v[82:85], v[78:81], v[50:53]
	v_mfma_f32_16x16x32_bf16 v[42:45], v[86:89], v[78:81], v[42:45]
	v_mfma_f32_16x16x32_bf16 v[38:41], v[90:93], v[78:81], v[38:41]
	v_mfma_f32_16x16x32_bf16 v[34:37], v[94:97], v[78:81], v[34:37]
	ds_read_b128 v[66:69], v248
	ds_read_b128 v[70:73], v248 offset:2048
	ds_read_b128 v[74:77], v248 offset:4096
	ds_read_b128 v[78:81], v248 offset:6144
	ds_read_b128 v[82:85], v249 offset:18432
	ds_read_b128 v[86:89], v249 offset:20480
	ds_read_b128 v[90:93], v249 offset:22528
	ds_read_b128 v[94:97], v249 offset:24576
	s_waitcnt lgkmcnt(3)
	v_mfma_f32_16x16x32_bf16 v[10:13], v[82:85], v[66:69], v[10:13]
	s_waitcnt lgkmcnt(2)
	v_mfma_f32_16x16x32_bf16 v[2:5], v[86:89], v[66:69], v[2:5]
	s_waitcnt lgkmcnt(1)
	v_mfma_f32_16x16x32_bf16 v[6:9], v[90:93], v[66:69], v[6:9]
	s_waitcnt lgkmcnt(0)
	v_mfma_f32_16x16x32_bf16 v[22:25], v[94:97], v[66:69], v[22:25]
	v_add_u32_e32 v66, s2, v113
	v_or_b32_e32 v68, s26, v114
	v_ashrrev_i32_e32 v67, 31, v66
	v_mfma_f32_16x16x32_bf16 v[14:17], v[82:85], v[70:73], v[14:17]
	v_ashrrev_i32_e32 v69, 31, v68
	v_lshlrev_b64 v[68:69], 2, v[68:69]
	v_readlane_b32 s2, v254, 17
	v_mfma_f32_16x16x32_bf16 v[18:21], v[86:89], v[70:73], v[18:21]
	s_nop 0
	v_add_u32_e32 v103, s2, v103
	v_mfma_f32_16x16x32_bf16 v[26:29], v[90:93], v[70:73], v[26:29]
	v_mfma_f32_16x16x32_bf16 v[30:33], v[94:97], v[70:73], v[30:33]
	v_lshlrev_b64 v[70:71], 12, v[66:67]
	v_lshl_add_u64 v[70:71], s[8:9], 0, v[70:71]
	v_lshl_add_u64 v[70:71], v[70:71], 0, v[68:69]
	global_store_dwordx4 v[70:71], v[10:13], off
	global_store_dwordx4 v[70:71], v[2:5], off offset:64
	global_store_dwordx4 v[70:71], v[6:9], off offset:128
	global_store_dwordx4 v[70:71], v[22:25], off offset:192
	v_or_b32_e32 v2, 16, v66
	v_ashrrev_i32_e32 v3, 31, v2
	v_lshlrev_b64 v[2:3], 12, v[2:3]
	v_lshl_add_u64 v[2:3], s[8:9], 0, v[2:3]
	v_lshl_add_u64 v[2:3], v[2:3], 0, v[68:69]
	global_store_dwordx4 v[2:3], v[14:17], off
	global_store_dwordx4 v[2:3], v[18:21], off offset:64
	global_store_dwordx4 v[2:3], v[26:29], off offset:128
	global_store_dwordx4 v[2:3], v[30:33], off offset:192
	v_or_b32_e32 v2, 32, v66
	v_mfma_f32_16x16x32_bf16 v[46:49], v[82:85], v[74:77], v[46:49]
	v_ashrrev_i32_e32 v3, 31, v2
	v_lshlrev_b64 v[2:3], 12, v[2:3]
	v_lshl_add_u64 v[2:3], s[8:9], 0, v[2:3]
	v_mfma_f32_16x16x32_bf16 v[54:57], v[86:89], v[74:77], v[54:57]
	v_lshl_add_u64 v[2:3], v[2:3], 0, v[68:69]
	v_mfma_f32_16x16x32_bf16 v[58:61], v[90:93], v[74:77], v[58:61]
	v_mfma_f32_16x16x32_bf16 v[62:65], v[94:97], v[74:77], v[62:65]
	s_nop 0
	global_store_dwordx4 v[2:3], v[46:49], off
	s_nop 2
	global_store_dwordx4 v[2:3], v[54:57], off offset:64
	s_nop 0
	global_store_dwordx4 v[2:3], v[58:61], off offset:128
	global_store_dwordx4 v[2:3], v[62:65], off offset:192
	v_or_b32_e32 v2, 48, v66
	v_ashrrev_i32_e32 v3, 31, v2
	v_mfma_f32_16x16x32_bf16 v[50:53], v[82:85], v[78:81], v[50:53]
	v_lshlrev_b64 v[2:3], 12, v[2:3]
	v_lshl_add_u64 v[2:3], s[8:9], 0, v[2:3]
	v_lshl_add_u64 v[2:3], v[2:3], 0, v[68:69]
	v_mfma_f32_16x16x32_bf16 v[42:45], v[86:89], v[78:81], v[42:45]
	v_mfma_f32_16x16x32_bf16 v[38:41], v[90:93], v[78:81], v[38:41]
	v_mfma_f32_16x16x32_bf16 v[34:37], v[94:97], v[78:81], v[34:37]
	s_setprio 0
	s_nop 1
	global_store_dwordx4 v[2:3], v[50:53], off
	s_nop 2
	global_store_dwordx4 v[2:3], v[42:45], off offset:64
	global_store_dwordx4 v[2:3], v[38:41], off offset:128
	global_store_dwordx4 v[2:3], v[34:37], off offset:192
	s_cbranch_scc0 .LBB0_217
	s_movk_i32 s26, 0xff

.LBB0_242:
	s_waitcnt lgkmcnt(0)
	s_barrier
	s_waitcnt vmcnt(6)
	ds_write_b128 v102, v[70:73]
	s_waitcnt vmcnt(6)
	ds_write_b128 v102, v[66:69] offset:18432
	s_waitcnt vmcnt(5)
	ds_write_b128 v102, v[74:77] offset:4096
	s_waitcnt vmcnt(4)
	ds_write_b128 v102, v[78:81] offset:22528
	s_waitcnt vmcnt(3)
	ds_write_b128 v102, v[82:85] offset:8192
	s_waitcnt vmcnt(2)
	ds_write_b128 v102, v[86:89] offset:26624
	s_waitcnt vmcnt(1)
	ds_write_b128 v102, v[90:93] offset:12288
	s_waitcnt vmcnt(0)
	ds_write_b128 v102, v[94:97] offset:30720
	s_waitcnt lgkmcnt(0)
	s_barrier
	v_lshl_add_u64 v[212:213], v[108:109], 0, s[6:7]
	global_load_dwordx4 v[66:69], v[212:213], off offset:128
	s_add_u32 s100, s6, 0xa7c0000
	s_addc_u32 s101, s7, 0
	v_lshl_add_u64 v[214:215], v[110:111], 0, s[100:101]
	global_load_dwordx4 v[70:73], v[214:215], off offset:128
	s_add_u32 s100, s6, 0xa7d0000
	s_addc_u32 s101, s7, 0
	v_lshl_add_u64 v[216:217], v[110:111], 0, s[100:101]
	global_load_dwordx4 v[74:77], v[216:217], off offset:128
	s_add_u32 s100, s6, 0x10000
	s_addc_u32 s101, s7, 0
	v_lshl_add_u64 v[218:219], v[108:109], 0, s[100:101]
	global_load_dwordx4 v[78:81], v[218:219], off offset:128
	s_add_u32 s100, s6, 0xa7e0000
	s_addc_u32 s101, s7, 0
	v_lshl_add_u64 v[212:213], v[110:111], 0, s[100:101]
	global_load_dwordx4 v[82:85], v[212:213], off offset:128
	s_add_u32 s100, s6, 0x20000
	s_addc_u32 s101, s7, 0
	v_lshl_add_u64 v[214:215], v[108:109], 0, s[100:101]
	global_load_dwordx4 v[86:89], v[214:215], off offset:128
	s_add_u32 s100, s6, 0xa7f0000
	s_addc_u32 s101, s7, 0
	v_lshl_add_u64 v[216:217], v[110:111], 0, s[100:101]
	global_load_dwordx4 v[90:93], v[216:217], off offset:128
	s_add_u32 s100, s6, 0x30000
	s_addc_u32 s101, s7, 0
	v_lshl_add_u64 v[218:219], v[108:109], 0, s[100:101]
	global_load_dwordx4 v[94:97], v[218:219], off offset:128
	s_setprio 3
	ds_read_b128 v[146:149], v115 offset:18432
	ds_read_b128 v[150:153], v0
	ds_read_b128 v[154:157], v115 offset:20480
	ds_read_b128 v[158:161], v115 offset:22528
	ds_read_b128 v[162:165], v115 offset:24576
	s_waitcnt lgkmcnt(3)
	v_mfma_f32_16x16x32_bf16 v[14:17], v[146:149], v[150:153], v[14:17]
	ds_read_b128 v[208:211], v249 offset:22528
	s_waitcnt lgkmcnt(3)
	v_mfma_f32_16x16x32_bf16 v[10:13], v[154:157], v[150:153], v[10:13]
	s_waitcnt lgkmcnt(2)
	v_mfma_f32_16x16x32_bf16 v[2:5], v[158:161], v[150:153], v[2:5]
	s_waitcnt lgkmcnt(1)
	v_mfma_f32_16x16x32_bf16 v[6:9], v[162:165], v[150:153], v[6:9]
	ds_read_b128 v[150:153], v0 offset:2048
	s_waitcnt lgkmcnt(0)
	v_mfma_f32_16x16x32_bf16 v[26:29], v[146:149], v[150:153], v[26:29]
	v_mfma_f32_16x16x32_bf16 v[22:25], v[154:157], v[150:153], v[22:25]
	v_mfma_f32_16x16x32_bf16 v[18:21], v[158:161], v[150:153], v[18:21]
	v_mfma_f32_16x16x32_bf16 v[30:33], v[162:165], v[150:153], v[30:33]
	ds_read_b128 v[150:153], v0 offset:4096
	s_waitcnt lgkmcnt(0)
	v_mfma_f32_16x16x32_bf16 v[34:37], v[146:149], v[150:153], v[34:37]
	v_mfma_f32_16x16x32_bf16 v[42:45], v[154:157], v[150:153], v[42:45]
	v_mfma_f32_16x16x32_bf16 v[50:53], v[158:161], v[150:153], v[50:53]
	v_mfma_f32_16x16x32_bf16 v[58:61], v[162:165], v[150:153], v[58:61]
	ds_read_b128 v[150:153], v0 offset:6144
	s_waitcnt lgkmcnt(0)
	v_mfma_f32_16x16x32_bf16 v[54:57], v[154:157], v[150:153], v[54:57]
	ds_read_b128 v[154:157], v249 offset:18432
	v_mfma_f32_16x16x32_bf16 v[38:41], v[162:165], v[150:153], v[38:41]
	ds_read_b128 v[162:165], v249 offset:20480
	v_mfma_f32_16x16x32_bf16 v[62:65], v[146:149], v[150:153], v[62:65]
	ds_read_b128 v[146:149], v248
	v_mfma_f32_16x16x32_bf16 v[46:49], v[158:161], v[150:153], v[46:49]
	ds_read_b128 v[116:119], v249 offset:24576
	ds_read_b128 v[150:153], v248 offset:2048
	ds_read_b128 v[158:161], v248 offset:4096
	ds_read_b128 v[120:123], v248 offset:6144
	s_waitcnt lgkmcnt(4)
	v_mfma_f32_16x16x32_bf16 v[14:17], v[154:157], v[146:149], v[14:17]
	v_mfma_f32_16x16x32_bf16 v[10:13], v[162:165], v[146:149], v[10:13]
	v_mfma_f32_16x16x32_bf16 v[2:5], v[208:211], v[146:149], v[2:5]
	s_waitcnt lgkmcnt(3)
	v_mfma_f32_16x16x32_bf16 v[6:9], v[116:119], v[146:149], v[6:9]
	s_waitcnt lgkmcnt(2)
	v_mfma_f32_16x16x32_bf16 v[26:29], v[154:157], v[150:153], v[26:29]
	v_mfma_f32_16x16x32_bf16 v[22:25], v[162:165], v[150:153], v[22:25]
	v_mfma_f32_16x16x32_bf16 v[18:21], v[208:211], v[150:153], v[18:21]
	v_mfma_f32_16x16x32_bf16 v[30:33], v[116:119], v[150:153], v[30:33]
	s_waitcnt lgkmcnt(1)
	v_mfma_f32_16x16x32_bf16 v[34:37], v[154:157], v[158:161], v[34:37]
	v_mfma_f32_16x16x32_bf16 v[42:45], v[162:165], v[158:161], v[42:45]
	v_mfma_f32_16x16x32_bf16 v[50:53], v[208:211], v[158:161], v[50:53]
	v_mfma_f32_16x16x32_bf16 v[58:61], v[116:119], v[158:161], v[58:61]
	s_waitcnt lgkmcnt(0)
	v_mfma_f32_16x16x32_bf16 v[62:65], v[154:157], v[120:123], v[62:65]
	v_mfma_f32_16x16x32_bf16 v[54:57], v[162:165], v[120:123], v[54:57]
	v_mfma_f32_16x16x32_bf16 v[46:49], v[208:211], v[120:123], v[46:49]
	v_mfma_f32_16x16x32_bf16 v[38:41], v[116:119], v[120:123], v[38:41]
	s_setprio 0
	s_add_u32 s6, s6, 0x80
	s_addc_u32 s7, s7, 0
	s_cmpk_eq_i32 s6, 0x780
	s_cbranch_scc0 .LBB0_242
	s_barrier
	s_waitcnt vmcnt(6)
	ds_write_b128 v102, v[70:73]
	ds_write_b128 v102, v[66:69] offset:18432
	s_waitcnt vmcnt(5)
	ds_write_b128 v102, v[74:77] offset:4096
	s_waitcnt vmcnt(4)
	ds_write_b128 v102, v[78:81] offset:22528
	s_waitcnt vmcnt(3)
	ds_write_b128 v102, v[82:85] offset:8192
	s_waitcnt vmcnt(2)
	ds_write_b128 v102, v[86:89] offset:26624
	s_waitcnt vmcnt(1)
	ds_write_b128 v102, v[90:93] offset:12288
	s_waitcnt vmcnt(0)
	ds_write_b128 v102, v[94:97] offset:30720
	s_waitcnt lgkmcnt(0)
	s_barrier
	s_setprio 3
	ds_read_b128 v[66:69], v0
	ds_read_b128 v[70:73], v0 offset:2048
	ds_read_b128 v[74:77], v0 offset:4096
	ds_read_b128 v[78:81], v0 offset:6144
	ds_read_b128 v[82:85], v115 offset:18432
	ds_read_b128 v[86:89], v115 offset:20480
	ds_read_b128 v[90:93], v115 offset:22528
	ds_read_b128 v[94:97], v115 offset:24576
	s_waitcnt lgkmcnt(3)
	v_mfma_f32_16x16x32_bf16 v[14:17], v[82:85], v[66:69], v[14:17]
	s_add_i32 s2, s2, s66
	s_cmpk_gt_i32 s2, 0x3ff
	s_waitcnt lgkmcnt(2)
	v_mfma_f32_16x16x32_bf16 v[10:13], v[86:89], v[66:69], v[10:13]
	s_waitcnt lgkmcnt(1)
	v_mfma_f32_16x16x32_bf16 v[2:5], v[90:93], v[66:69], v[2:5]
	s_waitcnt lgkmcnt(0)
	v_mfma_f32_16x16x32_bf16 v[6:9], v[94:97], v[66:69], v[6:9]
	v_mfma_f32_16x16x32_bf16 v[26:29], v[82:85], v[70:73], v[26:29]
	v_mfma_f32_16x16x32_bf16 v[22:25], v[86:89], v[70:73], v[22:25]
	v_mfma_f32_16x16x32_bf16 v[18:21], v[90:93], v[70:73], v[18:21]
	v_mfma_f32_16x16x32_bf16 v[30:33], v[94:97], v[70:73], v[30:33]
	v_mfma_f32_16x16x32_bf16 v[66:69], v[82:85], v[74:77], v[34:37]
	v_mfma_f32_16x16x32_bf16 v[70:73], v[86:89], v[74:77], v[42:45]
	v_mfma_f32_16x16x32_bf16 v[50:53], v[90:93], v[74:77], v[50:53]
	v_mfma_f32_16x16x32_bf16 v[58:61], v[94:97], v[74:77], v[58:61]
	v_mfma_f32_16x16x32_bf16 v[62:65], v[82:85], v[78:81], v[62:65]
	v_mfma_f32_16x16x32_bf16 v[54:57], v[86:89], v[78:81], v[54:57]
	v_mfma_f32_16x16x32_bf16 v[74:77], v[90:93], v[78:81], v[46:49]
	v_mfma_f32_16x16x32_bf16 v[78:81], v[94:97], v[78:81], v[38:41]
	ds_read_b128 v[34:37], v248
	ds_read_b128 v[82:85], v248 offset:2048
	ds_read_b128 v[86:89], v248 offset:4096
	ds_read_b128 v[90:93], v248 offset:6144
	ds_read_b128 v[94:97], v249 offset:18432
	ds_read_b128 v[108:111], v249 offset:20480
	ds_read_b128 v[116:119], v249 offset:22528
	ds_read_b128 v[120:123], v249 offset:24576
	s_waitcnt lgkmcnt(2)
	v_mfma_f32_16x16x32_bf16 v[42:45], v[108:111], v[82:85], v[22:25]
	s_waitcnt lgkmcnt(1)
	v_mfma_f32_16x16x32_bf16 v[22:25], v[116:119], v[86:89], v[50:53]
	s_nop 2
	v_add_u32_e32 v50, s0, v113
	v_or_b32_e32 v52, s26, v114
	v_ashrrev_i32_e32 v51, 31, v50
	v_mfma_f32_16x16x32_bf16 v[130:133], v[108:111], v[34:37], v[10:13]
	v_ashrrev_i32_e32 v53, 31, v52
	v_lshlrev_b64 v[52:53], 2, v[52:53]
	v_readlane_b32 s0, v254, 17
	v_mfma_f32_16x16x32_bf16 v[10:13], v[108:111], v[90:93], v[54:57]
	s_nop 0
	v_add_u32_e32 v103, s0, v103
	s_nop 0
	v_lshlrev_b64 v[54:55], 12, v[50:51]
	v_lshl_add_u64 v[56:57], s[22:23], 0, v[54:55]
	v_mfma_f32_16x16x32_bf16 v[38:41], v[116:119], v[82:85], v[18:21]
	v_lshl_add_u64 v[54:55], s[8:9], 0, v[54:55]
	s_waitcnt lgkmcnt(0)
	v_mfma_f32_16x16x32_bf16 v[18:21], v[120:123], v[86:89], v[58:61]
	s_nop 2
	v_lshl_add_u64 v[58:59], v[56:57], 0, v[52:53]
	v_lshl_add_u64 v[60:61], v[54:55], 0, v[52:53]
	global_load_dwordx4 v[54:57], v[58:59], off
	v_mfma_f32_16x16x32_bf16 v[126:129], v[94:97], v[34:37], v[14:17]
	v_mfma_f32_16x16x32_bf16 v[134:137], v[116:119], v[34:37], v[2:5]
	v_mfma_f32_16x16x32_bf16 v[138:141], v[120:123], v[34:37], v[6:9]
	s_waitcnt vmcnt(0)
	s_nop 4
	v_pk_add_f32 v[54:55], v[126:127], v[54:55]
	v_pk_add_f32 v[56:57], v[128:129], v[56:57]
	global_store_dwordx4 v[60:61], v[54:57], off
	global_load_dwordx4 v[54:57], v[58:59], off offset:64
	v_mfma_f32_16x16x32_bf16 v[46:49], v[94:97], v[82:85], v[26:29]
	s_waitcnt vmcnt(0)
	v_pk_add_f32 v[54:55], v[130:131], v[54:55]
	v_pk_add_f32 v[56:57], v[132:133], v[56:57]
	global_store_dwordx4 v[60:61], v[54:57], off offset:64
	global_load_dwordx4 v[54:57], v[58:59], off offset:128
	v_mfma_f32_16x16x32_bf16 v[34:37], v[120:123], v[82:85], v[30:33]
	s_waitcnt vmcnt(0)
	v_pk_add_f32 v[54:55], v[134:135], v[54:55]
	v_pk_add_f32 v[56:57], v[136:137], v[56:57]
	global_store_dwordx4 v[60:61], v[54:57], off offset:128
	global_load_dwordx4 v[54:57], v[58:59], off offset:192
	v_mfma_f32_16x16x32_bf16 v[30:33], v[94:97], v[86:89], v[66:69]
	s_waitcnt vmcnt(0)
	v_pk_add_f32 v[54:55], v[138:139], v[54:55]
	v_pk_add_f32 v[56:57], v[140:141], v[56:57]
	global_store_dwordx4 v[60:61], v[54:57], off offset:192
	v_mfma_f32_16x16x32_bf16 v[26:29], v[108:111], v[86:89], v[70:73]
	s_nop 0
	v_or_b32_e32 v54, 16, v50
	v_ashrrev_i32_e32 v55, 31, v54
	v_lshlrev_b64 v[54:55], 12, v[54:55]
	v_lshl_add_u64 v[56:57], s[22:23], 0, v[54:55]
	v_lshl_add_u64 v[54:55], s[8:9], 0, v[54:55]
	v_lshl_add_u64 v[58:59], v[56:57], 0, v[52:53]
	v_lshl_add_u64 v[60:61], v[54:55], 0, v[52:53]
	global_load_dwordx4 v[54:57], v[58:59], off
	v_mfma_f32_16x16x32_bf16 v[14:17], v[94:97], v[90:93], v[62:65]
	s_waitcnt vmcnt(0)
	v_pk_add_f32 v[46:47], v[46:47], v[54:55]
	v_pk_add_f32 v[48:49], v[48:49], v[56:57]
	global_store_dwordx4 v[60:61], v[46:49], off
	global_load_dwordx4 v[46:49], v[58:59], off offset:64
	v_mfma_f32_16x16x32_bf16 v[6:9], v[116:119], v[90:93], v[74:77]
	s_waitcnt vmcnt(0)
	v_pk_add_f32 v[42:43], v[42:43], v[46:47]
	v_pk_add_f32 v[44:45], v[44:45], v[48:49]
	global_store_dwordx4 v[60:61], v[42:45], off offset:64
	global_load_dwordx4 v[42:45], v[58:59], off offset:128
	v_mfma_f32_16x16x32_bf16 v[2:5], v[120:123], v[90:93], v[78:81]
	s_setprio 0
	s_waitcnt vmcnt(0)
	v_pk_add_f32 v[38:39], v[38:39], v[42:43]
	v_pk_add_f32 v[40:41], v[40:41], v[44:45]
	global_store_dwordx4 v[60:61], v[38:41], off offset:128
	global_load_dwordx4 v[38:41], v[58:59], off offset:192
	s_waitcnt vmcnt(0)
	v_pk_add_f32 v[34:35], v[34:35], v[38:39]
	v_pk_add_f32 v[36:37], v[36:37], v[40:41]
	global_store_dwordx4 v[60:61], v[34:37], off offset:192
	s_nop 1
	v_or_b32_e32 v34, 32, v50
	v_ashrrev_i32_e32 v35, 31, v34
	v_lshlrev_b64 v[34:35], 12, v[34:35]
	v_lshl_add_u64 v[36:37], s[22:23], 0, v[34:35]
	v_lshl_add_u64 v[34:35], s[8:9], 0, v[34:35]
	v_lshl_add_u64 v[38:39], v[36:37], 0, v[52:53]
	v_lshl_add_u64 v[40:41], v[34:35], 0, v[52:53]
	global_load_dwordx4 v[34:37], v[38:39], off
	s_waitcnt vmcnt(0)
	v_pk_add_f32 v[30:31], v[30:31], v[34:35]
	v_pk_add_f32 v[32:33], v[32:33], v[36:37]
	global_store_dwordx4 v[40:41], v[30:33], off
	global_load_dwordx4 v[30:33], v[38:39], off offset:64
	s_waitcnt vmcnt(0)
	v_pk_add_f32 v[26:27], v[26:27], v[30:31]
	v_pk_add_f32 v[28:29], v[28:29], v[32:33]
	global_store_dwordx4 v[40:41], v[26:29], off offset:64
	global_load_dwordx4 v[26:29], v[38:39], off offset:128
	s_waitcnt vmcnt(0)
	v_pk_add_f32 v[22:23], v[22:23], v[26:27]
	v_pk_add_f32 v[24:25], v[24:25], v[28:29]
	global_store_dwordx4 v[40:41], v[22:25], off offset:128
	global_load_dwordx4 v[22:25], v[38:39], off offset:192
	s_waitcnt vmcnt(0)
	v_pk_add_f32 v[18:19], v[18:19], v[22:23]
	v_pk_add_f32 v[20:21], v[20:21], v[24:25]
	global_store_dwordx4 v[40:41], v[18:21], off offset:192
	s_nop 1
	v_or_b32_e32 v18, 48, v50
	v_ashrrev_i32_e32 v19, 31, v18
	v_lshlrev_b64 v[18:19], 12, v[18:19]
	v_lshl_add_u64 v[20:21], s[22:23], 0, v[18:19]
	v_lshl_add_u64 v[24:25], v[20:21], 0, v[52:53]
	global_load_dwordx4 v[20:23], v[24:25], off
	v_lshl_add_u64 v[18:19], s[8:9], 0, v[18:19]
	v_lshl_add_u64 v[18:19], v[18:19], 0, v[52:53]
	s_waitcnt vmcnt(0)
	v_pk_add_f32 v[14:15], v[14:15], v[20:21]
	v_pk_add_f32 v[16:17], v[16:17], v[22:23]
	global_store_dwordx4 v[18:19], v[14:17], off
	global_load_dwordx4 v[14:17], v[24:25], off offset:64
	s_waitcnt vmcnt(0)
	v_pk_add_f32 v[10:11], v[10:11], v[14:15]
	v_pk_add_f32 v[12:13], v[12:13], v[16:17]
	global_store_dwordx4 v[18:19], v[10:13], off offset:64
	global_load_dwordx4 v[10:13], v[24:25], off offset:128
	s_waitcnt vmcnt(0)
	v_pk_add_f32 v[6:7], v[6:7], v[10:11]
	v_pk_add_f32 v[8:9], v[8:9], v[12:13]
	global_store_dwordx4 v[18:19], v[6:9], off offset:128
	global_load_dwordx4 v[6:9], v[24:25], off offset:192
	s_waitcnt vmcnt(0)
	v_pk_add_f32 v[2:3], v[2:3], v[6:7]
	v_pk_add_f32 v[4:5], v[4:5], v[8:9]
	global_store_dwordx4 v[18:19], v[2:5], off offset:192
	s_cbranch_scc0 .LBB0_241
	s_movk_i32 s26, 0xff

.LBB0_312:
	s_setprio 0
	s_mul_i32 s78, s98, 0x4800
	v_or_b32_e32 v0, s78, v205
	v_add_u32_e32 v2, v0, v207
	ds_read_b128 v[60:63], v2
	ds_read_b128 v[64:67], v2 offset:64
	v_add_u32_e32 v0, v0, v222
	ds_read_b128 v[72:75], v0
	ds_read_b128 v[92:95], v0 offset:64
	ds_read_b128 v[100:103], v2 offset:4608
	ds_read_b128 v[104:107], v2 offset:4672
	ds_read_b128 v[112:115], v2 offset:6912
	ds_read_b128 v[156:159], v2 offset:6976
	s_waitcnt vmcnt(3) lgkmcnt(5)
	s_setprio 3
	v_mfma_f32_16x16x32_bf16 v[96:99], v[72:75], v[20:23], 0
	s_cmp_eq_u32 s74, s85
	s_cselect_b64 s[6:7], -1, 0
	s_or_b64 s[6:7], s[18:19], s[6:7]
	v_mfma_f32_16x16x32_bf16 v[68:71], v[60:63], v[20:23], 0
	s_lshl_b32 s0, s74, 6
	s_cmp_lt_i32 s0, s94
	s_cselect_b64 s[8:9], -1, 0
	s_waitcnt lgkmcnt(3)
	v_mfma_f32_16x16x32_bf16 v[108:111], v[100:103], v[20:23], 0
	s_and_b64 s[8:9], s[68:69], s[8:9]
	s_or_b64 s[64:65], s[6:7], s[8:9]
	v_or_b32_e32 v245, s0, v206
	s_waitcnt lgkmcnt(1)
	v_mfma_f32_16x16x32_bf16 v[160:163], v[112:115], v[20:23], 0
	s_and_b64 vcc, exec, s[64:65]
	s_waitcnt vmcnt(1)
	v_mfma_f32_16x16x32_bf16 v[60:63], v[60:63], v[28:31], 0
	v_mfma_f32_16x16x32_bf16 v[164:167], v[72:75], v[28:31], 0
	v_mfma_f32_16x16x32_bf16 v[100:103], v[100:103], v[28:31], 0
	v_mfma_f32_16x16x32_bf16 v[196:199], v[112:115], v[28:31], 0
	v_mfma_f32_16x16x32_bf16 v[120:123], v[64:67], v[24:27], v[68:71]
	v_mfma_f32_16x16x32_bf16 v[116:119], v[92:95], v[24:27], v[96:99]
	v_mfma_f32_16x16x32_bf16 v[112:115], v[104:107], v[24:27], v[108:111]
	s_waitcnt lgkmcnt(0)
	v_mfma_f32_16x16x32_bf16 v[108:111], v[156:159], v[24:27], v[160:163]
	s_waitcnt vmcnt(0)
	v_mfma_f32_16x16x32_bf16 v[72:75], v[64:67], v[32:35], v[60:63]
	v_mfma_f32_16x16x32_bf16 v[68:71], v[92:95], v[32:35], v[164:167]
	v_mfma_f32_16x16x32_bf16 v[64:67], v[104:107], v[32:35], v[100:103]
	v_mfma_f32_16x16x32_bf16 v[60:63], v[156:159], v[32:35], v[196:199]
	s_setprio 0
	s_cbranch_vccz .LBB0_474
	v_add_u32_e32 v92, -1, v237
	s_orn2_b64 s[6:7], s[14:15], s[12:13]
	v_add_u32_e32 v93, 1, v239
	v_mov_b32_e32 v94, 0x80000001
	v_cndmask_b32_e64 v92, v92, v236, s[12:13]
	v_cndmask_b32_e64 v93, v93, v94, s[6:7]
	v_sub_u32_e32 v92, v92, v93
	v_sub_u32_e32 v93, v245, v93
	v_add_u32_e32 v94, 0, v93
	v_cmp_gt_u32_e32 vcc, v94, v92
	v_add_u32_e32 v95, 1, v93
	v_cmp_gt_u32_e64 s[8:9], v95, v92
	v_add_u32_e32 v0, 2, v93
	v_cmp_gt_u32_e64 s[10:11], v0, v92
	v_cndmask_b32_e32 v120, v120, v193, vcc
	v_add_u32_e32 v94, 3, v93
	v_cmp_gt_u32_e32 vcc, v94, v92
	v_cndmask_b32_e64 v121, v121, v193, s[8:9]
	v_add_u32_e32 v95, 16, v93
	v_cmp_gt_u32_e64 s[8:9], v95, v92
	v_cndmask_b32_e64 v122, v122, v193, s[10:11]
	v_add_u32_e32 v0, 17, v93
	v_cmp_gt_u32_e64 s[10:11], v0, v92
	v_cndmask_b32_e32 v123, v123, v193, vcc
	v_add_u32_e32 v94, 18, v93
	v_cmp_gt_u32_e32 vcc, v94, v92
	v_cndmask_b32_e64 v116, v116, v193, s[8:9]
	v_add_u32_e32 v95, 19, v93
	v_cmp_gt_u32_e64 s[8:9], v95, v92
	v_cndmask_b32_e64 v117, v117, v193, s[10:11]
	v_add_u32_e32 v0, 32, v93
	v_cmp_gt_u32_e64 s[10:11], v0, v92
	v_cndmask_b32_e32 v118, v118, v193, vcc
	v_add_u32_e32 v94, 33, v93
	v_cmp_gt_u32_e32 vcc, v94, v92
	v_cndmask_b32_e64 v119, v119, v193, s[8:9]
	v_add_u32_e32 v95, 34, v93
	v_cmp_gt_u32_e64 s[8:9], v95, v92
	v_cndmask_b32_e64 v112, v112, v193, s[10:11]
	v_add_u32_e32 v0, 35, v93
	v_cmp_gt_u32_e64 s[10:11], v0, v92
	v_cndmask_b32_e32 v113, v113, v193, vcc
	v_add_u32_e32 v94, 48, v93
	v_cmp_gt_u32_e32 vcc, v94, v92
	v_cndmask_b32_e64 v114, v114, v193, s[8:9]
	v_add_u32_e32 v95, 49, v93
	v_cmp_gt_u32_e64 s[8:9], v95, v92
	v_cndmask_b32_e64 v115, v115, v193, s[10:11]
	v_add_u32_e32 v0, 50, v93
	v_cmp_gt_u32_e64 s[10:11], v0, v92
	v_cndmask_b32_e32 v108, v108, v193, vcc
	v_add_u32_e32 v94, 51, v93
	v_cmp_gt_u32_e32 vcc, v94, v92
	v_cndmask_b32_e64 v109, v109, v193, s[8:9]
	v_cndmask_b32_e64 v110, v110, v193, s[10:11]
	v_cndmask_b32_e32 v111, v111, v193, vcc

.LBB0_486:
	v_add3_u32 v0, s78, v207, v235
	v_cvt_pk_bf16_f32 v44, v2, v3
	v_add_u32_e32 v2, 0x2000, v0
	ds_read2_b64 v[52:55], v2 offset0:128 offset1:132
	v_add_u32_e32 v3, 0x2800, v0
	ds_read2_b64 v[68:71], v3 offset0:160 offset1:164
	v_cvt_pk_bf16_f32 v45, v156, v157
	v_cvt_pk_bf16_f32 v46, v158, v159
	v_cvt_pk_bf16_f32 v47, v160, v161
	v_cvt_pk_bf16_f32 v48, v84, v85
	s_waitcnt lgkmcnt(0)
	v_mov_b32_e32 v72, v68
	v_mov_b32_e32 v73, v69
	s_setprio 3
	v_mfma_f32_16x16x32_bf16 v[56:59], v[52:55], v[44:47], v[104:107]
	v_cvt_pk_bf16_f32 v49, v86, v87
	v_cvt_pk_bf16_f32 v50, v88, v89
	v_cvt_pk_bf16_f32 v51, v90, v91
	v_add_u32_e32 v104, 0x3000, v0
	v_add_u32_e32 v0, 0x3800, v0
	ds_read2_b64 v[84:87], v0 offset0:232 offset1:236
	v_mfma_f32_16x16x32_bf16 v[52:55], v[52:55], v[48:51], v[80:83]
	v_cvt_pk_bf16_f32 v60, v162, v163
	v_cvt_pk_bf16_f32 v61, v164, v165
	v_cvt_pk_bf16_f32 v62, v166, v167
	v_mfma_f32_16x16x32_bf16 v[80:83], v[70:73], v[44:47], v[92:95]
	s_waitcnt lgkmcnt(0)
	v_mov_b32_e32 v88, v84
	v_mov_b32_e32 v89, v85
	v_cvt_pk_bf16_f32 v63, v168, v169
	v_mfma_f32_16x16x32_bf16 v[68:71], v[70:73], v[48:51], v[76:79]
	ds_read2_b64 v[72:75], v104 offset0:200 offset1:204
	v_cvt_pk_bf16_f32 v64, v116, v117
	v_cvt_pk_bf16_f32 v65, v118, v119
	s_waitcnt lgkmcnt(0)
	v_mfma_f32_16x16x32_bf16 v[76:79], v[72:75], v[44:47], v[100:103]
	v_cvt_pk_bf16_f32 v66, v120, v121
	v_cvt_pk_bf16_f32 v67, v122, v123
	v_mfma_f32_16x16x32_bf16 v[72:75], v[72:75], v[48:51], v[112:115]
	v_mfma_f32_16x16x32_bf16 v[92:95], v[86:89], v[48:51], v[108:111]
	ds_read2_b64 v[48:51], v2 offset0:136 offset1:140
	v_mfma_f32_16x16x32_bf16 v[44:47], v[86:89], v[44:47], v[96:99]
	s_waitcnt lgkmcnt(0)
	v_mfma_f32_16x16x32_bf16 v[88:91], v[48:51], v[60:63], v[56:59]
	v_mfma_f32_16x16x32_bf16 v[56:59], v[48:51], v[64:67], v[52:55]
	ds_read2_b64 v[48:51], v3 offset0:168 offset1:172
	s_waitcnt lgkmcnt(0)
	s_nop 0
	v_mov_b32_e32 v52, v48
	v_mov_b32_e32 v53, v49
	s_nop 1
	v_mfma_f32_16x16x32_bf16 v[84:87], v[50:53], v[60:63], v[80:83]
	v_mfma_f32_16x16x32_bf16 v[52:55], v[50:53], v[64:67], v[68:71]
	ds_read2_b64 v[48:51], v104 offset0:192 offset1:196
	s_nop 1
	ds_read2_b64 v[68:71], v0 offset0:224 offset1:228
	s_waitcnt lgkmcnt(1)
	v_mfma_f32_16x16x32_bf16 v[80:83], v[48:51], v[60:63], v[76:79]
	v_mfma_f32_16x16x32_bf16 v[48:51], v[48:51], v[64:67], v[72:75]
	s_waitcnt lgkmcnt(0)
	s_nop 1
	v_mov_b32_e32 v72, v68
	v_mov_b32_e32 v73, v69
	s_nop 1
	v_mfma_f32_16x16x32_bf16 v[76:79], v[70:73], v[60:63], v[44:47]
	v_mfma_f32_16x16x32_bf16 v[44:47], v[70:73], v[64:67], v[92:95]
	s_setprio 0
	s_branch .LBB0_669

.LBB0_748:
	s_setprio 0
	s_lshr_b32 s13, s6, 2
	s_and_b32 s12, s6, 3
	s_cmp_eq_u32 s13, s38
	s_cselect_b64 s[10:11], -1, 0
	s_cmp_lg_u32 s13, s38
	s_cselect_b64 s[6:7], -1, 0
	v_cmp_le_i32_e32 vcc, s12, v117
	s_or_b64 s[14:15], s[6:7], vcc
	v_mov_b32_e32 v66, v126
	v_mov_b32_e32 v67, v127
	s_and_saveexec_b64 s[6:7], s[14:15]
	s_cbranch_execz .LBB0_761
	s_lshl_b32 s13, 1, s13
	v_and_b32_e32 v66, s13, v120
	v_cmp_ne_u32_e32 vcc, 0, v66
	v_and_b32_e32 v66, s13, v121
	s_or_b64 s[96:97], s[10:11], vcc
	v_cmp_ne_u32_e64 s[98:99], 0, v66
	s_or_b64 s[14:15], s[96:97], s[98:99]
	v_cndmask_b32_e64 v66, 0, 1, s[14:15]
	v_cmp_ne_u32_e32 vcc, 0, v66
	s_cbranch_vccz .LBB0_759
	s_mulk_i32 s9, 0x4800
	v_or_b32_e32 v66, s9, v132
	v_add_u32_e32 v147, v66, v133
	ds_read_b128 v[66:69], v147
	ds_read_b128 v[82:85], v147 offset:64
	ds_read_b128 v[74:77], v147 offset:2304
	ds_read_b128 v[86:89], v147 offset:2368
	ds_read_b128 v[90:93], v147 offset:4608
	ds_read_b128 v[148:151], v147 offset:4672
	ds_read_b128 v[152:155], v147 offset:6912
	ds_read_b128 v[156:159], v147 offset:6976
	s_waitcnt vmcnt(3) lgkmcnt(7)
	s_setprio 3
	v_mfma_f32_16x16x32_bf16 v[70:73], v[66:69], v[2:5], 0
	v_cmp_eq_u32_e32 vcc, s12, v117
	s_and_b64 s[12:13], s[10:11], vcc
	s_waitcnt lgkmcnt(5)
	v_mfma_f32_16x16x32_bf16 v[78:81], v[74:77], v[2:5], 0
	s_waitcnt lgkmcnt(3)
	v_mfma_f32_16x16x32_bf16 v[94:97], v[90:93], v[2:5], 0
	s_waitcnt lgkmcnt(1)
	v_mfma_f32_16x16x32_bf16 v[160:163], v[152:155], v[2:5], 0
	s_waitcnt vmcnt(1)
	v_mfma_f32_16x16x32_bf16 v[164:167], v[66:69], v[14:17], 0
	v_mfma_f32_16x16x32_bf16 v[204:207], v[74:77], v[14:17], 0
	v_mfma_f32_16x16x32_bf16 v[208:211], v[90:93], v[14:17], 0
	v_mfma_f32_16x16x32_bf16 v[152:155], v[152:155], v[14:17], 0
	v_mfma_f32_16x16x32_bf16 v[74:77], v[82:85], v[6:9], v[70:73]
	v_mfma_f32_16x16x32_bf16 v[70:73], v[86:89], v[6:9], v[78:81]
	v_mfma_f32_16x16x32_bf16 v[66:69], v[148:151], v[6:9], v[94:97]
	s_waitcnt lgkmcnt(0)
	v_mfma_f32_16x16x32_bf16 v[78:81], v[156:159], v[6:9], v[160:163]
	s_waitcnt vmcnt(0)
	v_mfma_f32_16x16x32_bf16 v[94:97], v[82:85], v[18:21], v[164:167]
	v_mfma_f32_16x16x32_bf16 v[90:93], v[86:89], v[18:21], v[204:207]
	v_mfma_f32_16x16x32_bf16 v[86:89], v[148:151], v[18:21], v[208:211]
	v_mfma_f32_16x16x32_bf16 v[82:85], v[156:159], v[18:21], v[152:155]
	s_setprio 0
	s_and_saveexec_b64 s[14:15], s[12:13]
	s_cbranch_execz .LBB0_752
	s_nop 0
	v_mov_b32_e32 v78, s43
	v_cndmask_b32_e64 v78, v74, v78, s[50:51]
	v_cndmask_b32_e64 v74, v78, v74, s[52:53]
	v_mov_b32_e32 v78, s43
	v_cndmask_b32_e64 v70, v70, v78, s[58:59]
	v_cndmask_b32_e64 v66, v66, v78, s[66:67]
	v_mov_b32_e32 v78, 0xf149f2ca
	v_cndmask_b32_e64 v75, v193, v75, s[52:53]
	v_cndmask_b32_e64 v76, v76, v193, s[54:55]
	v_cndmask_b32_e64 v77, v77, v193, s[56:57]
	v_cndmask_b32_e64 v71, v71, v193, s[60:61]
	v_cndmask_b32_e64 v72, v72, v193, s[62:63]
	v_cndmask_b32_e64 v73, v73, v193, s[64:65]
	v_cndmask_b32_e64 v67, v67, v193, s[68:69]
	v_cndmask_b32_e64 v68, v68, v193, s[70:71]
	v_cndmask_b32_e64 v69, v69, v193, s[72:73]
	v_mov_b32_e32 v79, v78
	v_mov_b32_e32 v80, v78
	v_mov_b32_e32 v81, v78

.LBB0_758:
	v_cndmask_b32_e64 v149, v193, -v148, s[10:11]
	v_fmamk_f32 v94, v94, 0x3e38aa3b, v149
	v_exp_f32_e32 v94, v94
	v_fmamk_f32 v95, v95, 0x3e38aa3b, v149
	v_exp_f32_e32 v95, v95
	v_fmamk_f32 v96, v96, 0x3e38aa3b, v149
	v_exp_f32_e32 v96, v96
	v_fmamk_f32 v97, v97, 0x3e38aa3b, v149
	v_exp_f32_e32 v97, v97
	v_fmamk_f32 v90, v90, 0x3e38aa3b, v149
	v_add_f32_e32 v150, 0, v94
	v_exp_f32_e32 v90, v90
	v_fmamk_f32 v91, v91, 0x3e38aa3b, v149
	v_add_f32_e32 v150, v95, v150
	v_exp_f32_e32 v91, v91
	v_fmamk_f32 v92, v92, 0x3e38aa3b, v149
	v_add_f32_e32 v150, v96, v150
	v_exp_f32_e32 v92, v92
	v_fmamk_f32 v93, v93, 0x3e38aa3b, v149
	v_add_f32_e32 v150, v97, v150
	v_exp_f32_e32 v93, v93
	v_fmamk_f32 v86, v86, 0x3e38aa3b, v149
	v_add_f32_e32 v150, v90, v150
	v_exp_f32_e32 v86, v86
	v_fmamk_f32 v87, v87, 0x3e38aa3b, v149
	v_add_f32_e32 v150, v91, v150
	v_exp_f32_e32 v87, v87
	v_fmamk_f32 v88, v88, 0x3e38aa3b, v149
	v_add_f32_e32 v150, v92, v150
	v_exp_f32_e32 v88, v88
	v_fmamk_f32 v89, v89, 0x3e38aa3b, v149
	v_add_f32_e32 v150, v93, v150
	v_exp_f32_e32 v89, v89
	v_fmamk_f32 v82, v82, 0x3e38aa3b, v149
	v_add_f32_e32 v150, v86, v150
	v_exp_f32_e32 v151, v82
	v_add_f32_e32 v150, v87, v150
	v_add_f32_e32 v150, v88, v150
	v_add_f32_e32 v150, v89, v150
	v_fmamk_f32 v83, v83, 0x3e38aa3b, v149
	v_add_f32_e32 v82, v151, v150
	v_exp_f32_e32 v150, v83
	v_fmamk_f32 v83, v84, 0x3e38aa3b, v149
	v_exp_f32_e32 v84, v83
	v_fmac_f32_e32 v149, 0x3e38aa3b, v85
	v_exp_f32_e32 v85, v149
	v_cndmask_b32_e64 v83, v193, -v147, s[96:97]
	v_add_f32_e32 v82, v150, v82
	v_fmamk_f32 v66, v66, 0x3e38aa3b, v83
	v_add_f32_e32 v82, v84, v82
	v_exp_f32_e32 v153, v66
	v_fmamk_f32 v66, v67, 0x3e38aa3b, v83
	v_add_f32_e32 v82, v85, v82
	v_fmamk_f32 v74, v74, 0x3e38aa3b, v83
	v_exp_f32_e32 v154, v66
	v_fmamk_f32 v66, v68, 0x3e38aa3b, v83
	v_fmac_f32_e32 v82, v126, v130
	v_exp_f32_e32 v126, v74
	v_fmamk_f32 v74, v75, 0x3e38aa3b, v83
	v_exp_f32_e32 v155, v66
	v_fmamk_f32 v66, v69, 0x3e38aa3b, v83
	v_exp_f32_e32 v130, v74
	v_fmamk_f32 v74, v76, 0x3e38aa3b, v83
	v_exp_f32_e32 v156, v66
	v_fmamk_f32 v66, v78, 0x3e38aa3b, v83
	v_exp_f32_e32 v149, v74
	v_fmamk_f32 v74, v77, 0x3e38aa3b, v83
	v_exp_f32_e32 v78, v66
	v_fmamk_f32 v66, v79, 0x3e38aa3b, v83
	v_exp_f32_e32 v152, v74
	v_fmamk_f32 v70, v70, 0x3e38aa3b, v83
	v_fmamk_f32 v71, v71, 0x3e38aa3b, v83
	v_fmamk_f32 v72, v72, 0x3e38aa3b, v83
	v_fmamk_f32 v73, v73, 0x3e38aa3b, v83
	v_exp_f32_e32 v79, v66
	v_fmamk_f32 v66, v80, 0x3e38aa3b, v83
	v_fmac_f32_e32 v83, 0x3e38aa3b, v81
	v_exp_f32_e32 v70, v70
	v_exp_f32_e32 v71, v71
	v_exp_f32_e32 v81, v83
	v_add_f32_e32 v83, 0, v126
	v_add_f32_e32 v83, v130, v83
	v_exp_f32_e32 v72, v72
	v_add_f32_e32 v83, v149, v83
	v_exp_f32_e32 v73, v73
	v_add_f32_e32 v83, v152, v83
	v_cvt_pk_bf16_f32 v76, v70, v71
	v_add_f32_e32 v70, v70, v83
	v_add_f32_e32 v70, v71, v70
	v_add_f32_e32 v70, v72, v70
	v_add_f32_e32 v70, v73, v70
	v_add_f32_e32 v70, v153, v70
	v_add_f32_e32 v70, v154, v70
	v_exp_f32_e32 v80, v66
	v_add_f32_e32 v70, v155, v70
	v_add_f32_e32 v70, v156, v70
	v_add_f32_e32 v70, v78, v70
	v_add_f32_e32 v70, v79, v70
	v_cvt_pk_bf16_f32 v69, v80, v81
	v_add_f32_e32 v70, v80, v70
	v_cvt_pk_bf16_f32 v80, v90, v91
	v_add3_u32 v90, s9, v133, v143
	v_add_u32_e32 v91, 0x2000, v90
	v_cvt_pk_bf16_f32 v77, v72, v73
	v_add_f32_e32 v83, v81, v70
	v_cvt_pk_bf16_f32 v70, v86, v87
	v_cvt_pk_bf16_f32 v73, v84, v85
	ds_read2_b64 v[84:87], v91 offset0:128 offset1:132
	v_cvt_pk_bf16_f32 v74, v126, v130
	v_cvt_pk_bf16_f32 v75, v149, v152
	v_cvt_pk_bf16_f32 v68, v78, v79
	v_cvt_pk_bf16_f32 v78, v94, v95
	v_cvt_pk_bf16_f32 v79, v96, v97
	v_cvt_pk_bf16_f32 v81, v92, v93
	v_add_u32_e32 v92, 0x2800, v90
	s_waitcnt lgkmcnt(0)
	s_setprio 3
	v_mfma_f32_16x16x32_bf16 v[62:65], v[84:87], v[74:77], v[62:65]
	v_cvt_pk_bf16_f32 v71, v88, v89
	v_add_u32_e32 v93, 0x3000, v90
	v_add_u32_e32 v90, 0x3800, v90
	v_mfma_f32_16x16x32_bf16 v[46:49], v[84:87], v[78:81], v[46:49]
	ds_read2_b64 v[84:87], v92 offset0:160 offset1:164
	v_cvt_pk_bf16_f32 v66, v153, v154
	v_cvt_pk_bf16_f32 v67, v155, v156
	v_cvt_pk_bf16_f32 v72, v151, v150
	v_fmac_f32_e32 v83, v127, v128
	s_waitcnt lgkmcnt(0)
	v_mov_b32_e32 v88, v84
	v_mov_b32_e32 v89, v85
	v_mov_b32_e32 v127, v83
	v_mov_b32_e32 v126, v82
	v_mfma_f32_16x16x32_bf16 v[50:53], v[86:89], v[74:77], v[50:53]
	v_mov_b32_e32 v130, v148
	v_mov_b32_e32 v128, v147
	v_mfma_f32_16x16x32_bf16 v[42:45], v[86:89], v[78:81], v[42:45]
	ds_read2_b64 v[84:87], v93 offset0:200 offset1:204
	s_waitcnt lgkmcnt(0)
	v_mfma_f32_16x16x32_bf16 v[58:61], v[84:87], v[74:77], v[58:61]
	v_mfma_f32_16x16x32_bf16 v[38:41], v[84:87], v[78:81], v[38:41]
	ds_read2_b64 v[84:87], v90 offset0:232 offset1:236
	s_waitcnt lgkmcnt(0)
	v_mov_b32_e32 v88, v84
	v_mov_b32_e32 v89, v85
	s_nop 1
	v_mfma_f32_16x16x32_bf16 v[54:57], v[86:89], v[74:77], v[54:57]
	ds_read2_b64 v[74:77], v91 offset0:136 offset1:140
	s_waitcnt lgkmcnt(0)
	v_mfma_f32_16x16x32_bf16 v[62:65], v[74:77], v[66:69], v[62:65]
	v_mfma_f32_16x16x32_bf16 v[46:49], v[74:77], v[70:73], v[46:49]
	ds_read2_b64 v[74:77], v92 offset0:168 offset1:172
	v_mfma_f32_16x16x32_bf16 v[34:37], v[86:89], v[78:81], v[34:37]
	s_waitcnt lgkmcnt(0)
	v_mov_b32_e32 v78, v74
	v_mov_b32_e32 v79, v75
	s_nop 1
	v_mfma_f32_16x16x32_bf16 v[50:53], v[76:79], v[66:69], v[50:53]
	v_mfma_f32_16x16x32_bf16 v[42:45], v[76:79], v[70:73], v[42:45]
	ds_read2_b64 v[74:77], v93 offset0:192 offset1:196
	s_waitcnt lgkmcnt(0)
	v_mfma_f32_16x16x32_bf16 v[58:61], v[74:77], v[66:69], v[58:61]
	v_mfma_f32_16x16x32_bf16 v[38:41], v[74:77], v[70:73], v[38:41]
	ds_read2_b64 v[74:77], v90 offset0:224 offset1:228
	s_waitcnt lgkmcnt(0)
	v_mov_b32_e32 v78, v74
	v_mov_b32_e32 v79, v75
	s_nop 1
	v_mfma_f32_16x16x32_bf16 v[54:57], v[76:79], v[66:69], v[54:57]
	v_mfma_f32_16x16x32_bf16 v[34:37], v[76:79], v[70:73], v[34:37]
	s_setprio 0
	s_branch .LBB0_760

.LBB0_776:
	s_setprio 0
	v_cmp_le_i32_e32 vcc, s35, v101
	s_xor_b64 s[6:7], s[38:39], -1
	s_and_b64 s[10:11], vcc, s[6:7]
	s_and_saveexec_b64 s[6:7], s[10:11]
	s_cbranch_execz .LBB0_778
	s_mul_i32 s10, s26, 0x4800
	v_add_u32_e32 v169, s10, v154
	v_add_u32_e32 v0, v169, v153
	ds_read_b128 v[66:69], v0
	ds_read_b128 v[74:77], v0 offset:64
	ds_read_b128 v[78:81], v0 offset:2304
	ds_read_b128 v[82:85], v0 offset:2368
	ds_read_b128 v[90:93], v0 offset:4608
	ds_read_b128 v[108:111], v0 offset:4672
	ds_read_b128 v[116:119], v0 offset:6912
	ds_read_b128 v[120:123], v0 offset:6976
	s_waitcnt vmcnt(3) lgkmcnt(7)
	s_setprio 3
	v_mfma_f32_16x16x32_bf16 v[70:73], v[66:69], v[2:5], 0
	v_cmp_lt_i32_e32 vcc, v184, v182
	s_mov_b32 s30, 0x3f317218
	v_mov_b32_e32 v214, v1
	s_waitcnt vmcnt(2) lgkmcnt(6)
	v_mfma_f32_16x16x32_bf16 v[130:133], v[74:77], v[6:9], v[70:73]
	v_cndmask_b32_e32 v0, v180, v184, vcc
	v_lshlrev_b32_e32 v204, 2, v0
	v_cmp_lt_i32_e32 vcc, v183, v182
	s_waitcnt lgkmcnt(1)
	v_mfma_f32_16x16x32_bf16 v[126:129], v[116:119], v[2:5], 0
	v_mov_b32_e32 v216, v1
	s_nop 1
	v_mul_f32_e32 v70, 0x3e000000, v130
	v_mul_f32_e64 v71, |v70|, s41
	v_exp_f32_e32 v71, v71
	v_max_f32_e32 v70, 0, v70
	v_cndmask_b32_e32 v72, v180, v183, vcc
	v_mfma_f32_16x16x32_bf16 v[112:115], v[90:93], v[2:5], 0
	v_add_f32_e32 v0, 1.0, v71
	v_log_f32_e32 v0, v0
	v_lshlrev_b32_e32 v203, 2, v72
	s_waitcnt vmcnt(1)
	v_mfma_f32_16x16x32_bf16 v[134:137], v[90:93], v[14:17], 0
	v_cmp_ne_u32_e32 vcc, 0, v168
	v_fmac_f32_e32 v70, 0x3f317218, v0
	v_mul_f32_e32 v0, 0x3e000000, v131
	v_fma_f32 v145, v130, s4, -v70
	v_add_f32_e32 v212, 0, v70
	v_mul_f32_e64 v90, |v0|, s41
	s_waitcnt lgkmcnt(0)
	v_mfma_f32_16x16x32_bf16 v[70:73], v[120:123], v[6:9], v[126:129]
	v_max_f32_e32 v0, 0, v0
	s_or_b64 s[10:11], s[48:49], vcc
	s_or_b64 s[94:95], s[56:57], vcc
	v_mfma_f32_16x16x32_bf16 v[86:89], v[78:81], v[2:5], 0
	v_exp_f32_e32 v126, v90
	s_nop 2
	v_mul_f32_e32 v127, 0x3e000000, v70
	s_or_b64 s[16:17], s[64:65], vcc
	v_mfma_f32_16x16x32_bf16 v[78:81], v[78:81], v[14:17], 0
	v_add_f32_e32 v126, 1.0, v126
	s_or_b64 s[14:15], s[54:55], vcc
	s_or_b64 s[18:19], s[68:69], vcc
	v_mfma_f32_16x16x32_bf16 v[90:93], v[82:85], v[6:9], v[86:89]
	s_or_b64 s[96:97], s[58:59], vcc
	v_cndmask_b32_e64 v226, v193, v145, s[94:95]
	s_or_b64 s[98:99], s[62:63], vcc
	v_mul_f32_e64 v86, |v127|, s41
	v_exp_f32_e32 v128, v86
	v_mfma_f32_16x16x32_bf16 v[86:89], v[108:111], v[6:9], v[112:115]
	v_mov_b32_e32 v145, v1
	s_or_b64 s[20:21], s[80:81], vcc
	s_or_b64 s[22:23], s[84:85], vcc
	v_log_f32_e32 v112, v126
	s_waitcnt vmcnt(0)
	v_mfma_f32_16x16x32_bf16 v[82:85], v[82:85], v[18:21], v[78:81]
	v_add_f32_e32 v113, 1.0, v128
	v_log_f32_e32 v113, v113
	v_fmac_f32_e32 v0, 0x3f317218, v112
	v_mfma_f32_16x16x32_bf16 v[78:81], v[108:111], v[18:21], v[134:137]
	v_mul_f32_e32 v109, 0x3e000000, v132
	v_mul_f32_e64 v110, |v109|, s41
	v_exp_f32_e32 v110, v110
	v_cndmask_b32_e64 v108, 0, v0, s[10:11]
	v_fma_f32 v0, v131, s4, -v0
	v_mul_f32_e32 v111, 0x3e000000, v133
	v_cndmask_b32_e64 v205, v193, v0, s[10:11]
	v_max_f32_e32 v0, 0, v109
	v_add_f32_e32 v109, 1.0, v110
	v_mul_f32_e64 v110, |v111|, s41
	v_log_f32_e32 v109, v109
	v_exp_f32_e32 v112, v110
	s_or_b64 s[10:11], s[50:51], vcc
	v_max_f32_e32 v114, 0, v127
	v_fmac_f32_e32 v0, 0x3f317218, v109
	v_add_f32_e32 v109, 1.0, v112
	v_log_f32_e32 v109, v109
	v_cndmask_b32_e64 v110, 0, v0, s[10:11]
	v_fma_f32 v0, v132, s4, -v0
	v_cndmask_b32_e64 v206, v193, v0, s[10:11]
	v_max_f32_e32 v0, 0, v111
	v_fmac_f32_e32 v0, 0x3f317218, v109
	v_mul_f32_e32 v109, 0x3e000000, v90
	v_mul_f32_e64 v111, |v109|, s41
	v_exp_f32_e32 v111, v111
	s_or_b64 s[10:11], s[52:53], vcc
	v_cndmask_b32_e64 v112, 0, v0, s[10:11]
	v_fma_f32 v0, v133, s4, -v0
	v_cndmask_b32_e64 v207, v193, v0, s[10:11]
	v_add_f32_e32 v0, 1.0, v111
	v_mul_f32_e32 v111, 0x3e000000, v91
	v_mfma_f32_16x16x32_bf16 v[66:69], v[66:69], v[14:17], 0
	v_fmac_f32_e32 v114, 0x3f317218, v113
	v_mul_f32_e64 v113, |v111|, s41
	v_log_f32_e32 v0, v0
	v_mfma_f32_16x16x32_bf16 v[116:119], v[116:119], v[14:17], 0
	v_exp_f32_e32 v113, v113
	s_or_b64 s[10:11], s[60:61], vcc
	v_cndmask_b32_e64 v132, 0, v212, s[94:95]
	v_mfma_f32_16x16x32_bf16 v[66:69], v[74:77], v[18:21], v[66:69]
	v_mov_b32_e32 v212, v1
	s_or_b64 s[12:13], s[86:87], vcc
	s_or_b64 s[24:25], s[88:89], vcc
	v_mfma_f32_16x16x32_bf16 v[74:77], v[120:123], v[18:21], v[116:119]
	s_setprio 0
	v_fma_f32 v70, v70, s4, -v114
	v_cndmask_b32_e32 v70, v193, v70, vcc
	s_nop 0
	v_max_f32_e32 v118, 0, v109
	v_fmac_f32_e32 v118, 0x3f317218, v0
	v_add_f32_e32 v0, 1.0, v113
	v_mul_f32_e32 v113, 0x3e000000, v92
	v_log_f32_e32 v109, v0
	v_mul_f32_e64 v0, |v113|, s41
	v_exp_f32_e32 v115, v0
	v_max_f32_e32 v0, 0, v111
	v_mul_f32_e32 v148, 0x3f317218, v109
	v_max_f32_e32 v150, 0, v113
	v_add_f32_e32 v109, 1.0, v115
	v_log_f32_e32 v196, v109
	v_mul_f32_e32 v109, 0x3e000000, v93
	v_mul_f32_e64 v111, |v109|, s41
	v_mul_f32_e32 v113, 0x3e000000, v86
	v_exp_f32_e32 v111, v111
	v_mul_f32_e64 v115, |v113|, s41
	v_exp_f32_e32 v115, v115
	v_max_f32_e32 v198, 0, v109
	v_add_f32_e32 v109, 1.0, v111
	v_log_f32_e32 v210, v109
	v_add_f32_e32 v109, 1.0, v115
	v_mul_f32_e32 v111, 0x3e000000, v87
	v_log_f32_e32 v109, v109
	v_mul_f32_e64 v115, |v111|, s41
	v_exp_f32_e32 v115, v115
	v_max_f32_e32 v134, 0, v113
	v_fmac_f32_e32 v134, 0x3f317218, v109
	v_mul_f32_e32 v109, 0x3e000000, v88
	v_fma_f32 v113, v86, s4, -v134
	v_add_f32_e32 v86, 1.0, v115
	v_mul_f32_e64 v115, |v109|, s41
	v_log_f32_e32 v86, v86
	v_exp_f32_e32 v115, v115
	v_max_f32_e32 v144, 0, v111
	v_max_f32_e32 v138, 0, v109
	v_mul_f32_e32 v146, 0x3f317218, v86
	v_add_f32_e32 v86, 1.0, v115
	v_log_f32_e32 v142, v86
	v_mul_f32_e32 v86, 0x3e000000, v89
	v_mul_f32_e64 v109, |v86|, s41
	v_mul_f32_e32 v111, 0x3e000000, v71
	v_exp_f32_e32 v109, v109
	v_mul_f32_e64 v115, |v111|, s41
	v_exp_f32_e32 v115, v115
	v_max_f32_e32 v136, 0, v86
	v_add_f32_e32 v86, 1.0, v109
	v_log_f32_e32 v140, v86
	v_add_f32_e32 v86, 1.0, v115
	v_mul_f32_e32 v115, 0x3e000000, v72
	v_log_f32_e32 v109, v86
	v_mul_f32_e64 v86, |v115|, s41
	v_exp_f32_e32 v116, v86
	v_max_f32_e32 v86, 0, v111
	v_mul_f32_e32 v111, 0x3e000000, v66
	v_max_f32_e32 v120, 0, v115
	v_mul_f32_e64 v115, |v111|, s41
	v_exp_f32_e32 v115, v115
	v_mul_f32_e32 v126, 0x3f317218, v109
	v_add_f32_e32 v109, 1.0, v116
	v_log_f32_e32 v122, v109
	v_mul_f32_e32 v109, 0x3e000000, v73
	v_mul_f32_e64 v116, |v109|, s41
	v_max_f32_e32 v128, 0, v109
	v_add_f32_e32 v109, 1.0, v115
	v_exp_f32_e32 v116, v116
	v_log_f32_e32 v109, v109
	v_max_f32_e32 v111, 0, v111
	v_fma_f32 v90, v90, s4, -v118
	v_add_f32_e32 v115, 1.0, v116
	v_fmac_f32_e32 v111, 0x3f317218, v109
	v_mul_f32_e32 v109, 0x3e000000, v67
	v_log_f32_e32 v130, v115
	v_mul_f32_e64 v115, |v109|, s41
	v_exp_f32_e32 v115, v115
	v_fma_f32 v208, v66, s4, -v111
	v_add_f32_e32 v133, 0, v111
	v_mul_f32_e32 v111, 0x3e000000, v68
	v_add_f32_e32 v66, 1.0, v115
	v_log_f32_e32 v66, v66
	v_mul_f32_e64 v115, |v111|, s41
	v_exp_f32_e32 v115, v115
	v_max_f32_e32 v109, 0, v109
	v_fmac_f32_e32 v109, 0x3f317218, v66
	v_fma_f32 v209, v67, s4, -v109
	v_add_f32_e32 v67, 1.0, v115
	v_log_f32_e32 v116, v67
	v_mul_f32_e32 v67, 0x3e000000, v69
	v_max_f32_e32 v66, 0, v111
	v_mul_f32_e64 v111, |v67|, s41
	v_mul_f32_e32 v115, 0x3e000000, v82
	v_exp_f32_e32 v111, v111
	v_mul_f32_e64 v117, |v115|, s41
	v_exp_f32_e32 v119, v117
	v_max_f32_e32 v149, 0, v115
	v_add_f32_e32 v111, 1.0, v111
	v_log_f32_e32 v117, v111
	v_add_f32_e32 v111, 1.0, v119
	v_mul_f32_e32 v119, 0x3e000000, v83
	v_mul_f32_e64 v121, |v119|, s41
	v_log_f32_e32 v111, v111
	v_exp_f32_e32 v121, v121
	v_mul_f32_e32 v115, 0x3e000000, v84
	v_max_f32_e32 v213, 0, v119
	v_fmac_f32_e32 v149, 0x3f317218, v111
	v_add_f32_e32 v111, 1.0, v121
	v_mul_f32_e64 v121, |v115|, s41
	v_log_f32_e32 v111, v111
	v_exp_f32_e32 v121, v121
	v_max_f32_e32 v151, 0, v115
	v_fma_f32 v82, v82, s4, -v149
	v_mul_f32_e32 v119, 0x3f317218, v111
	v_add_f32_e32 v111, 1.0, v121
	v_log_f32_e32 v197, v111
	v_mul_f32_e32 v111, 0x3e000000, v85
	v_mul_f32_e64 v115, |v111|, s41
	v_mul_f32_e32 v121, 0x3e000000, v78
	v_exp_f32_e32 v115, v115
	v_mul_f32_e64 v123, |v121|, s41
	v_exp_f32_e32 v123, v123
	v_max_f32_e32 v199, 0, v111
	v_add_f32_e32 v111, 1.0, v115
	v_mul_f32_e32 v115, 0x3e000000, v79
	v_log_f32_e32 v211, v111
	v_add_f32_e32 v111, 1.0, v123
	v_mul_f32_e64 v123, |v115|, s41
	v_log_f32_e32 v111, v111
	v_exp_f32_e32 v123, v123
	v_max_f32_e32 v147, 0, v121
	v_mul_f32_e32 v121, 0x3e000000, v80
	v_fmac_f32_e32 v147, 0x3f317218, v111
	v_add_f32_e32 v111, 1.0, v123
	v_mul_f32_e64 v123, |v121|, s41
	v_log_f32_e32 v111, v111
	v_exp_f32_e32 v123, v123
	v_max_f32_e32 v215, 0, v115
	v_max_f32_e32 v139, 0, v121
	v_mul_f32_e32 v135, 0x3f317218, v111
	v_add_f32_e32 v111, 1.0, v123
	v_log_f32_e32 v143, v111
	v_mul_f32_e32 v111, 0x3e000000, v81
	v_mul_f32_e64 v115, |v111|, s41
	v_mul_f32_e32 v121, 0x3e000000, v74
	v_exp_f32_e32 v115, v115
	v_mul_f32_e64 v123, |v121|, s41
	v_exp_f32_e32 v123, v123
	v_max_f32_e32 v137, 0, v111
	v_add_f32_e32 v111, 1.0, v115
	v_mul_f32_e32 v115, 0x3e000000, v75
	v_log_f32_e32 v141, v111
	v_add_f32_e32 v111, 1.0, v123
	v_mul_f32_e64 v123, |v115|, s41
	v_log_f32_e32 v111, v111
	v_exp_f32_e32 v123, v123
	v_max_f32_e32 v127, 0, v121
	v_max_f32_e32 v217, 0, v115
	v_fmac_f32_e32 v127, 0x3f317218, v111
	v_add_f32_e32 v111, 1.0, v123
	v_log_f32_e32 v111, v111
	v_pk_add_f32 v[218:219], v[0:1], v[148:149]
	v_pk_fma_f32 v[148:149], v[196:197], s[30:31], v[150:151] op_sel_hi:[1,0,1]
	v_pk_fma_f32 v[150:151], v[210:211], s[30:31], v[198:199] op_sel_hi:[1,0,1]
	v_mul_f32_e32 v115, 0x3f317218, v111
	v_mul_f32_e32 v111, 0x3e000000, v76
	v_mul_f32_e64 v121, |v111|, s41
	v_exp_f32_e32 v123, v121
	v_max_f32_e32 v121, 0, v111
	v_mul_f32_e32 v111, 0x3e000000, v77
	v_mul_f32_e64 v129, |v111|, s41
	v_exp_f32_e32 v131, v129
	v_max_f32_e32 v129, 0, v111
	v_pk_add_f32 v[198:199], v[212:213], v[118:119]
	v_fma_f32 v0, v91, s4, -v218
	v_add_f32_e32 v111, 1.0, v131
	v_log_f32_e32 v131, v111
	v_cndmask_b32_e64 v111, v193, v90, s[10:11]
	v_fma_f32 v90, v92, s4, -v148
	v_cndmask_b32_e64 v227, v193, v90, s[16:17]
	v_fma_f32 v90, v93, s4, -v150
	v_cndmask_b32_e64 v228, v193, v90, s[18:19]
	v_cndmask_b32_e64 v197, 0, v219, s[94:95]
	v_cndmask_b32_e64 v196, 0, v218, s[14:15]
	v_cndmask_b32_e64 v91, 0, v199, s[96:97]
	v_cndmask_b32_e64 v90, 0, v198, s[10:11]
	v_pk_add_f32 v[118:119], v[196:197], v[90:91]
	v_cndmask_b32_e64 v93, 0, v149, s[98:99]
	v_cndmask_b32_e64 v92, 0, v148, s[16:17]
	v_pk_add_f32 v[144:145], v[144:145], v[146:147]
	v_pk_add_f32 v[210:211], v[92:93], v[118:119]
	v_cndmask_b32_e64 v118, 0, v150, s[18:19]
	s_or_b64 s[18:19], s[76:77], vcc
	v_fma_f32 v87, v87, s4, -v144
	s_or_b64 s[16:17], s[72:73], vcc
	v_fma_f32 v78, v78, s4, -v147
	v_cndmask_b32_e64 v0, v193, v0, s[14:15]
	v_cndmask_b32_e64 v90, v193, v113, s[18:19]
	v_cndmask_b32_e64 v113, v193, v87, s[16:17]
	v_pk_fma_f32 v[142:143], v[142:143], s[30:31], v[138:139] op_sel_hi:[1,0,1]
	s_or_b64 s[14:15], s[70:71], vcc
	v_cndmask_b32_e64 v144, 0, v144, s[16:17]
	v_pk_add_f32 v[146:147], v[214:215], v[134:135]
	s_or_b64 s[16:17], s[74:75], vcc
	s_or_b64 s[10:11], s[66:67], vcc
	v_fma_f32 v87, v88, s4, -v142
	v_pk_fma_f32 v[140:141], v[140:141], s[30:31], v[136:137] op_sel_hi:[1,0,1]
	v_cndmask_b32_e64 v145, 0, v145, s[14:15]
	v_cndmask_b32_e64 v135, 0, v147, s[16:17]
	v_cndmask_b32_e64 v134, 0, v146, s[18:19]
	s_or_b64 s[18:19], s[78:79], vcc
	v_cndmask_b32_e64 v119, 0, v151, s[10:11]
	v_cndmask_b32_e64 v148, v193, v87, s[20:21]
	v_fma_f32 v87, v89, s4, -v140
	v_pk_add_f32 v[88:89], v[144:145], v[134:135]
	v_cndmask_b32_e64 v137, 0, v143, s[18:19]
	v_cndmask_b32_e64 v136, 0, v142, s[20:21]
	s_or_b64 s[20:21], s[82:83], vcc
	v_pk_add_f32 v[210:211], v[118:119], v[210:211]
	v_pk_add_f32 v[88:89], v[136:137], v[88:89]
	v_cndmask_b32_e64 v139, 0, v141, s[20:21]
	v_cndmask_b32_e64 v138, 0, v140, s[22:23]
	ds_bpermute_b32 v212, v204, v210
	ds_bpermute_b32 v213, v204, v211
	v_pk_add_f32 v[88:89], v[138:139], v[88:89]
	ds_bpermute_b32 v214, v204, v88
	ds_bpermute_b32 v215, v204, v89
	v_add_f32_e32 v123, 1.0, v123
	s_waitcnt lgkmcnt(2)
	v_pk_add_f32 v[210:211], v[210:211], v[212:213]
	ds_bpermute_b32 v218, v203, v210
	v_log_f32_e32 v123, v123
	s_waitcnt lgkmcnt(1)
	v_pk_add_f32 v[220:221], v[88:89], v[214:215]
	ds_bpermute_b32 v222, v203, v220
	v_cndmask_b32_e64 v150, v193, v87, s[22:23]
	v_cndmask_b32_e64 v87, 0, v212, s[44:45]
	s_waitcnt lgkmcnt(1)
	v_cndmask_b32_e64 v88, 0, v218, s[46:47]
	v_add_f32_e32 v134, v87, v88
	v_cndmask_b32_e64 v87, 0, v214, s[44:45]
	s_waitcnt lgkmcnt(0)
	v_cndmask_b32_e64 v88, 0, v222, s[46:47]
	v_add_f32_e32 v140, v87, v88
	v_mov_b32_e32 v87, v1
	v_fma_f32 v74, v74, s4, -v127
	v_pk_add_f32 v[86:87], v[86:87], v[126:127]
	v_pk_fma_f32 v[126:127], v[130:131], s[30:31], v[128:129] op_sel_hi:[1,0,1]
	v_pk_add_f32 v[130:131], v[216:217], v[114:115]
	v_cndmask_b32_e64 v74, v193, v74, s[12:13]
	v_pk_fma_f32 v[122:123], v[122:123], s[30:31], v[120:121] op_sel_hi:[1,0,1]
	v_cndmask_b32_e64 v129, 0, v87, s[12:13]
	v_cndmask_b32_e32 v128, 0, v86, vcc
	v_cndmask_b32_e64 v89, 0, v131, s[24:25]
	v_cndmask_b32_e32 v88, 0, v130, vcc
	s_or_b64 s[12:13], s[90:91], vcc
	v_pk_add_f32 v[120:121], v[128:129], v[88:89]
	v_cndmask_b32_e64 v115, 0, v123, s[12:13]
	v_cndmask_b32_e32 v114, 0, v122, vcc
	s_or_b64 s[22:23], s[92:93], vcc
	v_pk_add_f32 v[216:217], v[114:115], v[120:121]
	v_cndmask_b32_e64 v121, 0, v127, s[22:23]
	v_cndmask_b32_e32 v120, 0, v126, vcc
	v_pk_add_f32 v[216:217], v[120:121], v[216:217]
	ds_bpermute_b32 v224, v204, v216
	ds_bpermute_b32 v225, v204, v217
	v_fma_f32 v71, v71, s4, -v86
	ds_bpermute_b32 v219, v203, v211
	ds_bpermute_b32 v223, v203, v221
	v_fma_f32 v72, v72, s4, -v122
	s_waitcnt lgkmcnt(2)
	v_pk_add_f32 v[86:87], v[216:217], v[224:225]
	ds_bpermute_b32 v216, v203, v86
	ds_bpermute_b32 v217, v203, v87
	v_cndmask_b32_e32 v88, v193, v72, vcc
	v_fma_f32 v72, v73, s4, -v126
	v_cndmask_b32_e32 v122, v193, v72, vcc
	v_cndmask_b32_e64 v72, 0, v224, s[44:45]
	s_waitcnt lgkmcnt(1)
	v_cndmask_b32_e64 v73, 0, v216, s[46:47]
	s_waitcnt lgkmcnt(0)
	v_pk_add_f32 v[86:87], v[86:87], v[216:217]
	v_add_f32_e32 v126, v72, v73
	v_pk_add_f32 v[72:73], v[210:211], v[218:219]
	v_pk_add_f32 v[210:211], v[220:221], v[222:223]
	v_pk_add_f32 v[220:221], v[106:107], v[86:87]
	v_add_f32_e32 v106, v106, v126
	v_pk_add_f32 v[210:211], v[210:211], v[220:221]
	v_add_f32_e32 v120, v120, v106
	v_pk_add_f32 v[86:87], v[72:73], v[210:211]
	v_add_f32_e32 v72, v134, v210
	v_add_f32_e32 v73, v118, v72
	v_add_f32_e32 v92, v92, v73
	v_add_f32_e32 v118, v196, v92
	v_sub_f32_e32 v0, v0, v92
	v_sub_f32_e32 v92, v111, v118
	v_add_f32_e32 v111, v140, v220
	v_add_f32_e32 v118, v138, v111
	v_sub_f32_e32 v72, v228, v72
	v_sub_f32_e32 v73, v227, v73
	v_add_f32_e32 v129, v136, v118
	v_sub_f32_e32 v106, v122, v106
	v_sub_f32_e32 v88, v88, v120
	v_mul_f32_e32 v72, 0x3fb8aa3b, v72
	v_mul_f32_e32 v73, 0x3fb8aa3b, v73
	v_mul_f32_e32 v0, 0x3fb8aa3b, v0
	v_mul_f32_e32 v92, 0x3fb8aa3b, v92
	v_add_f32_e32 v130, v144, v129
	v_mul_f32_e32 v106, 0x3fb8aa3b, v106
	v_mul_f32_e32 v88, 0x3fb8aa3b, v88
	v_exp_f32_e32 v72, v72
	v_exp_f32_e32 v73, v73
	v_exp_f32_e32 v0, v0
	v_exp_f32_e32 v92, v92
	v_sub_f32_e32 v113, v113, v129
	v_sub_f32_e32 v90, v90, v130
	v_exp_f32_e32 v106, v106
	v_exp_f32_e32 v88, v88
	v_mul_f32_e32 v113, 0x3fb8aa3b, v113
	v_mul_f32_e32 v90, 0x3fb8aa3b, v90
	v_add_f32_e32 v114, v114, v120
	v_cndmask_b32_e32 v71, v193, v71, vcc
	v_sub_f32_e32 v111, v150, v111
	v_sub_f32_e32 v118, v148, v118
	v_exp_f32_e32 v113, v113
	v_exp_f32_e32 v90, v90
	v_add_f32_e32 v126, v128, v114
	v_mul_f32_e32 v111, 0x3fb8aa3b, v111
	v_mul_f32_e32 v118, 0x3fb8aa3b, v118
	v_sub_f32_e32 v71, v71, v114
	v_sub_f32_e32 v70, v70, v126
	v_exp_f32_e32 v111, v111
	v_exp_f32_e32 v118, v118
	v_mul_f32_e32 v71, 0x3fb8aa3b, v71
	v_mul_f32_e32 v70, 0x3fb8aa3b, v70
	v_cvt_pk_bf16_f32 v128, v92, v0
	v_cvt_pk_bf16_f32 v129, v73, v72
	v_cvt_pk_bf16_f32 v73, v88, v106
	v_cndmask_b32_e64 v0, v193, v82, s[94:95]
	v_fma_f32 v82, v83, s4, -v199
	v_fma_f32 v83, v84, s4, -v149
	v_fma_f32 v84, v85, s4, -v151
	v_cndmask_b32_e64 v85, 0, v213, s[44:45]
	v_cndmask_b32_e64 v88, 0, v219, s[46:47]
	v_exp_f32_e32 v114, v71
	v_exp_f32_e32 v120, v70
	v_add_f32_e32 v85, v85, v88
	v_cndmask_b32_e64 v88, v193, v78, s[14:15]
	v_fma_f32 v78, v79, s4, -v147
	v_max_f32_e32 v67, 0, v67
	v_cvt_pk_bf16_f32 v70, v90, v113
	v_cndmask_b32_e64 v90, v193, v78, s[16:17]
	v_fma_f32 v78, v80, s4, -v143
	v_cndmask_b32_e64 v92, v193, v78, s[18:19]
	v_fma_f32 v78, v81, s4, -v141
	v_pk_fma_f32 v[66:67], v[116:117], s[30:31], v[66:67] op_sel_hi:[1,0,1]
	v_pk_add_f32 v[132:133], v[108:109], v[132:133]
	v_cvt_pk_bf16_f32 v71, v118, v111
	v_cndmask_b32_e64 v106, v193, v78, s[20:21]
	v_cndmask_b32_e64 v78, 0, v215, s[44:45]
	v_cndmask_b32_e64 v79, 0, v223, s[46:47]
	v_mov_b32_e32 v111, v66
	v_cvt_pk_bf16_f32 v72, v120, v114
	v_add_f32_e32 v114, v78, v79
	v_pk_add_f32 v[78:79], v[110:111], v[132:133]
	v_mov_b32_e32 v113, v67
	v_pk_add_f32 v[78:79], v[112:113], v[78:79]
	ds_bpermute_b32 v80, v204, v78
	ds_bpermute_b32 v81, v204, v79
	v_fma_f32 v76, v76, s4, -v123
	v_cndmask_b32_e64 v111, v193, v76, s[12:13]
	v_fma_f32 v76, v77, s4, -v127
	v_cndmask_b32_e64 v113, v193, v76, s[22:23]
	s_waitcnt lgkmcnt(0)
	v_pk_add_f32 v[116:117], v[78:79], v[80:81]
	ds_bpermute_b32 v122, v203, v116
	v_cndmask_b32_e64 v76, 0, v225, s[44:45]
	v_cndmask_b32_e64 v77, 0, v217, s[46:47]
	v_add_f32_e32 v76, v76, v77
	v_cndmask_b32_e64 v77, 0, v80, s[44:45]
	s_waitcnt lgkmcnt(0)
	v_cndmask_b32_e64 v78, 0, v122, s[46:47]
	v_add_f32_e32 v77, v77, v78
	v_add_f32_e32 v77, v77, v86
	v_add_f32_e32 v78, v112, v77
	v_add_f32_e32 v79, v110, v78
	v_sub_f32_e32 v77, v207, v77
	v_sub_f32_e32 v78, v206, v78
	v_mul_f32_e32 v77, 0x3fb8aa3b, v77
	v_mul_f32_e32 v78, 0x3fb8aa3b, v78
	ds_bpermute_b32 v123, v203, v117
	v_exp_f32_e32 v77, v77
	v_exp_f32_e32 v78, v78
	v_add_f32_e32 v80, v108, v79
	v_sub_f32_e32 v79, v205, v79
	v_sub_f32_e32 v80, v226, v80
	v_cvt_pk_bf16_f32 v127, v78, v77
	v_cndmask_b32_e64 v77, 0, v81, s[44:45]
	s_waitcnt lgkmcnt(0)
	v_cndmask_b32_e64 v78, 0, v123, s[46:47]
	v_add_f32_e32 v77, v77, v78
	v_add_f32_e32 v77, v77, v87
	v_mul_f32_e32 v79, 0x3fb8aa3b, v79
	v_mul_f32_e32 v80, 0x3fb8aa3b, v80
	v_fma_f32 v69, v69, s4, -v67
	v_add_f32_e32 v67, v77, v67
	v_exp_f32_e32 v79, v79
	v_exp_f32_e32 v80, v80
	v_add_f32_e32 v78, v66, v67
	v_fma_f32 v66, v68, s4, -v66
	v_sub_f32_e32 v66, v66, v67
	v_mul_f32_e32 v66, 0x3fb8aa3b, v66
	v_exp_f32_e32 v108, v66
	v_sub_f32_e32 v66, v209, v78
	v_cvt_pk_bf16_f32 v126, v80, v79
	v_add_f32_e32 v79, v109, v78
	v_mul_f32_e32 v66, 0x3fb8aa3b, v66
	v_exp_f32_e32 v78, v66
	v_sub_f32_e32 v66, v208, v79
	v_mul_f32_e32 v66, 0x3fb8aa3b, v66
	v_cndmask_b32_e64 v84, v193, v84, s[10:11]
	v_exp_f32_e32 v79, v66
	v_add_f32_e32 v66, v85, v211
	v_add_f32_e32 v67, v119, v66
	v_sub_f32_e32 v66, v84, v66
	v_cndmask_b32_e64 v83, v193, v83, s[98:99]
	v_mul_f32_e32 v66, 0x3fb8aa3b, v66
	v_exp_f32_e32 v84, v66
	v_sub_f32_e32 v66, v83, v67
	v_cndmask_b32_e64 v82, v193, v82, s[96:97]
	v_add_f32_e32 v68, v93, v67
	v_mul_f32_e32 v66, 0x3fb8aa3b, v66
	v_sub_f32_e32 v69, v69, v77
	v_exp_f32_e32 v85, v66
	v_sub_f32_e32 v66, v82, v68
	v_mul_f32_e32 v69, 0x3fb8aa3b, v69
	v_mul_f32_e32 v66, 0x3fb8aa3b, v66
	v_exp_f32_e32 v77, v69
	v_add_f32_e32 v69, v91, v68
	v_exp_f32_e32 v91, v66
	v_add_f32_e32 v66, v114, v221
	v_add_f32_e32 v67, v139, v66
	v_sub_f32_e32 v66, v106, v66
	v_mul_f32_e32 v66, 0x3fb8aa3b, v66
	v_exp_f32_e32 v93, v66
	v_sub_f32_e32 v66, v92, v67
	v_add_f32_e32 v68, v137, v67
	v_mul_f32_e32 v66, 0x3fb8aa3b, v66
	v_exp_f32_e32 v92, v66
	v_sub_f32_e32 v66, v90, v68
	v_sub_f32_e32 v0, v0, v69
	v_add_f32_e32 v69, v135, v68
	v_mul_f32_e32 v66, 0x3fb8aa3b, v66
	v_exp_f32_e32 v90, v66
	v_sub_f32_e32 v66, v88, v69
	v_lshl_add_u32 v88, v155, 1, v169
	v_add_u32_e32 v106, 0x2000, v88
	v_mul_f32_e32 v80, 0x3fb8aa3b, v66
	ds_read2_b64 v[66:69], v106 offset0:128 offset1:132
	v_add_u32_e32 v110, 0x2800, v88
	v_exp_f32_e32 v109, v80
	ds_read2_b64 v[80:83], v110 offset0:160 offset1:164
	v_mul_f32_e32 v0, 0x3fb8aa3b, v0
	v_exp_f32_e32 v0, v0
	v_add_f32_e32 v107, v107, v76
	v_cvt_pk_bf16_f32 v76, v79, v78
	v_cvt_pk_bf16_f32 v79, v85, v84
	s_waitcnt lgkmcnt(0)
	v_mov_b32_e32 v84, v80
	v_mov_b32_e32 v85, v81
	v_cvt_pk_bf16_f32 v77, v108, v77
	v_cvt_pk_bf16_f32 v78, v0, v91
	v_add_u32_e32 v108, 0x3000, v88
	s_setprio 3
	v_mfma_f32_16x16x32_bf16 v[62:65], v[66:69], v[126:129], v[62:65]
	v_sub_f32_e32 v80, v113, v107
	v_add_u32_e32 v88, 0x3800, v88
	v_add_f32_e32 v0, v121, v107
	v_mfma_f32_16x16x32_bf16 v[54:57], v[66:69], v[76:79], v[54:57]
	ds_read2_b64 v[66:69], v108 offset0:200 offset1:204
	v_mul_f32_e32 v107, 0x3fb8aa3b, v80
	v_fma_f32 v75, v75, s4, -v131
	v_mfma_f32_16x16x32_bf16 v[58:61], v[82:85], v[126:129], v[58:61]
	v_add_f32_e32 v91, v115, v0
	v_cndmask_b32_e64 v75, v193, v75, s[24:25]
	v_add_f32_e32 v89, v89, v91
	v_mfma_f32_16x16x32_bf16 v[46:49], v[82:85], v[76:79], v[46:49]
	ds_read2_b64 v[80:83], v88 offset0:232 offset1:236
	v_sub_f32_e32 v0, v111, v0
	v_sub_f32_e32 v75, v75, v91
	s_waitcnt lgkmcnt(1)
	v_mfma_f32_16x16x32_bf16 v[50:53], v[66:69], v[126:129], v[50:53]
	v_sub_f32_e32 v74, v74, v89
	s_waitcnt lgkmcnt(0)
	v_mov_b32_e32 v84, v80
	v_mov_b32_e32 v85, v81
	v_mfma_f32_16x16x32_bf16 v[42:45], v[66:69], v[76:79], v[42:45]
	ds_read2_b64 v[66:69], v106 offset0:136 offset1:140
	v_mul_f32_e32 v0, 0x3fb8aa3b, v0
	v_mul_f32_e32 v75, 0x3fb8aa3b, v75
	v_mul_f32_e32 v74, 0x3fb8aa3b, v74
	v_exp_f32_e32 v107, v107
	v_exp_f32_e32 v0, v0
	v_exp_f32_e32 v91, v75
	v_mfma_f32_16x16x32_bf16 v[34:37], v[82:85], v[76:79], v[34:37]
	v_exp_f32_e32 v76, v74
	ds_read2_b64 v[78:81], v110 offset0:168 offset1:172
	v_cvt_pk_bf16_f32 v74, v109, v90
	v_cvt_pk_bf16_f32 v75, v92, v93
	v_cvt_pk_bf16_f32 v76, v76, v91
	v_cvt_pk_bf16_f32 v77, v0, v107
	s_waitcnt lgkmcnt(1)
	v_mfma_f32_16x16x32_bf16 v[62:65], v[66:69], v[70:73], v[62:65]
	s_mov_b32 s10, 0x42b40000
	s_mov_b32 s97, 0x27c0000
	s_mov_b32 s96, 0x800000
	v_mfma_f32_16x16x32_bf16 v[54:57], v[66:69], v[74:77], v[54:57]
	s_waitcnt lgkmcnt(0)
	v_mov_b32_e32 v66, v80
	v_mov_b32_e32 v67, v81
	v_mov_b32_e32 v68, v78
	v_mov_b32_e32 v69, v79
	ds_read2_b64 v[78:81], v88 offset0:224 offset1:228
	v_mfma_f32_16x16x32_bf16 v[38:41], v[82:85], v[126:129], v[38:41]
	s_mov_b32 s30, 0x27e0000
	v_mfma_f32_16x16x32_bf16 v[58:61], v[66:69], v[70:73], v[58:61]
	v_mfma_f32_16x16x32_bf16 v[46:49], v[66:69], v[74:77], v[46:49]
	ds_read2_b64 v[66:69], v108 offset0:192 offset1:196
	s_waitcnt lgkmcnt(0)
	v_mfma_f32_16x16x32_bf16 v[50:53], v[66:69], v[70:73], v[50:53]
	v_mfma_f32_16x16x32_bf16 v[42:45], v[66:69], v[74:77], v[42:45]
	v_mov_b32_e32 v66, v80
	v_mov_b32_e32 v67, v81
	v_mov_b32_e32 v68, v78
	v_mov_b32_e32 v69, v79
	s_nop 1
	v_mfma_f32_16x16x32_bf16 v[38:41], v[66:69], v[70:73], v[38:41]
	v_add_f32_e64 v70, v116, v122
	v_add_f32_e64 v71, v117, v123
	v_pk_add_f32 v[106:107], v[70:71], v[86:87]
	v_mfma_f32_16x16x32_bf16 v[34:37], v[66:69], v[74:77], v[34:37]
	s_setprio 0
	v_cmp_lt_f32_e32 vcc, s10, v106
	v_cmp_lt_f32_e64 s[10:11], s10, v107
	s_and_b64 s[10:11], vcc, s[10:11]
	s_nop 0
	v_cndmask_b32_e64 v0, 0, 1, s[10:11]
	v_cmp_ne_u32_e32 vcc, 0, v0
	s_cmp_eq_u64 vcc, exec
	s_cselect_b64 s[10:11], -1, 0
	s_andn2_b64 s[12:13], s[38:39], exec
	s_and_b64 s[10:11], s[10:11], exec
	s_or_b64 s[38:39], s[12:13], s[10:11]

.LBB0_792:
	s_barrier
	s_waitcnt vmcnt(7)
	ds_write_b128 v106, v[66:69]
	s_waitcnt vmcnt(6)
	ds_write_b128 v106, v[70:73] offset:18432
	s_waitcnt vmcnt(5)
	ds_write_b128 v106, v[74:77] offset:4096
	s_waitcnt vmcnt(4)
	ds_write_b128 v106, v[78:81] offset:22528
	s_waitcnt vmcnt(3)
	ds_write_b128 v106, v[82:85] offset:8192
	s_waitcnt vmcnt(2)
	ds_write_b128 v106, v[86:89] offset:26624
	s_waitcnt vmcnt(1)
	ds_write_b128 v106, v[90:93] offset:12288
	s_waitcnt vmcnt(0)
	ds_write_b128 v106, v[94:97] offset:30720
	s_waitcnt lgkmcnt(0)
	s_barrier
	s_add_u32 s100, s6, 0x27c0000
	s_addc_u32 s101, s7, 0
	v_lshl_add_u64 v[212:213], v[114:115], 0, s[100:101]
	global_load_dwordx4 v[66:69], v[212:213], off offset:128
	v_lshl_add_u64 v[214:215], v[112:113], 0, s[6:7]
	global_load_dwordx4 v[70:73], v[214:215], off offset:128
	s_add_u32 s100, s6, 0x27d0000
	s_addc_u32 s101, s7, 0
	v_lshl_add_u64 v[216:217], v[114:115], 0, s[100:101]
	global_load_dwordx4 v[74:77], v[216:217], off offset:128
	s_add_u32 s100, s6, 0x10000
	s_addc_u32 s101, s7, 0
	v_lshl_add_u64 v[218:219], v[112:113], 0, s[100:101]
	global_load_dwordx4 v[78:81], v[218:219], off offset:128
	s_add_u32 s100, s6, 0x27e0000
	s_addc_u32 s101, s7, 0
	v_lshl_add_u64 v[212:213], v[114:115], 0, s[100:101]
	global_load_dwordx4 v[82:85], v[212:213], off offset:128
	s_add_u32 s100, s6, 0x20000
	s_addc_u32 s101, s7, 0
	v_lshl_add_u64 v[214:215], v[112:113], 0, s[100:101]
	global_load_dwordx4 v[86:89], v[214:215], off offset:128
	s_add_u32 s100, s6, 0x27f0000
	s_addc_u32 s101, s7, 0
	v_lshl_add_u64 v[216:217], v[114:115], 0, s[100:101]
	global_load_dwordx4 v[90:93], v[216:217], off offset:128
	s_add_u32 s100, s6, 0x30000
	s_addc_u32 s101, s7, 0
	v_lshl_add_u64 v[218:219], v[112:113], 0, s[100:101]
	global_load_dwordx4 v[94:97], v[218:219], off offset:128
	s_setprio 3
	ds_read_b128 v[146:149], v121 offset:18432
	ds_read_b128 v[150:153], v120
	ds_read_b128 v[154:157], v248
	ds_read_b128 v[158:161], v249 offset:18432
	ds_read_b128 v[162:165], v121 offset:20480
	ds_read_b128 v[166:169], v249 offset:20480
	ds_read_b128 v[204:207], v121 offset:22528
	ds_read_b128 v[208:211], v249 offset:22528
	ds_read_b128 v[126:129], v121 offset:24576
	ds_read_b128 v[130:133], v249 offset:24576
	s_waitcnt lgkmcnt(8)
	v_mfma_f32_16x16x32_bf16 v[62:65], v[146:149], v[150:153], v[62:65]
	s_waitcnt lgkmcnt(5)
	v_mfma_f32_16x16x32_bf16 v[58:61], v[162:165], v[150:153], v[58:61]
	s_waitcnt lgkmcnt(3)
	v_mfma_f32_16x16x32_bf16 v[54:57], v[204:207], v[150:153], v[54:57]
	s_waitcnt lgkmcnt(1)
	v_mfma_f32_16x16x32_bf16 v[50:53], v[126:129], v[150:153], v[50:53]
	ds_read_b128 v[150:153], v120 offset:2048
	ds_read_b128 v[134:137], v248 offset:2048
	s_waitcnt lgkmcnt(1)
	v_mfma_f32_16x16x32_bf16 v[46:49], v[146:149], v[150:153], v[46:49]
	v_mfma_f32_16x16x32_bf16 v[42:45], v[162:165], v[150:153], v[42:45]
	v_mfma_f32_16x16x32_bf16 v[34:37], v[204:207], v[150:153], v[34:37]
	v_mfma_f32_16x16x32_bf16 v[30:33], v[126:129], v[150:153], v[30:33]
	ds_read_b128 v[150:153], v120 offset:4096
	ds_read_b128 v[138:141], v248 offset:4096
	s_waitcnt lgkmcnt(1)
	v_mfma_f32_16x16x32_bf16 v[18:21], v[146:149], v[150:153], v[18:21]
	v_mfma_f32_16x16x32_bf16 v[14:17], v[162:165], v[150:153], v[14:17]
	v_mfma_f32_16x16x32_bf16 v[10:13], v[204:207], v[150:153], v[10:13]
	v_mfma_f32_16x16x32_bf16 v[6:9], v[126:129], v[150:153], v[6:9]
	ds_read_b128 v[150:153], v120 offset:6144
	ds_read_b128 v[142:145], v248 offset:6144
	s_waitcnt lgkmcnt(1)
	v_mfma_f32_16x16x32_bf16 v[2:5], v[146:149], v[150:153], v[2:5]
	v_mfma_f32_16x16x32_bf16 v[62:65], v[158:161], v[154:157], v[62:65]
	v_mfma_f32_16x16x32_bf16 v[58:61], v[166:169], v[154:157], v[58:61]
	v_mfma_f32_16x16x32_bf16 v[54:57], v[208:211], v[154:157], v[54:57]
	v_mfma_f32_16x16x32_bf16 v[50:53], v[130:133], v[154:157], v[50:53]
	v_mfma_f32_16x16x32_bf16 v[38:41], v[162:165], v[150:153], v[38:41]
	v_mfma_f32_16x16x32_bf16 v[26:29], v[204:207], v[150:153], v[26:29]
	v_mfma_f32_16x16x32_bf16 v[22:25], v[126:129], v[150:153], v[22:25]
	v_mfma_f32_16x16x32_bf16 v[46:49], v[158:161], v[134:137], v[46:49]
	v_mfma_f32_16x16x32_bf16 v[42:45], v[166:169], v[134:137], v[42:45]
	v_mfma_f32_16x16x32_bf16 v[18:21], v[158:161], v[138:141], v[18:21]
	v_mfma_f32_16x16x32_bf16 v[14:17], v[166:169], v[138:141], v[14:17]
	s_waitcnt lgkmcnt(0)
	v_mfma_f32_16x16x32_bf16 v[2:5], v[158:161], v[142:145], v[2:5]
	v_mfma_f32_16x16x32_bf16 v[38:41], v[166:169], v[142:145], v[38:41]
	v_mfma_f32_16x16x32_bf16 v[34:37], v[208:211], v[134:137], v[34:37]
	v_mfma_f32_16x16x32_bf16 v[10:13], v[208:211], v[138:141], v[10:13]
	v_mfma_f32_16x16x32_bf16 v[26:29], v[208:211], v[142:145], v[26:29]
	v_mfma_f32_16x16x32_bf16 v[30:33], v[130:133], v[134:137], v[30:33]
	v_mfma_f32_16x16x32_bf16 v[6:9], v[130:133], v[138:141], v[6:9]
	v_mfma_f32_16x16x32_bf16 v[22:25], v[130:133], v[142:145], v[22:25]
	s_setprio 0
	s_add_u32 s6, s6, 0x80
	s_addc_u32 s7, s7, 0
	s_cmpk_eq_i32 s6, 0x780
	s_cbranch_scc0 .LBB0_792
	s_barrier
	s_waitcnt vmcnt(7)
	ds_write_b128 v106, v[66:69]
	s_waitcnt vmcnt(6)
	ds_write_b128 v106, v[70:73] offset:18432
	s_waitcnt vmcnt(5)
	ds_write_b128 v106, v[74:77] offset:4096
	s_waitcnt vmcnt(4)
	ds_write_b128 v106, v[78:81] offset:22528
	s_waitcnt vmcnt(3)
	ds_write_b128 v106, v[82:85] offset:8192
	s_waitcnt vmcnt(2)
	ds_write_b128 v106, v[86:89] offset:26624
	s_waitcnt vmcnt(1)
	ds_write_b128 v106, v[90:93] offset:12288
	s_waitcnt vmcnt(0)
	ds_write_b128 v106, v[94:97] offset:30720
	s_waitcnt lgkmcnt(0)
	s_barrier
	s_setprio 3
	ds_read_b128 v[66:69], v121 offset:18432
	ds_read_b128 v[70:73], v120
	ds_read_b128 v[74:77], v121 offset:20480
	ds_read_b128 v[78:81], v121 offset:22528
	s_waitcnt lgkmcnt(0)
	v_mfma_f32_16x16x32_bf16 v[82:85], v[78:81], v[70:73], v[54:57]
	s_nop 2
	ds_read_b128 v[54:57], v121 offset:24576
	ds_read_b128 v[90:93], v249 offset:20480
	s_cmp_lt_i32 s20, 2
	v_mfma_f32_16x16x32_bf16 v[62:65], v[66:69], v[70:73], v[62:65]
	ds_read_b128 v[94:97], v249 offset:22528
	s_mov_b64 s[10:11], -1
	v_mfma_f32_16x16x32_bf16 v[58:61], v[74:77], v[70:73], v[58:61]
	s_waitcnt lgkmcnt(2)
	v_mfma_f32_16x16x32_bf16 v[70:73], v[54:57], v[70:73], v[50:53]
	s_nop 2
	ds_read_b128 v[50:53], v120 offset:2048
	s_waitcnt lgkmcnt(0)
	v_mfma_f32_16x16x32_bf16 v[46:49], v[66:69], v[50:53], v[46:49]
	v_mfma_f32_16x16x32_bf16 v[42:45], v[74:77], v[50:53], v[42:45]
	v_mfma_f32_16x16x32_bf16 v[34:37], v[78:81], v[50:53], v[34:37]
	v_mfma_f32_16x16x32_bf16 v[30:33], v[54:57], v[50:53], v[30:33]
	ds_read_b128 v[50:53], v120 offset:4096
	s_waitcnt lgkmcnt(0)
	v_mfma_f32_16x16x32_bf16 v[18:21], v[66:69], v[50:53], v[18:21]
	v_mfma_f32_16x16x32_bf16 v[14:17], v[74:77], v[50:53], v[14:17]
	v_mfma_f32_16x16x32_bf16 v[10:13], v[78:81], v[50:53], v[10:13]
	v_mfma_f32_16x16x32_bf16 v[6:9], v[54:57], v[50:53], v[6:9]
	ds_read_b128 v[50:53], v120 offset:6144
	s_waitcnt lgkmcnt(0)
	v_mfma_f32_16x16x32_bf16 v[2:5], v[66:69], v[50:53], v[2:5]
	v_mfma_f32_16x16x32_bf16 v[66:69], v[74:77], v[50:53], v[38:41]
	v_mfma_f32_16x16x32_bf16 v[74:77], v[78:81], v[50:53], v[26:29]
	ds_read_b128 v[78:81], v249 offset:18432
	v_mfma_f32_16x16x32_bf16 v[86:89], v[54:57], v[50:53], v[22:25]
	s_nop 2
	ds_read_b128 v[22:25], v248
	s_waitcnt lgkmcnt(0)
	v_mfma_f32_16x16x32_bf16 v[54:57], v[90:93], v[22:25], v[58:61]
	v_mfma_f32_16x16x32_bf16 v[58:61], v[94:97], v[22:25], v[82:85]
	s_nop 2
	ds_read_b128 v[82:85], v249 offset:24576
	v_mfma_f32_16x16x32_bf16 v[50:53], v[78:81], v[22:25], v[62:65]
	s_waitcnt lgkmcnt(0)
	v_mfma_f32_16x16x32_bf16 v[62:65], v[82:85], v[22:25], v[70:73]
	ds_read_b128 v[22:25], v248 offset:2048
	s_nop 1
	ds_read_b128 v[70:73], v248 offset:4096
	s_waitcnt lgkmcnt(1)
	v_mfma_f32_16x16x32_bf16 v[46:49], v[78:81], v[22:25], v[46:49]
	v_mfma_f32_16x16x32_bf16 v[42:45], v[90:93], v[22:25], v[42:45]
	v_mfma_f32_16x16x32_bf16 v[38:41], v[94:97], v[22:25], v[34:37]
	v_mfma_f32_16x16x32_bf16 v[34:37], v[82:85], v[22:25], v[30:33]
	s_waitcnt lgkmcnt(0)
	v_mfma_f32_16x16x32_bf16 v[30:33], v[78:81], v[70:73], v[18:21]
	v_mfma_f32_16x16x32_bf16 v[26:29], v[90:93], v[70:73], v[14:17]
	v_mfma_f32_16x16x32_bf16 v[22:25], v[94:97], v[70:73], v[10:13]
	v_mfma_f32_16x16x32_bf16 v[18:21], v[82:85], v[70:73], v[6:9]
	ds_read_b128 v[70:73], v248 offset:6144
	s_waitcnt lgkmcnt(0)
	v_mfma_f32_16x16x32_bf16 v[14:17], v[78:81], v[70:73], v[2:5]
	v_mfma_f32_16x16x32_bf16 v[10:13], v[90:93], v[70:73], v[66:69]
	v_mfma_f32_16x16x32_bf16 v[6:9], v[94:97], v[70:73], v[74:77]
	s_nop 1
	v_or_b32_e32 v66, s9, v117
	v_mfma_f32_16x16x32_bf16 v[2:5], v[82:85], v[70:73], v[86:89]
	s_setprio 0
	s_cbranch_scc1 .LBB0_796
	s_mov_b64 s[10:11], 0
	s_cmp_eq_u32 s20, 2
	s_mov_b64 s[6:7], 0
	s_cbranch_scc0 .LBB0_796
	s_movk_i32 s6, 0x800
	v_cmp_gt_i32_e32 vcc, s6, v66
	s_and_b64 s[6:7], vcc, exec
